# pair GEMM loops: wave priority 3 while issuing LDS fragment reads + DMA, 1 during the MFMA block, 0 at the barrier (was 0 / 1 / 0)
# speedup vs baseline: 1.0150x; 1.0150x over previous
.Lfin3_loop:
	s_setprio 3
	v_add_u32_e32 v234, s22, v232
	v_add_u32_e32 v236, s28, v232
	v_add_u32_e32 v235, s22, v233
	v_add_u32_e32 v237, s28, v233
	ds_read_b128 v[136:139], v234
	ds_read_b128 v[140:143], v234 offset:2048
	ds_read_b128 v[144:147], v234 offset:4096
	ds_read_b128 v[148:151], v234 offset:6144
	ds_read_b128 v[188:191], v236
	ds_read_b128 v[196:199], v236 offset:2048
	ds_read_b128 v[200:203], v236 offset:4096
	ds_read_b128 v[204:207], v236 offset:6144
	ds_read_b128 v[172:175], v235
	ds_read_b128 v[176:179], v235 offset:2048
	ds_read_b128 v[180:183], v235 offset:4096
	ds_read_b128 v[184:187], v235 offset:6144
	ds_read_b128 v[212:215], v237
	ds_read_b128 v[216:219], v237 offset:2048
	ds_read_b128 v[220:223], v237 offset:4096
	ds_read_b128 v[224:227], v237 offset:6144
	s_add_i32 m0, s51, 0xc000
	s_nop 0
	global_load_lds_dwordx4 v228, s[44:45]
	s_add_i32 m0, s51, 0xc400
	s_nop 0
	global_load_lds_dwordx4 v230, s[44:45]
	s_add_i32 m0, s51, 0xe000
	s_nop 0
	global_load_lds_dwordx4 v229, s[44:45]
	s_add_i32 m0, s51, 0xe400
	s_nop 0
	global_load_lds_dwordx4 v231, s[44:45]
	s_add_i32 m0, s51, 0x10000
	s_nop 0
	global_load_lds_dwordx4 v228, s[46:47]
	s_add_i32 m0, s51, 0x10400
	s_nop 0
	global_load_lds_dwordx4 v230, s[46:47]
	s_waitcnt lgkmcnt(8)
	s_setprio 1
	v_mfma_f32_16x16x32_bf16 v[2:5], v[136:139], v[188:191], v[2:5]
	v_mfma_f32_16x16x32_bf16 v[6:9], v[136:139], v[196:199], v[6:9]
	v_mfma_f32_16x16x32_bf16 v[10:13], v[136:139], v[200:203], v[10:13]
	v_mfma_f32_16x16x32_bf16 v[14:17], v[136:139], v[204:207], v[14:17]
	v_mfma_f32_16x16x32_bf16 v[18:21], v[140:143], v[188:191], v[18:21]
	v_mfma_f32_16x16x32_bf16 v[22:25], v[140:143], v[196:199], v[22:25]
	v_mfma_f32_16x16x32_bf16 v[26:29], v[140:143], v[200:203], v[26:29]
	v_mfma_f32_16x16x32_bf16 v[30:33], v[140:143], v[204:207], v[30:33]
	v_mfma_f32_16x16x32_bf16 v[34:37], v[144:147], v[188:191], v[34:37]
	v_mfma_f32_16x16x32_bf16 v[38:41], v[144:147], v[196:199], v[38:41]
	v_mfma_f32_16x16x32_bf16 v[42:45], v[144:147], v[200:203], v[42:45]
	v_mfma_f32_16x16x32_bf16 v[46:49], v[144:147], v[204:207], v[46:49]
	v_mfma_f32_16x16x32_bf16 v[50:53], v[148:151], v[188:191], v[50:53]
	v_mfma_f32_16x16x32_bf16 v[54:57], v[148:151], v[196:199], v[54:57]
	v_mfma_f32_16x16x32_bf16 v[58:61], v[148:151], v[200:203], v[58:61]
	v_mfma_f32_16x16x32_bf16 v[62:65], v[148:151], v[204:207], v[62:65]
	s_waitcnt lgkmcnt(0)
	v_mfma_f32_16x16x32_bf16 v[2:5], v[172:175], v[212:215], v[2:5]
	v_mfma_f32_16x16x32_bf16 v[6:9], v[172:175], v[216:219], v[6:9]
	v_mfma_f32_16x16x32_bf16 v[10:13], v[172:175], v[220:223], v[10:13]
	v_mfma_f32_16x16x32_bf16 v[14:17], v[172:175], v[224:227], v[14:17]
	v_mfma_f32_16x16x32_bf16 v[18:21], v[176:179], v[212:215], v[18:21]
	v_mfma_f32_16x16x32_bf16 v[22:25], v[176:179], v[216:219], v[22:25]
	v_mfma_f32_16x16x32_bf16 v[26:29], v[176:179], v[220:223], v[26:29]
	v_mfma_f32_16x16x32_bf16 v[30:33], v[176:179], v[224:227], v[30:33]
	v_mfma_f32_16x16x32_bf16 v[34:37], v[180:183], v[212:215], v[34:37]
	v_mfma_f32_16x16x32_bf16 v[38:41], v[180:183], v[216:219], v[38:41]
	v_mfma_f32_16x16x32_bf16 v[42:45], v[180:183], v[220:223], v[42:45]
	v_mfma_f32_16x16x32_bf16 v[46:49], v[180:183], v[224:227], v[46:49]
	v_mfma_f32_16x16x32_bf16 v[50:53], v[184:187], v[212:215], v[50:53]
	v_mfma_f32_16x16x32_bf16 v[54:57], v[184:187], v[216:219], v[54:57]
	v_mfma_f32_16x16x32_bf16 v[58:61], v[184:187], v[220:223], v[58:61]
	v_mfma_f32_16x16x32_bf16 v[62:65], v[184:187], v[224:227], v[62:65]
	s_setprio 0
	s_waitcnt vmcnt(6)
	s_barrier
	s_setprio 3
	v_add_u32_e32 v236, s40, v232
	v_add_u32_e32 v237, s40, v233
	ds_read_b128 v[188:191], v236
	ds_read_b128 v[196:199], v236 offset:2048
	ds_read_b128 v[200:203], v236 offset:4096
	ds_read_b128 v[204:207], v236 offset:6144
	ds_read_b128 v[212:215], v237
	ds_read_b128 v[216:219], v237 offset:2048
	ds_read_b128 v[220:223], v237 offset:4096
	ds_read_b128 v[224:227], v237 offset:6144
	s_mov_b32 m0, s51
	s_nop 0
	global_load_lds_dwordx4 v229, s[46:47]
	s_add_i32 m0, s51, 0x400
	s_nop 0
	global_load_lds_dwordx4 v231, s[46:47]
	s_add_i32 m0, s51, 0x2000
	s_nop 0
	global_load_lds_dwordx4 v228, s[48:49]
	s_add_i32 m0, s51, 0x2400
	s_nop 0
	global_load_lds_dwordx4 v230, s[48:49]
	s_add_i32 m0, s51, 0x4000
	s_nop 0
	global_load_lds_dwordx4 v229, s[48:49]
	s_add_i32 m0, s51, 0x4400
	s_nop 0
	global_load_lds_dwordx4 v231, s[48:49]
	s_waitcnt lgkmcnt(4)
	s_setprio 1
	v_mfma_f32_16x16x32_bf16 v[66:69], v[136:139], v[188:191], v[66:69]
	v_mfma_f32_16x16x32_bf16 v[70:73], v[136:139], v[196:199], v[70:73]
	v_mfma_f32_16x16x32_bf16 v[74:77], v[136:139], v[200:203], v[74:77]
	v_mfma_f32_16x16x32_bf16 v[78:81], v[136:139], v[204:207], v[78:81]
	v_mfma_f32_16x16x32_bf16 v[82:85], v[140:143], v[188:191], v[82:85]
	v_mfma_f32_16x16x32_bf16 v[86:89], v[140:143], v[196:199], v[86:89]
	v_mfma_f32_16x16x32_bf16 v[90:93], v[140:143], v[200:203], v[90:93]
	v_mfma_f32_16x16x32_bf16 v[94:97], v[140:143], v[204:207], v[94:97]
	v_mfma_f32_16x16x32_bf16 v[98:101], v[144:147], v[188:191], v[98:101]
	v_mfma_f32_16x16x32_bf16 v[102:105], v[144:147], v[196:199], v[102:105]
	v_mfma_f32_16x16x32_bf16 v[106:109], v[144:147], v[200:203], v[106:109]
	v_mfma_f32_16x16x32_bf16 v[110:113], v[144:147], v[204:207], v[110:113]
	v_mfma_f32_16x16x32_bf16 v[114:117], v[148:151], v[188:191], v[114:117]
	v_mfma_f32_16x16x32_bf16 v[118:121], v[148:151], v[196:199], v[118:121]
	v_mfma_f32_16x16x32_bf16 v[122:125], v[148:151], v[200:203], v[122:125]
	v_mfma_f32_16x16x32_bf16 v[126:129], v[148:151], v[204:207], v[126:129]
	s_waitcnt lgkmcnt(0)
	v_mfma_f32_16x16x32_bf16 v[66:69], v[172:175], v[212:215], v[66:69]
	v_mfma_f32_16x16x32_bf16 v[70:73], v[172:175], v[216:219], v[70:73]
	v_mfma_f32_16x16x32_bf16 v[74:77], v[172:175], v[220:223], v[74:77]
	v_mfma_f32_16x16x32_bf16 v[78:81], v[172:175], v[224:227], v[78:81]
	v_mfma_f32_16x16x32_bf16 v[82:85], v[176:179], v[212:215], v[82:85]
	v_mfma_f32_16x16x32_bf16 v[86:89], v[176:179], v[216:219], v[86:89]
	v_mfma_f32_16x16x32_bf16 v[90:93], v[176:179], v[220:223], v[90:93]
	v_mfma_f32_16x16x32_bf16 v[94:97], v[176:179], v[224:227], v[94:97]
	v_mfma_f32_16x16x32_bf16 v[98:101], v[180:183], v[212:215], v[98:101]
	v_mfma_f32_16x16x32_bf16 v[102:105], v[180:183], v[216:219], v[102:105]
	v_mfma_f32_16x16x32_bf16 v[106:109], v[180:183], v[220:223], v[106:109]
	v_mfma_f32_16x16x32_bf16 v[110:113], v[180:183], v[224:227], v[110:113]
	v_mfma_f32_16x16x32_bf16 v[114:117], v[184:187], v[212:215], v[114:117]
	v_mfma_f32_16x16x32_bf16 v[118:121], v[184:187], v[216:219], v[118:121]
	v_mfma_f32_16x16x32_bf16 v[122:125], v[184:187], v[220:223], v[122:125]
	v_mfma_f32_16x16x32_bf16 v[126:129], v[184:187], v[224:227], v[126:129]
	s_setprio 0
	v_add_u32_e32 v228, 0x80, v228
	v_add_u32_e32 v229, 0x80, v229
	v_add_u32_e32 v230, 0x80, v230
	v_add_u32_e32 v231, 0x80, v231
	s_waitcnt vmcnt(4)
	s_barrier
	s_setprio 3
	v_add_u32_e32 v234, s23, v232
	v_add_u32_e32 v236, s29, v232
	v_add_u32_e32 v235, s23, v233
	v_add_u32_e32 v237, s29, v233
	ds_read_b128 v[136:139], v234
	ds_read_b128 v[140:143], v234 offset:2048
	ds_read_b128 v[144:147], v234 offset:4096
	ds_read_b128 v[148:151], v234 offset:6144
	ds_read_b128 v[188:191], v236
	ds_read_b128 v[196:199], v236 offset:2048
	ds_read_b128 v[200:203], v236 offset:4096
	ds_read_b128 v[204:207], v236 offset:6144
	ds_read_b128 v[172:175], v235
	ds_read_b128 v[176:179], v235 offset:2048
	ds_read_b128 v[180:183], v235 offset:4096
	ds_read_b128 v[184:187], v235 offset:6144
	ds_read_b128 v[212:215], v237
	ds_read_b128 v[216:219], v237 offset:2048
	ds_read_b128 v[220:223], v237 offset:4096
	ds_read_b128 v[224:227], v237 offset:6144
	s_add_i32 m0, s51, 0x6000
	s_nop 0
	global_load_lds_dwordx4 v228, s[44:45]
	s_add_i32 m0, s51, 0x6400
	s_nop 0
	global_load_lds_dwordx4 v230, s[44:45]
	s_add_i32 m0, s51, 0x8000
	s_nop 0
	global_load_lds_dwordx4 v229, s[44:45]
	s_add_i32 m0, s51, 0x8400
	s_nop 0
	global_load_lds_dwordx4 v231, s[44:45]
	s_add_i32 m0, s51, 0xa000
	s_nop 0
	global_load_lds_dwordx4 v228, s[46:47]
	s_add_i32 m0, s51, 0xa400
	s_nop 0
	global_load_lds_dwordx4 v230, s[46:47]
	s_waitcnt lgkmcnt(8)
	s_setprio 1
	v_mfma_f32_16x16x32_bf16 v[2:5], v[136:139], v[188:191], v[2:5]
	v_mfma_f32_16x16x32_bf16 v[6:9], v[136:139], v[196:199], v[6:9]
	v_mfma_f32_16x16x32_bf16 v[10:13], v[136:139], v[200:203], v[10:13]
	v_mfma_f32_16x16x32_bf16 v[14:17], v[136:139], v[204:207], v[14:17]
	v_mfma_f32_16x16x32_bf16 v[18:21], v[140:143], v[188:191], v[18:21]
	v_mfma_f32_16x16x32_bf16 v[22:25], v[140:143], v[196:199], v[22:25]
	v_mfma_f32_16x16x32_bf16 v[26:29], v[140:143], v[200:203], v[26:29]
	v_mfma_f32_16x16x32_bf16 v[30:33], v[140:143], v[204:207], v[30:33]
	v_mfma_f32_16x16x32_bf16 v[34:37], v[144:147], v[188:191], v[34:37]
	v_mfma_f32_16x16x32_bf16 v[38:41], v[144:147], v[196:199], v[38:41]
	v_mfma_f32_16x16x32_bf16 v[42:45], v[144:147], v[200:203], v[42:45]
	v_mfma_f32_16x16x32_bf16 v[46:49], v[144:147], v[204:207], v[46:49]
	v_mfma_f32_16x16x32_bf16 v[50:53], v[148:151], v[188:191], v[50:53]
	v_mfma_f32_16x16x32_bf16 v[54:57], v[148:151], v[196:199], v[54:57]
	v_mfma_f32_16x16x32_bf16 v[58:61], v[148:151], v[200:203], v[58:61]
	v_mfma_f32_16x16x32_bf16 v[62:65], v[148:151], v[204:207], v[62:65]
	s_waitcnt lgkmcnt(0)
	v_mfma_f32_16x16x32_bf16 v[2:5], v[172:175], v[212:215], v[2:5]
	v_mfma_f32_16x16x32_bf16 v[6:9], v[172:175], v[216:219], v[6:9]
	v_mfma_f32_16x16x32_bf16 v[10:13], v[172:175], v[220:223], v[10:13]
	v_mfma_f32_16x16x32_bf16 v[14:17], v[172:175], v[224:227], v[14:17]
	v_mfma_f32_16x16x32_bf16 v[18:21], v[176:179], v[212:215], v[18:21]
	v_mfma_f32_16x16x32_bf16 v[22:25], v[176:179], v[216:219], v[22:25]
	v_mfma_f32_16x16x32_bf16 v[26:29], v[176:179], v[220:223], v[26:29]
	v_mfma_f32_16x16x32_bf16 v[30:33], v[176:179], v[224:227], v[30:33]
	v_mfma_f32_16x16x32_bf16 v[34:37], v[180:183], v[212:215], v[34:37]
	v_mfma_f32_16x16x32_bf16 v[38:41], v[180:183], v[216:219], v[38:41]
	v_mfma_f32_16x16x32_bf16 v[42:45], v[180:183], v[220:223], v[42:45]
	v_mfma_f32_16x16x32_bf16 v[46:49], v[180:183], v[224:227], v[46:49]
	v_mfma_f32_16x16x32_bf16 v[50:53], v[184:187], v[212:215], v[50:53]
	v_mfma_f32_16x16x32_bf16 v[54:57], v[184:187], v[216:219], v[54:57]
	v_mfma_f32_16x16x32_bf16 v[58:61], v[184:187], v[220:223], v[58:61]
	v_mfma_f32_16x16x32_bf16 v[62:65], v[184:187], v[224:227], v[62:65]
	s_setprio 0
	s_waitcnt vmcnt(6)
	s_barrier
	s_setprio 3
	v_add_u32_e32 v236, s41, v232
	v_add_u32_e32 v237, s41, v233
	ds_read_b128 v[188:191], v236
	ds_read_b128 v[196:199], v236 offset:2048
	ds_read_b128 v[200:203], v236 offset:4096
	ds_read_b128 v[204:207], v236 offset:6144
	ds_read_b128 v[212:215], v237
	ds_read_b128 v[216:219], v237 offset:2048
	ds_read_b128 v[220:223], v237 offset:4096
	ds_read_b128 v[224:227], v237 offset:6144
	s_add_i32 m0, s51, 0xc000
	s_nop 0
	global_load_lds_dwordx4 v229, s[46:47]
	s_add_i32 m0, s51, 0xc400
	s_nop 0
	global_load_lds_dwordx4 v231, s[46:47]
	s_add_i32 m0, s51, 0xe000
	s_nop 0
	global_load_lds_dwordx4 v228, s[48:49]
	s_add_i32 m0, s51, 0xe400
	s_nop 0
	global_load_lds_dwordx4 v230, s[48:49]
	s_add_i32 m0, s51, 0x10000
	s_nop 0
	global_load_lds_dwordx4 v229, s[48:49]
	s_add_i32 m0, s51, 0x10400
	s_nop 0
	global_load_lds_dwordx4 v231, s[48:49]
	s_waitcnt lgkmcnt(4)
	s_setprio 1
	v_mfma_f32_16x16x32_bf16 v[66:69], v[136:139], v[188:191], v[66:69]
	v_mfma_f32_16x16x32_bf16 v[70:73], v[136:139], v[196:199], v[70:73]
	v_mfma_f32_16x16x32_bf16 v[74:77], v[136:139], v[200:203], v[74:77]
	v_mfma_f32_16x16x32_bf16 v[78:81], v[136:139], v[204:207], v[78:81]
	v_mfma_f32_16x16x32_bf16 v[82:85], v[140:143], v[188:191], v[82:85]
	v_mfma_f32_16x16x32_bf16 v[86:89], v[140:143], v[196:199], v[86:89]
	v_mfma_f32_16x16x32_bf16 v[90:93], v[140:143], v[200:203], v[90:93]
	v_mfma_f32_16x16x32_bf16 v[94:97], v[140:143], v[204:207], v[94:97]
	v_mfma_f32_16x16x32_bf16 v[98:101], v[144:147], v[188:191], v[98:101]
	v_mfma_f32_16x16x32_bf16 v[102:105], v[144:147], v[196:199], v[102:105]
	v_mfma_f32_16x16x32_bf16 v[106:109], v[144:147], v[200:203], v[106:109]
	v_mfma_f32_16x16x32_bf16 v[110:113], v[144:147], v[204:207], v[110:113]
	v_mfma_f32_16x16x32_bf16 v[114:117], v[148:151], v[188:191], v[114:117]
	v_mfma_f32_16x16x32_bf16 v[118:121], v[148:151], v[196:199], v[118:121]
	v_mfma_f32_16x16x32_bf16 v[122:125], v[148:151], v[200:203], v[122:125]
	v_mfma_f32_16x16x32_bf16 v[126:129], v[148:151], v[204:207], v[126:129]
	s_waitcnt lgkmcnt(0)
	v_mfma_f32_16x16x32_bf16 v[66:69], v[172:175], v[212:215], v[66:69]
	v_mfma_f32_16x16x32_bf16 v[70:73], v[172:175], v[216:219], v[70:73]
	v_mfma_f32_16x16x32_bf16 v[74:77], v[172:175], v[220:223], v[74:77]
	v_mfma_f32_16x16x32_bf16 v[78:81], v[172:175], v[224:227], v[78:81]
	v_mfma_f32_16x16x32_bf16 v[82:85], v[176:179], v[212:215], v[82:85]
	v_mfma_f32_16x16x32_bf16 v[86:89], v[176:179], v[216:219], v[86:89]
	v_mfma_f32_16x16x32_bf16 v[90:93], v[176:179], v[220:223], v[90:93]
	v_mfma_f32_16x16x32_bf16 v[94:97], v[176:179], v[224:227], v[94:97]
	v_mfma_f32_16x16x32_bf16 v[98:101], v[180:183], v[212:215], v[98:101]
	v_mfma_f32_16x16x32_bf16 v[102:105], v[180:183], v[216:219], v[102:105]
	v_mfma_f32_16x16x32_bf16 v[106:109], v[180:183], v[220:223], v[106:109]
	v_mfma_f32_16x16x32_bf16 v[110:113], v[180:183], v[224:227], v[110:113]
	v_mfma_f32_16x16x32_bf16 v[114:117], v[184:187], v[212:215], v[114:117]
	v_mfma_f32_16x16x32_bf16 v[118:121], v[184:187], v[216:219], v[118:121]
	v_mfma_f32_16x16x32_bf16 v[122:125], v[184:187], v[220:223], v[122:125]
	v_mfma_f32_16x16x32_bf16 v[126:129], v[184:187], v[224:227], v[126:129]
	s_setprio 0
	v_add_u32_e32 v228, 0x80, v228
	v_add_u32_e32 v229, 0x80, v229
	v_add_u32_e32 v230, 0x80, v230
	v_add_u32_e32 v231, 0x80, v231
	s_waitcnt vmcnt(4)
	s_barrier
	s_setprio 3
	v_add_u32_e32 v234, s24, v232
	v_add_u32_e32 v236, s30, v232
	v_add_u32_e32 v235, s24, v233
	v_add_u32_e32 v237, s30, v233
	ds_read_b128 v[136:139], v234
	ds_read_b128 v[140:143], v234 offset:2048
	ds_read_b128 v[144:147], v234 offset:4096
	ds_read_b128 v[148:151], v234 offset:6144
	ds_read_b128 v[188:191], v236
	ds_read_b128 v[196:199], v236 offset:2048
	ds_read_b128 v[200:203], v236 offset:4096
	ds_read_b128 v[204:207], v236 offset:6144
	ds_read_b128 v[172:175], v235
	ds_read_b128 v[176:179], v235 offset:2048
	ds_read_b128 v[180:183], v235 offset:4096
	ds_read_b128 v[184:187], v235 offset:6144
	ds_read_b128 v[212:215], v237
	ds_read_b128 v[216:219], v237 offset:2048
	ds_read_b128 v[220:223], v237 offset:4096
	ds_read_b128 v[224:227], v237 offset:6144
	s_mov_b32 m0, s51
	s_nop 0
	global_load_lds_dwordx4 v228, s[44:45]
	s_add_i32 m0, s51, 0x400
	s_nop 0
	global_load_lds_dwordx4 v230, s[44:45]
	s_add_i32 m0, s51, 0x2000
	s_nop 0
	global_load_lds_dwordx4 v229, s[44:45]
	s_add_i32 m0, s51, 0x2400
	s_nop 0
	global_load_lds_dwordx4 v231, s[44:45]
	s_add_i32 m0, s51, 0x4000
	s_nop 0
	global_load_lds_dwordx4 v228, s[46:47]
	s_add_i32 m0, s51, 0x4400
	s_nop 0
	global_load_lds_dwordx4 v230, s[46:47]
	s_waitcnt lgkmcnt(8)
	s_setprio 1
	v_mfma_f32_16x16x32_bf16 v[2:5], v[136:139], v[188:191], v[2:5]
	v_mfma_f32_16x16x32_bf16 v[6:9], v[136:139], v[196:199], v[6:9]
	v_mfma_f32_16x16x32_bf16 v[10:13], v[136:139], v[200:203], v[10:13]
	v_mfma_f32_16x16x32_bf16 v[14:17], v[136:139], v[204:207], v[14:17]
	v_mfma_f32_16x16x32_bf16 v[18:21], v[140:143], v[188:191], v[18:21]
	v_mfma_f32_16x16x32_bf16 v[22:25], v[140:143], v[196:199], v[22:25]
	v_mfma_f32_16x16x32_bf16 v[26:29], v[140:143], v[200:203], v[26:29]
	v_mfma_f32_16x16x32_bf16 v[30:33], v[140:143], v[204:207], v[30:33]
	v_mfma_f32_16x16x32_bf16 v[34:37], v[144:147], v[188:191], v[34:37]
	v_mfma_f32_16x16x32_bf16 v[38:41], v[144:147], v[196:199], v[38:41]
	v_mfma_f32_16x16x32_bf16 v[42:45], v[144:147], v[200:203], v[42:45]
	v_mfma_f32_16x16x32_bf16 v[46:49], v[144:147], v[204:207], v[46:49]
	v_mfma_f32_16x16x32_bf16 v[50:53], v[148:151], v[188:191], v[50:53]
	v_mfma_f32_16x16x32_bf16 v[54:57], v[148:151], v[196:199], v[54:57]
	v_mfma_f32_16x16x32_bf16 v[58:61], v[148:151], v[200:203], v[58:61]
	v_mfma_f32_16x16x32_bf16 v[62:65], v[148:151], v[204:207], v[62:65]
	s_waitcnt lgkmcnt(0)
	v_mfma_f32_16x16x32_bf16 v[2:5], v[172:175], v[212:215], v[2:5]
	v_mfma_f32_16x16x32_bf16 v[6:9], v[172:175], v[216:219], v[6:9]
	v_mfma_f32_16x16x32_bf16 v[10:13], v[172:175], v[220:223], v[10:13]
	v_mfma_f32_16x16x32_bf16 v[14:17], v[172:175], v[224:227], v[14:17]
	v_mfma_f32_16x16x32_bf16 v[18:21], v[176:179], v[212:215], v[18:21]
	v_mfma_f32_16x16x32_bf16 v[22:25], v[176:179], v[216:219], v[22:25]
	v_mfma_f32_16x16x32_bf16 v[26:29], v[176:179], v[220:223], v[26:29]
	v_mfma_f32_16x16x32_bf16 v[30:33], v[176:179], v[224:227], v[30:33]
	v_mfma_f32_16x16x32_bf16 v[34:37], v[180:183], v[212:215], v[34:37]
	v_mfma_f32_16x16x32_bf16 v[38:41], v[180:183], v[216:219], v[38:41]
	v_mfma_f32_16x16x32_bf16 v[42:45], v[180:183], v[220:223], v[42:45]
	v_mfma_f32_16x16x32_bf16 v[46:49], v[180:183], v[224:227], v[46:49]
	v_mfma_f32_16x16x32_bf16 v[50:53], v[184:187], v[212:215], v[50:53]
	v_mfma_f32_16x16x32_bf16 v[54:57], v[184:187], v[216:219], v[54:57]
	v_mfma_f32_16x16x32_bf16 v[58:61], v[184:187], v[220:223], v[58:61]
	v_mfma_f32_16x16x32_bf16 v[62:65], v[184:187], v[224:227], v[62:65]
	s_setprio 0
	s_waitcnt vmcnt(6)
	s_barrier
	s_setprio 3
	v_add_u32_e32 v236, s42, v232
	v_add_u32_e32 v237, s42, v233
	ds_read_b128 v[188:191], v236
	ds_read_b128 v[196:199], v236 offset:2048
	ds_read_b128 v[200:203], v236 offset:4096
	ds_read_b128 v[204:207], v236 offset:6144
	ds_read_b128 v[212:215], v237
	ds_read_b128 v[216:219], v237 offset:2048
	ds_read_b128 v[220:223], v237 offset:4096
	ds_read_b128 v[224:227], v237 offset:6144
	s_add_i32 m0, s51, 0x6000
	s_nop 0
	global_load_lds_dwordx4 v229, s[46:47]
	s_add_i32 m0, s51, 0x6400
	s_nop 0
	global_load_lds_dwordx4 v231, s[46:47]
	s_add_i32 m0, s51, 0x8000
	s_nop 0
	global_load_lds_dwordx4 v228, s[48:49]
	s_add_i32 m0, s51, 0x8400
	s_nop 0
	global_load_lds_dwordx4 v230, s[48:49]
	s_add_i32 m0, s51, 0xa000
	s_nop 0
	global_load_lds_dwordx4 v229, s[48:49]
	s_add_i32 m0, s51, 0xa400
	s_nop 0
	global_load_lds_dwordx4 v231, s[48:49]
	s_waitcnt lgkmcnt(4)
	s_setprio 1
	v_mfma_f32_16x16x32_bf16 v[66:69], v[136:139], v[188:191], v[66:69]
	v_mfma_f32_16x16x32_bf16 v[70:73], v[136:139], v[196:199], v[70:73]
	v_mfma_f32_16x16x32_bf16 v[74:77], v[136:139], v[200:203], v[74:77]
	v_mfma_f32_16x16x32_bf16 v[78:81], v[136:139], v[204:207], v[78:81]
	v_mfma_f32_16x16x32_bf16 v[82:85], v[140:143], v[188:191], v[82:85]
	v_mfma_f32_16x16x32_bf16 v[86:89], v[140:143], v[196:199], v[86:89]
	v_mfma_f32_16x16x32_bf16 v[90:93], v[140:143], v[200:203], v[90:93]
	v_mfma_f32_16x16x32_bf16 v[94:97], v[140:143], v[204:207], v[94:97]
	v_mfma_f32_16x16x32_bf16 v[98:101], v[144:147], v[188:191], v[98:101]
	v_mfma_f32_16x16x32_bf16 v[102:105], v[144:147], v[196:199], v[102:105]
	v_mfma_f32_16x16x32_bf16 v[106:109], v[144:147], v[200:203], v[106:109]
	v_mfma_f32_16x16x32_bf16 v[110:113], v[144:147], v[204:207], v[110:113]
	v_mfma_f32_16x16x32_bf16 v[114:117], v[148:151], v[188:191], v[114:117]
	v_mfma_f32_16x16x32_bf16 v[118:121], v[148:151], v[196:199], v[118:121]
	v_mfma_f32_16x16x32_bf16 v[122:125], v[148:151], v[200:203], v[122:125]
	v_mfma_f32_16x16x32_bf16 v[126:129], v[148:151], v[204:207], v[126:129]
	s_waitcnt lgkmcnt(0)
	v_mfma_f32_16x16x32_bf16 v[66:69], v[172:175], v[212:215], v[66:69]
	v_mfma_f32_16x16x32_bf16 v[70:73], v[172:175], v[216:219], v[70:73]
	v_mfma_f32_16x16x32_bf16 v[74:77], v[172:175], v[220:223], v[74:77]
	v_mfma_f32_16x16x32_bf16 v[78:81], v[172:175], v[224:227], v[78:81]
	v_mfma_f32_16x16x32_bf16 v[82:85], v[176:179], v[212:215], v[82:85]
	v_mfma_f32_16x16x32_bf16 v[86:89], v[176:179], v[216:219], v[86:89]
	v_mfma_f32_16x16x32_bf16 v[90:93], v[176:179], v[220:223], v[90:93]
	v_mfma_f32_16x16x32_bf16 v[94:97], v[176:179], v[224:227], v[94:97]
	v_mfma_f32_16x16x32_bf16 v[98:101], v[180:183], v[212:215], v[98:101]
	v_mfma_f32_16x16x32_bf16 v[102:105], v[180:183], v[216:219], v[102:105]
	v_mfma_f32_16x16x32_bf16 v[106:109], v[180:183], v[220:223], v[106:109]
	v_mfma_f32_16x16x32_bf16 v[110:113], v[180:183], v[224:227], v[110:113]
	v_mfma_f32_16x16x32_bf16 v[114:117], v[184:187], v[212:215], v[114:117]
	v_mfma_f32_16x16x32_bf16 v[118:121], v[184:187], v[216:219], v[118:121]
	v_mfma_f32_16x16x32_bf16 v[122:125], v[184:187], v[220:223], v[122:125]
	v_mfma_f32_16x16x32_bf16 v[126:129], v[184:187], v[224:227], v[126:129]
	s_setprio 0
	v_add_u32_e32 v228, 0x80, v228
	v_add_u32_e32 v229, 0x80, v229
	v_add_u32_e32 v230, 0x80, v230
	v_add_u32_e32 v231, 0x80, v231
	s_waitcnt vmcnt(4)
	s_barrier
	s_add_i32 s52, s52, 1
	s_cmp_lt_u32 s52, 29
	s_cbranch_scc1 .Lfin3_loop
	s_setprio 3
	v_add_u32_e32 v234, s22, v232
	v_add_u32_e32 v236, s28, v232
	v_add_u32_e32 v235, s22, v233
	v_add_u32_e32 v237, s28, v233
	ds_read_b128 v[136:139], v234
	ds_read_b128 v[140:143], v234 offset:2048
	ds_read_b128 v[144:147], v234 offset:4096
	ds_read_b128 v[148:151], v234 offset:6144
	ds_read_b128 v[188:191], v236
	ds_read_b128 v[196:199], v236 offset:2048
	ds_read_b128 v[200:203], v236 offset:4096
	ds_read_b128 v[204:207], v236 offset:6144
	ds_read_b128 v[172:175], v235
	ds_read_b128 v[176:179], v235 offset:2048
	ds_read_b128 v[180:183], v235 offset:4096
	ds_read_b128 v[184:187], v235 offset:6144
	ds_read_b128 v[212:215], v237
	ds_read_b128 v[216:219], v237 offset:2048
	ds_read_b128 v[220:223], v237 offset:4096
	ds_read_b128 v[224:227], v237 offset:6144
	s_waitcnt lgkmcnt(8)
	s_setprio 1
	v_mfma_f32_16x16x32_bf16 v[2:5], v[136:139], v[188:191], v[2:5]
	v_mfma_f32_16x16x32_bf16 v[6:9], v[136:139], v[196:199], v[6:9]
	v_mfma_f32_16x16x32_bf16 v[10:13], v[136:139], v[200:203], v[10:13]
	v_mfma_f32_16x16x32_bf16 v[14:17], v[136:139], v[204:207], v[14:17]
	v_mfma_f32_16x16x32_bf16 v[18:21], v[140:143], v[188:191], v[18:21]
	v_mfma_f32_16x16x32_bf16 v[22:25], v[140:143], v[196:199], v[22:25]
	v_mfma_f32_16x16x32_bf16 v[26:29], v[140:143], v[200:203], v[26:29]
	v_mfma_f32_16x16x32_bf16 v[30:33], v[140:143], v[204:207], v[30:33]
	v_mfma_f32_16x16x32_bf16 v[34:37], v[144:147], v[188:191], v[34:37]
	v_mfma_f32_16x16x32_bf16 v[38:41], v[144:147], v[196:199], v[38:41]
	v_mfma_f32_16x16x32_bf16 v[42:45], v[144:147], v[200:203], v[42:45]
	v_mfma_f32_16x16x32_bf16 v[46:49], v[144:147], v[204:207], v[46:49]
	v_mfma_f32_16x16x32_bf16 v[50:53], v[148:151], v[188:191], v[50:53]
	v_mfma_f32_16x16x32_bf16 v[54:57], v[148:151], v[196:199], v[54:57]
	v_mfma_f32_16x16x32_bf16 v[58:61], v[148:151], v[200:203], v[58:61]
	v_mfma_f32_16x16x32_bf16 v[62:65], v[148:151], v[204:207], v[62:65]
	s_waitcnt lgkmcnt(0)
	v_mfma_f32_16x16x32_bf16 v[2:5], v[172:175], v[212:215], v[2:5]
	v_mfma_f32_16x16x32_bf16 v[6:9], v[172:175], v[216:219], v[6:9]
	v_mfma_f32_16x16x32_bf16 v[10:13], v[172:175], v[220:223], v[10:13]
	v_mfma_f32_16x16x32_bf16 v[14:17], v[172:175], v[224:227], v[14:17]
	v_mfma_f32_16x16x32_bf16 v[18:21], v[176:179], v[212:215], v[18:21]
	v_mfma_f32_16x16x32_bf16 v[22:25], v[176:179], v[216:219], v[22:25]
	v_mfma_f32_16x16x32_bf16 v[26:29], v[176:179], v[220:223], v[26:29]
	v_mfma_f32_16x16x32_bf16 v[30:33], v[176:179], v[224:227], v[30:33]
	v_mfma_f32_16x16x32_bf16 v[34:37], v[180:183], v[212:215], v[34:37]
	v_mfma_f32_16x16x32_bf16 v[38:41], v[180:183], v[216:219], v[38:41]
	v_mfma_f32_16x16x32_bf16 v[42:45], v[180:183], v[220:223], v[42:45]
	v_mfma_f32_16x16x32_bf16 v[46:49], v[180:183], v[224:227], v[46:49]
	v_mfma_f32_16x16x32_bf16 v[50:53], v[184:187], v[212:215], v[50:53]
	v_mfma_f32_16x16x32_bf16 v[54:57], v[184:187], v[216:219], v[54:57]
	v_mfma_f32_16x16x32_bf16 v[58:61], v[184:187], v[220:223], v[58:61]
	v_mfma_f32_16x16x32_bf16 v[62:65], v[184:187], v[224:227], v[62:65]
	s_setprio 0
	s_waitcnt vmcnt(0)
	s_barrier
	s_setprio 3
	v_add_u32_e32 v236, s40, v232
	v_add_u32_e32 v237, s40, v233
	ds_read_b128 v[188:191], v236
	ds_read_b128 v[196:199], v236 offset:2048
	ds_read_b128 v[200:203], v236 offset:4096
	ds_read_b128 v[204:207], v236 offset:6144
	ds_read_b128 v[212:215], v237
	ds_read_b128 v[216:219], v237 offset:2048
	ds_read_b128 v[220:223], v237 offset:4096
	ds_read_b128 v[224:227], v237 offset:6144
	s_waitcnt lgkmcnt(4)
	s_setprio 1
	v_mfma_f32_16x16x32_bf16 v[66:69], v[136:139], v[188:191], v[66:69]
	v_mfma_f32_16x16x32_bf16 v[70:73], v[136:139], v[196:199], v[70:73]
	v_mfma_f32_16x16x32_bf16 v[74:77], v[136:139], v[200:203], v[74:77]
	v_mfma_f32_16x16x32_bf16 v[78:81], v[136:139], v[204:207], v[78:81]
	v_mfma_f32_16x16x32_bf16 v[82:85], v[140:143], v[188:191], v[82:85]
	v_mfma_f32_16x16x32_bf16 v[86:89], v[140:143], v[196:199], v[86:89]
	v_mfma_f32_16x16x32_bf16 v[90:93], v[140:143], v[200:203], v[90:93]
	v_mfma_f32_16x16x32_bf16 v[94:97], v[140:143], v[204:207], v[94:97]
	v_mfma_f32_16x16x32_bf16 v[98:101], v[144:147], v[188:191], v[98:101]
	v_mfma_f32_16x16x32_bf16 v[102:105], v[144:147], v[196:199], v[102:105]
	v_mfma_f32_16x16x32_bf16 v[106:109], v[144:147], v[200:203], v[106:109]
	v_mfma_f32_16x16x32_bf16 v[110:113], v[144:147], v[204:207], v[110:113]
	v_mfma_f32_16x16x32_bf16 v[114:117], v[148:151], v[188:191], v[114:117]
	v_mfma_f32_16x16x32_bf16 v[118:121], v[148:151], v[196:199], v[118:121]
	v_mfma_f32_16x16x32_bf16 v[122:125], v[148:151], v[200:203], v[122:125]
	v_mfma_f32_16x16x32_bf16 v[126:129], v[148:151], v[204:207], v[126:129]
	s_waitcnt lgkmcnt(0)
	v_mfma_f32_16x16x32_bf16 v[66:69], v[172:175], v[212:215], v[66:69]
	v_mfma_f32_16x16x32_bf16 v[70:73], v[172:175], v[216:219], v[70:73]
	v_mfma_f32_16x16x32_bf16 v[74:77], v[172:175], v[220:223], v[74:77]
	v_mfma_f32_16x16x32_bf16 v[78:81], v[172:175], v[224:227], v[78:81]
	v_mfma_f32_16x16x32_bf16 v[82:85], v[176:179], v[212:215], v[82:85]
	v_mfma_f32_16x16x32_bf16 v[86:89], v[176:179], v[216:219], v[86:89]
	v_mfma_f32_16x16x32_bf16 v[90:93], v[176:179], v[220:223], v[90:93]
	v_mfma_f32_16x16x32_bf16 v[94:97], v[176:179], v[224:227], v[94:97]
	v_mfma_f32_16x16x32_bf16 v[98:101], v[180:183], v[212:215], v[98:101]
	v_mfma_f32_16x16x32_bf16 v[102:105], v[180:183], v[216:219], v[102:105]
	v_mfma_f32_16x16x32_bf16 v[106:109], v[180:183], v[220:223], v[106:109]
	v_mfma_f32_16x16x32_bf16 v[110:113], v[180:183], v[224:227], v[110:113]
	v_mfma_f32_16x16x32_bf16 v[114:117], v[184:187], v[212:215], v[114:117]
	v_mfma_f32_16x16x32_bf16 v[118:121], v[184:187], v[216:219], v[118:121]
	v_mfma_f32_16x16x32_bf16 v[122:125], v[184:187], v[220:223], v[122:125]
	v_mfma_f32_16x16x32_bf16 v[126:129], v[184:187], v[224:227], v[126:129]
	s_setprio 0
	s_nop 7
	s_barrier
	s_load_dwordx2 s[58:59], s[12:13], 0x100
	v_lshrrev_b32_e32 v241, 5, v131
	v_and_b32_e32 v242, 31, v131
	v_lshlrev_b32_e32 v243, 4, v242
	s_movk_i32 s56, 0x210
	v_mad_u32_u24 v239, v241, s56, v243
	v_add_u32_e32 v239, 16, v239
	v_lshlrev_b32_e32 v240, 13, v241
	v_or_b32_e32 v240, v240, v243
	s_lshl_b32 s56, s53, 13
	s_lshl_b32 s57, s54, 2
	s_add_i32 s56, s56, s57
	s_waitcnt lgkmcnt(0)
	s_add_u32 s58, s58, s56
	s_addc_u32 s59, s59, 0
	ds_write_b32 v238, v2
	ds_write_b32 v238, v3 offset:528
	ds_write_b32 v238, v4 offset:1056
	ds_write_b32 v238, v5 offset:1584
	ds_write_b32 v238, v6 offset:64
	ds_write_b32 v238, v7 offset:592
	ds_write_b32 v238, v8 offset:1120
	ds_write_b32 v238, v9 offset:1648
	ds_write_b32 v238, v10 offset:128
	ds_write_b32 v238, v11 offset:656
	ds_write_b32 v238, v12 offset:1184
	ds_write_b32 v238, v13 offset:1712
	ds_write_b32 v238, v14 offset:192
	ds_write_b32 v238, v15 offset:720
	ds_write_b32 v238, v16 offset:1248
	ds_write_b32 v238, v17 offset:1776
	ds_write_b32 v238, v18 offset:8448
	ds_write_b32 v238, v19 offset:8976
	ds_write_b32 v238, v20 offset:9504
	ds_write_b32 v238, v21 offset:10032
	ds_write_b32 v238, v22 offset:8512
	ds_write_b32 v238, v23 offset:9040
	ds_write_b32 v238, v24 offset:9568
	ds_write_b32 v238, v25 offset:10096
	ds_write_b32 v238, v26 offset:8576
	ds_write_b32 v238, v27 offset:9104
	ds_write_b32 v238, v28 offset:9632
	ds_write_b32 v238, v29 offset:10160
	ds_write_b32 v238, v30 offset:8640
	ds_write_b32 v238, v31 offset:9168
	ds_write_b32 v238, v32 offset:9696
	ds_write_b32 v238, v33 offset:10224
	ds_write_b32 v238, v34 offset:16896
	ds_write_b32 v238, v35 offset:17424
	ds_write_b32 v238, v36 offset:17952
	ds_write_b32 v238, v37 offset:18480
	ds_write_b32 v238, v38 offset:16960
	ds_write_b32 v238, v39 offset:17488
	ds_write_b32 v238, v40 offset:18016
	ds_write_b32 v238, v41 offset:18544
	ds_write_b32 v238, v42 offset:17024
	ds_write_b32 v238, v43 offset:17552
	ds_write_b32 v238, v44 offset:18080
	ds_write_b32 v238, v45 offset:18608
	ds_write_b32 v238, v46 offset:17088
	ds_write_b32 v238, v47 offset:17616
	ds_write_b32 v238, v48 offset:18144
	ds_write_b32 v238, v49 offset:18672
	ds_write_b32 v238, v50 offset:25344
	ds_write_b32 v238, v51 offset:25872
	ds_write_b32 v238, v52 offset:26400
	ds_write_b32 v238, v53 offset:26928
	ds_write_b32 v238, v54 offset:25408
	ds_write_b32 v238, v55 offset:25936
	ds_write_b32 v238, v56 offset:26464
	ds_write_b32 v238, v57 offset:26992
	ds_write_b32 v238, v58 offset:25472
	ds_write_b32 v238, v59 offset:26000
	ds_write_b32 v238, v60 offset:26528
	ds_write_b32 v238, v61 offset:27056
	ds_write_b32 v238, v62 offset:25536
	ds_write_b32 v238, v63 offset:26064
	ds_write_b32 v238, v64 offset:26592
	ds_write_b32 v238, v65 offset:27120
	s_mov_b32 s0, s58
	s_mov_b32 s1, s59
	global_load_dwordx4 v[136:139], v240, s[0:1]
	s_add_u32 s0, s0, 0x10000
	s_addc_u32 s1, s1, 0
	global_load_dwordx4 v[140:143], v240, s[0:1]
	s_add_u32 s0, s0, 0x10000
	s_addc_u32 s1, s1, 0
	global_load_dwordx4 v[144:147], v240, s[0:1]
	s_add_u32 s0, s0, 0x10000
	s_addc_u32 s1, s1, 0
	global_load_dwordx4 v[148:151], v240, s[0:1]
	s_add_u32 s0, s0, 0x10000
	s_addc_u32 s1, s1, 0
	global_load_dwordx4 v[172:175], v240, s[0:1]
	s_add_u32 s0, s0, 0x10000
	s_addc_u32 s1, s1, 0
	global_load_dwordx4 v[176:179], v240, s[0:1]
	s_add_u32 s0, s0, 0x10000
	s_addc_u32 s1, s1, 0
	global_load_dwordx4 v[180:183], v240, s[0:1]
	s_add_u32 s0, s0, 0x10000
	s_addc_u32 s1, s1, 0
	global_load_dwordx4 v[184:187], v240, s[0:1]
	s_add_u32 s0, s0, 0x10000
	s_addc_u32 s1, s1, 0
	global_load_dwordx4 v[188:191], v240, s[0:1]
	s_add_u32 s0, s0, 0x10000
	s_addc_u32 s1, s1, 0
	global_load_dwordx4 v[196:199], v240, s[0:1]
	s_add_u32 s0, s0, 0x10000
	s_addc_u32 s1, s1, 0
	global_load_dwordx4 v[200:203], v240, s[0:1]
	s_add_u32 s0, s0, 0x10000
	s_addc_u32 s1, s1, 0
	global_load_dwordx4 v[204:207], v240, s[0:1]
	s_add_u32 s0, s0, 0x10000
	s_addc_u32 s1, s1, 0
	global_load_dwordx4 v[212:215], v240, s[0:1]
	s_add_u32 s0, s0, 0x10000
	s_addc_u32 s1, s1, 0
	global_load_dwordx4 v[216:219], v240, s[0:1]
	s_add_u32 s0, s0, 0x10000
	s_addc_u32 s1, s1, 0
	global_load_dwordx4 v[220:223], v240, s[0:1]
	s_add_u32 s0, s0, 0x10000
	s_addc_u32 s1, s1, 0
	global_load_dwordx4 v[224:227], v240, s[0:1]
	s_waitcnt lgkmcnt(0)
	s_barrier
	ds_read_b128 v[2:5], v239
	ds_read_b128 v[6:9], v239 offset:4224
	ds_read_b128 v[10:13], v239 offset:8448
	ds_read_b128 v[14:17], v239 offset:12672
	ds_read_b128 v[18:21], v239 offset:16896
	ds_read_b128 v[22:25], v239 offset:21120
	ds_read_b128 v[26:29], v239 offset:25344
	ds_read_b128 v[30:33], v239 offset:29568
	ds_read_b128 v[34:37], v239 offset:33792
	ds_read_b128 v[38:41], v239 offset:38016
	ds_read_b128 v[42:45], v239 offset:42240
	ds_read_b128 v[46:49], v239 offset:46464
	ds_read_b128 v[50:53], v239 offset:50688
	ds_read_b128 v[54:57], v239 offset:54912
	ds_read_b128 v[58:61], v239 offset:59136
	ds_read_b128 v[62:65], v239 offset:63360
	s_mov_b32 s0, s58
	s_mov_b32 s1, s59
	s_waitcnt vmcnt(15) lgkmcnt(15)
	v_pk_add_f32 v[2:3], v[2:3], v[136:137]
	v_pk_add_f32 v[4:5], v[4:5], v[138:139]
	s_waitcnt vmcnt(14) lgkmcnt(14)
	v_pk_add_f32 v[6:7], v[6:7], v[140:141]
	v_pk_add_f32 v[8:9], v[8:9], v[142:143]
	s_waitcnt vmcnt(13) lgkmcnt(13)
	v_pk_add_f32 v[10:11], v[10:11], v[144:145]
	v_pk_add_f32 v[12:13], v[12:13], v[146:147]
	s_waitcnt vmcnt(12) lgkmcnt(12)
	v_pk_add_f32 v[14:15], v[14:15], v[148:149]
	v_pk_add_f32 v[16:17], v[16:17], v[150:151]
	s_waitcnt vmcnt(11) lgkmcnt(11)
	v_pk_add_f32 v[18:19], v[18:19], v[172:173]
	v_pk_add_f32 v[20:21], v[20:21], v[174:175]
	s_waitcnt vmcnt(10) lgkmcnt(10)
	v_pk_add_f32 v[22:23], v[22:23], v[176:177]
	v_pk_add_f32 v[24:25], v[24:25], v[178:179]
	s_waitcnt vmcnt(9) lgkmcnt(9)
	v_pk_add_f32 v[26:27], v[26:27], v[180:181]
	v_pk_add_f32 v[28:29], v[28:29], v[182:183]
	s_waitcnt vmcnt(8) lgkmcnt(8)
	v_pk_add_f32 v[30:31], v[30:31], v[184:185]
	v_pk_add_f32 v[32:33], v[32:33], v[186:187]
	s_waitcnt vmcnt(7) lgkmcnt(7)
	v_pk_add_f32 v[34:35], v[34:35], v[188:189]
	v_pk_add_f32 v[36:37], v[36:37], v[190:191]
	s_waitcnt vmcnt(6) lgkmcnt(6)
	v_pk_add_f32 v[38:39], v[38:39], v[196:197]
	v_pk_add_f32 v[40:41], v[40:41], v[198:199]
	s_waitcnt vmcnt(5) lgkmcnt(5)
	v_pk_add_f32 v[42:43], v[42:43], v[200:201]
	v_pk_add_f32 v[44:45], v[44:45], v[202:203]
	s_waitcnt vmcnt(4) lgkmcnt(4)
	v_pk_add_f32 v[46:47], v[46:47], v[204:205]
	v_pk_add_f32 v[48:49], v[48:49], v[206:207]
	s_waitcnt vmcnt(3) lgkmcnt(3)
	v_pk_add_f32 v[50:51], v[50:51], v[212:213]
	v_pk_add_f32 v[52:53], v[52:53], v[214:215]
	s_waitcnt vmcnt(2) lgkmcnt(2)
	v_pk_add_f32 v[54:55], v[54:55], v[216:217]
	v_pk_add_f32 v[56:57], v[56:57], v[218:219]
	s_waitcnt vmcnt(1) lgkmcnt(1)
	v_pk_add_f32 v[58:59], v[58:59], v[220:221]
	v_pk_add_f32 v[60:61], v[60:61], v[222:223]
	s_waitcnt vmcnt(0) lgkmcnt(0)
	v_pk_add_f32 v[62:63], v[62:63], v[224:225]
	v_pk_add_f32 v[64:65], v[64:65], v[226:227]
	global_store_dwordx4 v240, v[2:5], s[0:1]
	s_add_u32 s0, s0, 0x10000
	s_addc_u32 s1, s1, 0
	global_store_dwordx4 v240, v[6:9], s[0:1]
	s_add_u32 s0, s0, 0x10000
	s_addc_u32 s1, s1, 0
	global_store_dwordx4 v240, v[10:13], s[0:1]
	s_add_u32 s0, s0, 0x10000
	s_addc_u32 s1, s1, 0
	global_store_dwordx4 v240, v[14:17], s[0:1]
	s_add_u32 s0, s0, 0x10000
	s_addc_u32 s1, s1, 0
	global_store_dwordx4 v240, v[18:21], s[0:1]
	s_add_u32 s0, s0, 0x10000
	s_addc_u32 s1, s1, 0
	global_store_dwordx4 v240, v[22:25], s[0:1]
	s_add_u32 s0, s0, 0x10000
	s_addc_u32 s1, s1, 0
	global_store_dwordx4 v240, v[26:29], s[0:1]
	s_add_u32 s0, s0, 0x10000
	s_addc_u32 s1, s1, 0
	global_store_dwordx4 v240, v[30:33], s[0:1]
	s_add_u32 s0, s0, 0x10000
	s_addc_u32 s1, s1, 0
	global_store_dwordx4 v240, v[34:37], s[0:1]
	s_add_u32 s0, s0, 0x10000
	s_addc_u32 s1, s1, 0
	global_store_dwordx4 v240, v[38:41], s[0:1]
	s_add_u32 s0, s0, 0x10000
	s_addc_u32 s1, s1, 0
	global_store_dwordx4 v240, v[42:45], s[0:1]
	s_add_u32 s0, s0, 0x10000
	s_addc_u32 s1, s1, 0
	global_store_dwordx4 v240, v[46:49], s[0:1]
	s_add_u32 s0, s0, 0x10000
	s_addc_u32 s1, s1, 0
	global_store_dwordx4 v240, v[50:53], s[0:1]
	s_add_u32 s0, s0, 0x10000
	s_addc_u32 s1, s1, 0
	global_store_dwordx4 v240, v[54:57], s[0:1]
	s_add_u32 s0, s0, 0x10000
	s_addc_u32 s1, s1, 0
	global_store_dwordx4 v240, v[58:61], s[0:1]
	s_add_u32 s0, s0, 0x10000
	s_addc_u32 s1, s1, 0
	global_store_dwordx4 v240, v[62:65], s[0:1]
	s_add_u32 s58, s58, 0x1000
	s_addc_u32 s59, s59, 0
	s_waitcnt lgkmcnt(0)
	s_barrier
	ds_write_b32 v238, v66
	ds_write_b32 v238, v67 offset:528
	ds_write_b32 v238, v68 offset:1056
	ds_write_b32 v238, v69 offset:1584
	ds_write_b32 v238, v70 offset:64
	ds_write_b32 v238, v71 offset:592
	ds_write_b32 v238, v72 offset:1120
	ds_write_b32 v238, v73 offset:1648
	ds_write_b32 v238, v74 offset:128
	ds_write_b32 v238, v75 offset:656
	ds_write_b32 v238, v76 offset:1184
	ds_write_b32 v238, v77 offset:1712
	ds_write_b32 v238, v78 offset:192
	ds_write_b32 v238, v79 offset:720
	ds_write_b32 v238, v80 offset:1248
	ds_write_b32 v238, v81 offset:1776
	ds_write_b32 v238, v82 offset:8448
	ds_write_b32 v238, v83 offset:8976
	ds_write_b32 v238, v84 offset:9504
	ds_write_b32 v238, v85 offset:10032
	ds_write_b32 v238, v86 offset:8512
	ds_write_b32 v238, v87 offset:9040
	ds_write_b32 v238, v88 offset:9568
	ds_write_b32 v238, v89 offset:10096
	ds_write_b32 v238, v90 offset:8576
	ds_write_b32 v238, v91 offset:9104
	ds_write_b32 v238, v92 offset:9632
	ds_write_b32 v238, v93 offset:10160
	ds_write_b32 v238, v94 offset:8640
	ds_write_b32 v238, v95 offset:9168
	ds_write_b32 v238, v96 offset:9696
	ds_write_b32 v238, v97 offset:10224
	ds_write_b32 v238, v98 offset:16896
	ds_write_b32 v238, v99 offset:17424
	ds_write_b32 v238, v100 offset:17952
	ds_write_b32 v238, v101 offset:18480
	ds_write_b32 v238, v102 offset:16960
	ds_write_b32 v238, v103 offset:17488
	ds_write_b32 v238, v104 offset:18016
	ds_write_b32 v238, v105 offset:18544
	ds_write_b32 v238, v106 offset:17024
	ds_write_b32 v238, v107 offset:17552
	ds_write_b32 v238, v108 offset:18080
	ds_write_b32 v238, v109 offset:18608
	ds_write_b32 v238, v110 offset:17088
	ds_write_b32 v238, v111 offset:17616
	ds_write_b32 v238, v112 offset:18144
	ds_write_b32 v238, v113 offset:18672
	ds_write_b32 v238, v114 offset:25344
	ds_write_b32 v238, v115 offset:25872
	ds_write_b32 v238, v116 offset:26400
	ds_write_b32 v238, v117 offset:26928
	ds_write_b32 v238, v118 offset:25408
	ds_write_b32 v238, v119 offset:25936
	ds_write_b32 v238, v120 offset:26464
	ds_write_b32 v238, v121 offset:26992
	ds_write_b32 v238, v122 offset:25472
	ds_write_b32 v238, v123 offset:26000
	ds_write_b32 v238, v124 offset:26528
	ds_write_b32 v238, v125 offset:27056
	ds_write_b32 v238, v126 offset:25536
	ds_write_b32 v238, v127 offset:26064
	ds_write_b32 v238, v128 offset:26592
	ds_write_b32 v238, v129 offset:27120
	s_mov_b32 s0, s58
	s_mov_b32 s1, s59
	global_load_dwordx4 v[136:139], v240, s[0:1]
	s_add_u32 s0, s0, 0x10000
	s_addc_u32 s1, s1, 0
	global_load_dwordx4 v[140:143], v240, s[0:1]
	s_add_u32 s0, s0, 0x10000
	s_addc_u32 s1, s1, 0
	global_load_dwordx4 v[144:147], v240, s[0:1]
	s_add_u32 s0, s0, 0x10000
	s_addc_u32 s1, s1, 0
	global_load_dwordx4 v[148:151], v240, s[0:1]
	s_add_u32 s0, s0, 0x10000
	s_addc_u32 s1, s1, 0
	global_load_dwordx4 v[172:175], v240, s[0:1]
	s_add_u32 s0, s0, 0x10000
	s_addc_u32 s1, s1, 0
	global_load_dwordx4 v[176:179], v240, s[0:1]
	s_add_u32 s0, s0, 0x10000
	s_addc_u32 s1, s1, 0
	global_load_dwordx4 v[180:183], v240, s[0:1]
	s_add_u32 s0, s0, 0x10000
	s_addc_u32 s1, s1, 0
	global_load_dwordx4 v[184:187], v240, s[0:1]
	s_add_u32 s0, s0, 0x10000
	s_addc_u32 s1, s1, 0
	global_load_dwordx4 v[188:191], v240, s[0:1]
	s_add_u32 s0, s0, 0x10000
	s_addc_u32 s1, s1, 0
	global_load_dwordx4 v[196:199], v240, s[0:1]
	s_add_u32 s0, s0, 0x10000
	s_addc_u32 s1, s1, 0
	global_load_dwordx4 v[200:203], v240, s[0:1]
	s_add_u32 s0, s0, 0x10000
	s_addc_u32 s1, s1, 0
	global_load_dwordx4 v[204:207], v240, s[0:1]
	s_add_u32 s0, s0, 0x10000
	s_addc_u32 s1, s1, 0
	global_load_dwordx4 v[212:215], v240, s[0:1]
	s_add_u32 s0, s0, 0x10000
	s_addc_u32 s1, s1, 0
	global_load_dwordx4 v[216:219], v240, s[0:1]
	s_add_u32 s0, s0, 0x10000
	s_addc_u32 s1, s1, 0
	global_load_dwordx4 v[220:223], v240, s[0:1]
	s_add_u32 s0, s0, 0x10000
	s_addc_u32 s1, s1, 0
	global_load_dwordx4 v[224:227], v240, s[0:1]
	s_waitcnt lgkmcnt(0)
	s_barrier
	ds_read_b128 v[66:69], v239
	ds_read_b128 v[70:73], v239 offset:4224
	ds_read_b128 v[74:77], v239 offset:8448
	ds_read_b128 v[78:81], v239 offset:12672
	ds_read_b128 v[82:85], v239 offset:16896
	ds_read_b128 v[86:89], v239 offset:21120
	ds_read_b128 v[90:93], v239 offset:25344
	ds_read_b128 v[94:97], v239 offset:29568
	ds_read_b128 v[98:101], v239 offset:33792
	ds_read_b128 v[102:105], v239 offset:38016
	ds_read_b128 v[106:109], v239 offset:42240
	ds_read_b128 v[110:113], v239 offset:46464
	ds_read_b128 v[114:117], v239 offset:50688
	ds_read_b128 v[118:121], v239 offset:54912
	ds_read_b128 v[122:125], v239 offset:59136
	ds_read_b128 v[126:129], v239 offset:63360
	s_mov_b32 s0, s58
	s_mov_b32 s1, s59
	s_waitcnt vmcnt(15) lgkmcnt(15)
	v_pk_add_f32 v[66:67], v[66:67], v[136:137]
	v_pk_add_f32 v[68:69], v[68:69], v[138:139]
	s_waitcnt vmcnt(14) lgkmcnt(14)
	v_pk_add_f32 v[70:71], v[70:71], v[140:141]
	v_pk_add_f32 v[72:73], v[72:73], v[142:143]
	s_waitcnt vmcnt(13) lgkmcnt(13)
	v_pk_add_f32 v[74:75], v[74:75], v[144:145]
	v_pk_add_f32 v[76:77], v[76:77], v[146:147]
	s_waitcnt vmcnt(12) lgkmcnt(12)
	v_pk_add_f32 v[78:79], v[78:79], v[148:149]
	v_pk_add_f32 v[80:81], v[80:81], v[150:151]
	s_waitcnt vmcnt(11) lgkmcnt(11)
	v_pk_add_f32 v[82:83], v[82:83], v[172:173]
	v_pk_add_f32 v[84:85], v[84:85], v[174:175]
	s_waitcnt vmcnt(10) lgkmcnt(10)
	v_pk_add_f32 v[86:87], v[86:87], v[176:177]
	v_pk_add_f32 v[88:89], v[88:89], v[178:179]
	s_waitcnt vmcnt(9) lgkmcnt(9)
	v_pk_add_f32 v[90:91], v[90:91], v[180:181]
	v_pk_add_f32 v[92:93], v[92:93], v[182:183]
	s_waitcnt vmcnt(8) lgkmcnt(8)
	v_pk_add_f32 v[94:95], v[94:95], v[184:185]
	v_pk_add_f32 v[96:97], v[96:97], v[186:187]
	s_waitcnt vmcnt(7) lgkmcnt(7)
	v_pk_add_f32 v[98:99], v[98:99], v[188:189]
	v_pk_add_f32 v[100:101], v[100:101], v[190:191]
	s_waitcnt vmcnt(6) lgkmcnt(6)
	v_pk_add_f32 v[102:103], v[102:103], v[196:197]
	v_pk_add_f32 v[104:105], v[104:105], v[198:199]
	s_waitcnt vmcnt(5) lgkmcnt(5)
	v_pk_add_f32 v[106:107], v[106:107], v[200:201]
	v_pk_add_f32 v[108:109], v[108:109], v[202:203]
	s_waitcnt vmcnt(4) lgkmcnt(4)
	v_pk_add_f32 v[110:111], v[110:111], v[204:205]
	v_pk_add_f32 v[112:113], v[112:113], v[206:207]
	s_waitcnt vmcnt(3) lgkmcnt(3)
	v_pk_add_f32 v[114:115], v[114:115], v[212:213]
	v_pk_add_f32 v[116:117], v[116:117], v[214:215]
	s_waitcnt vmcnt(2) lgkmcnt(2)
	v_pk_add_f32 v[118:119], v[118:119], v[216:217]
	v_pk_add_f32 v[120:121], v[120:121], v[218:219]
	s_waitcnt vmcnt(1) lgkmcnt(1)
	v_pk_add_f32 v[122:123], v[122:123], v[220:221]
	v_pk_add_f32 v[124:125], v[124:125], v[222:223]
	s_waitcnt vmcnt(0) lgkmcnt(0)
	v_pk_add_f32 v[126:127], v[126:127], v[224:225]
	v_pk_add_f32 v[128:129], v[128:129], v[226:227]
	global_store_dwordx4 v240, v[66:69], s[0:1]
	s_add_u32 s0, s0, 0x10000
	s_addc_u32 s1, s1, 0
	global_store_dwordx4 v240, v[70:73], s[0:1]
	s_add_u32 s0, s0, 0x10000
	s_addc_u32 s1, s1, 0
	global_store_dwordx4 v240, v[74:77], s[0:1]
	s_add_u32 s0, s0, 0x10000
	s_addc_u32 s1, s1, 0
	global_store_dwordx4 v240, v[78:81], s[0:1]
	s_add_u32 s0, s0, 0x10000
	s_addc_u32 s1, s1, 0
	global_store_dwordx4 v240, v[82:85], s[0:1]
	s_add_u32 s0, s0, 0x10000
	s_addc_u32 s1, s1, 0
	global_store_dwordx4 v240, v[86:89], s[0:1]
	s_add_u32 s0, s0, 0x10000
	s_addc_u32 s1, s1, 0
	global_store_dwordx4 v240, v[90:93], s[0:1]
	s_add_u32 s0, s0, 0x10000
	s_addc_u32 s1, s1, 0
	global_store_dwordx4 v240, v[94:97], s[0:1]
	s_add_u32 s0, s0, 0x10000
	s_addc_u32 s1, s1, 0
	global_store_dwordx4 v240, v[98:101], s[0:1]
	s_add_u32 s0, s0, 0x10000
	s_addc_u32 s1, s1, 0
	global_store_dwordx4 v240, v[102:105], s[0:1]
	s_add_u32 s0, s0, 0x10000
	s_addc_u32 s1, s1, 0
	global_store_dwordx4 v240, v[106:109], s[0:1]
	s_add_u32 s0, s0, 0x10000
	s_addc_u32 s1, s1, 0
	global_store_dwordx4 v240, v[110:113], s[0:1]
	s_add_u32 s0, s0, 0x10000
	s_addc_u32 s1, s1, 0
	global_store_dwordx4 v240, v[114:117], s[0:1]
	s_add_u32 s0, s0, 0x10000
	s_addc_u32 s1, s1, 0
	global_store_dwordx4 v240, v[118:121], s[0:1]
	s_add_u32 s0, s0, 0x10000
	s_addc_u32 s1, s1, 0
	global_store_dwordx4 v240, v[122:125], s[0:1]
	s_add_u32 s0, s0, 0x10000
	s_addc_u32 s1, s1, 0
	global_store_dwordx4 v240, v[126:129], s[0:1]
	s_add_i32 s21, s21, s72
	s_cmpk_lt_i32 s21, 0x200
	s_waitcnt lgkmcnt(0)
	s_barrier
	s_cbranch_scc1 .Lfin3_tile

.Lgu2_loop:
	s_setprio 3
	v_add_u32_e32 v234, s22, v232
	v_add_u32_e32 v236, s28, v232
	v_add_u32_e32 v235, s22, v233
	v_add_u32_e32 v237, s28, v233
	ds_read_b128 v[136:139], v234
	ds_read_b128 v[140:143], v234 offset:2048
	ds_read_b128 v[144:147], v234 offset:4096
	ds_read_b128 v[148:151], v234 offset:6144
	ds_read_b128 v[188:191], v236
	ds_read_b128 v[196:199], v236 offset:2048
	ds_read_b128 v[200:203], v236 offset:4096
	ds_read_b128 v[204:207], v236 offset:6144
	ds_read_b128 v[172:175], v235
	ds_read_b128 v[176:179], v235 offset:2048
	ds_read_b128 v[180:183], v235 offset:4096
	ds_read_b128 v[184:187], v235 offset:6144
	ds_read_b128 v[212:215], v237
	ds_read_b128 v[216:219], v237 offset:2048
	ds_read_b128 v[220:223], v237 offset:4096
	ds_read_b128 v[224:227], v237 offset:6144
	s_add_i32 m0, s51, 0xc000
	s_nop 0
	global_load_lds_dwordx4 v228, s[44:45]
	s_add_i32 m0, s51, 0xc400
	s_nop 0
	global_load_lds_dwordx4 v230, s[44:45]
	s_add_i32 m0, s51, 0xe000
	s_nop 0
	global_load_lds_dwordx4 v229, s[44:45]
	s_add_i32 m0, s51, 0xe400
	s_nop 0
	global_load_lds_dwordx4 v231, s[44:45]
	s_add_i32 m0, s51, 0x10000
	s_nop 0
	global_load_lds_dwordx4 v228, s[46:47]
	s_add_i32 m0, s51, 0x10400
	s_nop 0
	global_load_lds_dwordx4 v230, s[46:47]
	s_waitcnt lgkmcnt(8)
	s_setprio 1
	v_mfma_f32_16x16x32_bf16 v[2:5], v[136:139], v[188:191], v[2:5]
	v_mfma_f32_16x16x32_bf16 v[6:9], v[136:139], v[196:199], v[6:9]
	v_mfma_f32_16x16x32_bf16 v[10:13], v[136:139], v[200:203], v[10:13]
	v_mfma_f32_16x16x32_bf16 v[14:17], v[136:139], v[204:207], v[14:17]
	v_mfma_f32_16x16x32_bf16 v[18:21], v[140:143], v[188:191], v[18:21]
	v_mfma_f32_16x16x32_bf16 v[22:25], v[140:143], v[196:199], v[22:25]
	v_mfma_f32_16x16x32_bf16 v[26:29], v[140:143], v[200:203], v[26:29]
	v_mfma_f32_16x16x32_bf16 v[30:33], v[140:143], v[204:207], v[30:33]
	v_mfma_f32_16x16x32_bf16 v[34:37], v[144:147], v[188:191], v[34:37]
	v_mfma_f32_16x16x32_bf16 v[38:41], v[144:147], v[196:199], v[38:41]
	v_mfma_f32_16x16x32_bf16 v[42:45], v[144:147], v[200:203], v[42:45]
	v_mfma_f32_16x16x32_bf16 v[46:49], v[144:147], v[204:207], v[46:49]
	v_mfma_f32_16x16x32_bf16 v[50:53], v[148:151], v[188:191], v[50:53]
	v_mfma_f32_16x16x32_bf16 v[54:57], v[148:151], v[196:199], v[54:57]
	v_mfma_f32_16x16x32_bf16 v[58:61], v[148:151], v[200:203], v[58:61]
	v_mfma_f32_16x16x32_bf16 v[62:65], v[148:151], v[204:207], v[62:65]
	s_waitcnt lgkmcnt(0)
	v_mfma_f32_16x16x32_bf16 v[2:5], v[172:175], v[212:215], v[2:5]
	v_mfma_f32_16x16x32_bf16 v[6:9], v[172:175], v[216:219], v[6:9]
	v_mfma_f32_16x16x32_bf16 v[10:13], v[172:175], v[220:223], v[10:13]
	v_mfma_f32_16x16x32_bf16 v[14:17], v[172:175], v[224:227], v[14:17]
	v_mfma_f32_16x16x32_bf16 v[18:21], v[176:179], v[212:215], v[18:21]
	v_mfma_f32_16x16x32_bf16 v[22:25], v[176:179], v[216:219], v[22:25]
	v_mfma_f32_16x16x32_bf16 v[26:29], v[176:179], v[220:223], v[26:29]
	v_mfma_f32_16x16x32_bf16 v[30:33], v[176:179], v[224:227], v[30:33]
	v_mfma_f32_16x16x32_bf16 v[34:37], v[180:183], v[212:215], v[34:37]
	v_mfma_f32_16x16x32_bf16 v[38:41], v[180:183], v[216:219], v[38:41]
	v_mfma_f32_16x16x32_bf16 v[42:45], v[180:183], v[220:223], v[42:45]
	v_mfma_f32_16x16x32_bf16 v[46:49], v[180:183], v[224:227], v[46:49]
	v_mfma_f32_16x16x32_bf16 v[50:53], v[184:187], v[212:215], v[50:53]
	v_mfma_f32_16x16x32_bf16 v[54:57], v[184:187], v[216:219], v[54:57]
	v_mfma_f32_16x16x32_bf16 v[58:61], v[184:187], v[220:223], v[58:61]
	v_mfma_f32_16x16x32_bf16 v[62:65], v[184:187], v[224:227], v[62:65]
	s_setprio 0
	s_waitcnt vmcnt(6)
	s_barrier
.Lgu2_loop_a0:
	s_setprio 3
	v_add_u32_e32 v236, s40, v232
	v_add_u32_e32 v237, s40, v233
	ds_read_b128 v[188:191], v236
	ds_read_b128 v[196:199], v236 offset:2048
	ds_read_b128 v[200:203], v236 offset:4096
	ds_read_b128 v[204:207], v236 offset:6144
	ds_read_b128 v[212:215], v237
	ds_read_b128 v[216:219], v237 offset:2048
	ds_read_b128 v[220:223], v237 offset:4096
	ds_read_b128 v[224:227], v237 offset:6144
	s_mov_b32 m0, s51
	s_nop 0
	global_load_lds_dwordx4 v229, s[46:47]
	s_add_i32 m0, s51, 0x400
	s_nop 0
	global_load_lds_dwordx4 v231, s[46:47]
	s_add_i32 m0, s51, 0x2000
	s_nop 0
	global_load_lds_dwordx4 v228, s[48:49]
	s_add_i32 m0, s51, 0x2400
	s_nop 0
	global_load_lds_dwordx4 v230, s[48:49]
	s_add_i32 m0, s51, 0x4000
	s_nop 0
	global_load_lds_dwordx4 v229, s[48:49]
	s_add_i32 m0, s51, 0x4400
	s_nop 0
	global_load_lds_dwordx4 v231, s[48:49]
	s_waitcnt lgkmcnt(4)
	s_setprio 1
	v_mfma_f32_16x16x32_bf16 v[66:69], v[136:139], v[188:191], v[66:69]
	v_mfma_f32_16x16x32_bf16 v[70:73], v[136:139], v[196:199], v[70:73]
	v_mfma_f32_16x16x32_bf16 v[74:77], v[136:139], v[200:203], v[74:77]
	v_mfma_f32_16x16x32_bf16 v[78:81], v[136:139], v[204:207], v[78:81]
	v_mfma_f32_16x16x32_bf16 v[82:85], v[140:143], v[188:191], v[82:85]
	v_mfma_f32_16x16x32_bf16 v[86:89], v[140:143], v[196:199], v[86:89]
	v_mfma_f32_16x16x32_bf16 v[90:93], v[140:143], v[200:203], v[90:93]
	v_mfma_f32_16x16x32_bf16 v[94:97], v[140:143], v[204:207], v[94:97]
	v_mfma_f32_16x16x32_bf16 v[98:101], v[144:147], v[188:191], v[98:101]
	v_mfma_f32_16x16x32_bf16 v[102:105], v[144:147], v[196:199], v[102:105]
	v_mfma_f32_16x16x32_bf16 v[106:109], v[144:147], v[200:203], v[106:109]
	v_mfma_f32_16x16x32_bf16 v[110:113], v[144:147], v[204:207], v[110:113]
	v_mfma_f32_16x16x32_bf16 v[114:117], v[148:151], v[188:191], v[114:117]
	v_mfma_f32_16x16x32_bf16 v[118:121], v[148:151], v[196:199], v[118:121]
	v_mfma_f32_16x16x32_bf16 v[122:125], v[148:151], v[200:203], v[122:125]
	v_mfma_f32_16x16x32_bf16 v[126:129], v[148:151], v[204:207], v[126:129]
	s_waitcnt lgkmcnt(0)
	v_mfma_f32_16x16x32_bf16 v[66:69], v[172:175], v[212:215], v[66:69]
	v_mfma_f32_16x16x32_bf16 v[70:73], v[172:175], v[216:219], v[70:73]
	v_mfma_f32_16x16x32_bf16 v[74:77], v[172:175], v[220:223], v[74:77]
	v_mfma_f32_16x16x32_bf16 v[78:81], v[172:175], v[224:227], v[78:81]
	v_mfma_f32_16x16x32_bf16 v[82:85], v[176:179], v[212:215], v[82:85]
	v_mfma_f32_16x16x32_bf16 v[86:89], v[176:179], v[216:219], v[86:89]
	v_mfma_f32_16x16x32_bf16 v[90:93], v[176:179], v[220:223], v[90:93]
	v_mfma_f32_16x16x32_bf16 v[94:97], v[176:179], v[224:227], v[94:97]
	v_mfma_f32_16x16x32_bf16 v[98:101], v[180:183], v[212:215], v[98:101]
	v_mfma_f32_16x16x32_bf16 v[102:105], v[180:183], v[216:219], v[102:105]
	v_mfma_f32_16x16x32_bf16 v[106:109], v[180:183], v[220:223], v[106:109]
	v_mfma_f32_16x16x32_bf16 v[110:113], v[180:183], v[224:227], v[110:113]
	v_mfma_f32_16x16x32_bf16 v[114:117], v[184:187], v[212:215], v[114:117]
	v_mfma_f32_16x16x32_bf16 v[118:121], v[184:187], v[216:219], v[118:121]
	v_mfma_f32_16x16x32_bf16 v[122:125], v[184:187], v[220:223], v[122:125]
	v_mfma_f32_16x16x32_bf16 v[126:129], v[184:187], v[224:227], v[126:129]
	s_setprio 0
	v_add_u32_e32 v228, 0x80, v228
	v_add_u32_e32 v229, 0x80, v229
	v_add_u32_e32 v230, 0x80, v230
	v_add_u32_e32 v231, 0x80, v231
	s_waitcnt vmcnt(4)
	s_barrier
	s_setprio 3
	v_add_u32_e32 v234, s23, v232
	v_add_u32_e32 v236, s29, v232
	v_add_u32_e32 v235, s23, v233
	v_add_u32_e32 v237, s29, v233
	ds_read_b128 v[136:139], v234
	ds_read_b128 v[140:143], v234 offset:2048
	ds_read_b128 v[144:147], v234 offset:4096
	ds_read_b128 v[148:151], v234 offset:6144
	ds_read_b128 v[188:191], v236
	ds_read_b128 v[196:199], v236 offset:2048
	ds_read_b128 v[200:203], v236 offset:4096
	ds_read_b128 v[204:207], v236 offset:6144
	ds_read_b128 v[172:175], v235
	ds_read_b128 v[176:179], v235 offset:2048
	ds_read_b128 v[180:183], v235 offset:4096
	ds_read_b128 v[184:187], v235 offset:6144
	ds_read_b128 v[212:215], v237
	ds_read_b128 v[216:219], v237 offset:2048
	ds_read_b128 v[220:223], v237 offset:4096
	ds_read_b128 v[224:227], v237 offset:6144
	s_add_i32 m0, s51, 0x6000
	s_nop 0
	global_load_lds_dwordx4 v228, s[44:45]
	s_add_i32 m0, s51, 0x6400
	s_nop 0
	global_load_lds_dwordx4 v230, s[44:45]
	s_add_i32 m0, s51, 0x8000
	s_nop 0
	global_load_lds_dwordx4 v229, s[44:45]
	s_add_i32 m0, s51, 0x8400
	s_nop 0
	global_load_lds_dwordx4 v231, s[44:45]
	s_add_i32 m0, s51, 0xa000
	s_nop 0
	global_load_lds_dwordx4 v228, s[46:47]
	s_add_i32 m0, s51, 0xa400
	s_nop 0
	global_load_lds_dwordx4 v230, s[46:47]
	s_waitcnt lgkmcnt(8)
	s_setprio 1
	v_mfma_f32_16x16x32_bf16 v[2:5], v[136:139], v[188:191], v[2:5]
	v_mfma_f32_16x16x32_bf16 v[6:9], v[136:139], v[196:199], v[6:9]
	v_mfma_f32_16x16x32_bf16 v[10:13], v[136:139], v[200:203], v[10:13]
	v_mfma_f32_16x16x32_bf16 v[14:17], v[136:139], v[204:207], v[14:17]
	v_mfma_f32_16x16x32_bf16 v[18:21], v[140:143], v[188:191], v[18:21]
	v_mfma_f32_16x16x32_bf16 v[22:25], v[140:143], v[196:199], v[22:25]
	v_mfma_f32_16x16x32_bf16 v[26:29], v[140:143], v[200:203], v[26:29]
	v_mfma_f32_16x16x32_bf16 v[30:33], v[140:143], v[204:207], v[30:33]
	v_mfma_f32_16x16x32_bf16 v[34:37], v[144:147], v[188:191], v[34:37]
	v_mfma_f32_16x16x32_bf16 v[38:41], v[144:147], v[196:199], v[38:41]
	v_mfma_f32_16x16x32_bf16 v[42:45], v[144:147], v[200:203], v[42:45]
	v_mfma_f32_16x16x32_bf16 v[46:49], v[144:147], v[204:207], v[46:49]
	v_mfma_f32_16x16x32_bf16 v[50:53], v[148:151], v[188:191], v[50:53]
	v_mfma_f32_16x16x32_bf16 v[54:57], v[148:151], v[196:199], v[54:57]
	v_mfma_f32_16x16x32_bf16 v[58:61], v[148:151], v[200:203], v[58:61]
	v_mfma_f32_16x16x32_bf16 v[62:65], v[148:151], v[204:207], v[62:65]
	s_waitcnt lgkmcnt(0)
	v_mfma_f32_16x16x32_bf16 v[2:5], v[172:175], v[212:215], v[2:5]
	v_mfma_f32_16x16x32_bf16 v[6:9], v[172:175], v[216:219], v[6:9]
	v_mfma_f32_16x16x32_bf16 v[10:13], v[172:175], v[220:223], v[10:13]
	v_mfma_f32_16x16x32_bf16 v[14:17], v[172:175], v[224:227], v[14:17]
	v_mfma_f32_16x16x32_bf16 v[18:21], v[176:179], v[212:215], v[18:21]
	v_mfma_f32_16x16x32_bf16 v[22:25], v[176:179], v[216:219], v[22:25]
	v_mfma_f32_16x16x32_bf16 v[26:29], v[176:179], v[220:223], v[26:29]
	v_mfma_f32_16x16x32_bf16 v[30:33], v[176:179], v[224:227], v[30:33]
	v_mfma_f32_16x16x32_bf16 v[34:37], v[180:183], v[212:215], v[34:37]
	v_mfma_f32_16x16x32_bf16 v[38:41], v[180:183], v[216:219], v[38:41]
	v_mfma_f32_16x16x32_bf16 v[42:45], v[180:183], v[220:223], v[42:45]
	v_mfma_f32_16x16x32_bf16 v[46:49], v[180:183], v[224:227], v[46:49]
	v_mfma_f32_16x16x32_bf16 v[50:53], v[184:187], v[212:215], v[50:53]
	v_mfma_f32_16x16x32_bf16 v[54:57], v[184:187], v[216:219], v[54:57]
	v_mfma_f32_16x16x32_bf16 v[58:61], v[184:187], v[220:223], v[58:61]
	v_mfma_f32_16x16x32_bf16 v[62:65], v[184:187], v[224:227], v[62:65]
	s_setprio 0
	s_waitcnt vmcnt(6)
	s_barrier
	s_setprio 3
	v_add_u32_e32 v236, s41, v232
	v_add_u32_e32 v237, s41, v233
	ds_read_b128 v[188:191], v236
	ds_read_b128 v[196:199], v236 offset:2048
	ds_read_b128 v[200:203], v236 offset:4096
	ds_read_b128 v[204:207], v236 offset:6144
	ds_read_b128 v[212:215], v237
	ds_read_b128 v[216:219], v237 offset:2048
	ds_read_b128 v[220:223], v237 offset:4096
	ds_read_b128 v[224:227], v237 offset:6144
	s_add_i32 m0, s51, 0xc000
	s_nop 0
	global_load_lds_dwordx4 v229, s[46:47]
	s_add_i32 m0, s51, 0xc400
	s_nop 0
	global_load_lds_dwordx4 v231, s[46:47]
	s_add_i32 m0, s51, 0xe000
	s_nop 0
	global_load_lds_dwordx4 v228, s[48:49]
	s_add_i32 m0, s51, 0xe400
	s_nop 0
	global_load_lds_dwordx4 v230, s[48:49]
	s_add_i32 m0, s51, 0x10000
	s_nop 0
	global_load_lds_dwordx4 v229, s[48:49]
	s_add_i32 m0, s51, 0x10400
	s_nop 0
	global_load_lds_dwordx4 v231, s[48:49]
	s_waitcnt lgkmcnt(4)
	s_setprio 1
	v_mfma_f32_16x16x32_bf16 v[66:69], v[136:139], v[188:191], v[66:69]
	v_mfma_f32_16x16x32_bf16 v[70:73], v[136:139], v[196:199], v[70:73]
	v_mfma_f32_16x16x32_bf16 v[74:77], v[136:139], v[200:203], v[74:77]
	v_mfma_f32_16x16x32_bf16 v[78:81], v[136:139], v[204:207], v[78:81]
	v_mfma_f32_16x16x32_bf16 v[82:85], v[140:143], v[188:191], v[82:85]
	v_mfma_f32_16x16x32_bf16 v[86:89], v[140:143], v[196:199], v[86:89]
	v_mfma_f32_16x16x32_bf16 v[90:93], v[140:143], v[200:203], v[90:93]
	v_mfma_f32_16x16x32_bf16 v[94:97], v[140:143], v[204:207], v[94:97]
	v_mfma_f32_16x16x32_bf16 v[98:101], v[144:147], v[188:191], v[98:101]
	v_mfma_f32_16x16x32_bf16 v[102:105], v[144:147], v[196:199], v[102:105]
	v_mfma_f32_16x16x32_bf16 v[106:109], v[144:147], v[200:203], v[106:109]
	v_mfma_f32_16x16x32_bf16 v[110:113], v[144:147], v[204:207], v[110:113]
	v_mfma_f32_16x16x32_bf16 v[114:117], v[148:151], v[188:191], v[114:117]
	v_mfma_f32_16x16x32_bf16 v[118:121], v[148:151], v[196:199], v[118:121]
	v_mfma_f32_16x16x32_bf16 v[122:125], v[148:151], v[200:203], v[122:125]
	v_mfma_f32_16x16x32_bf16 v[126:129], v[148:151], v[204:207], v[126:129]
	s_waitcnt lgkmcnt(0)
	v_mfma_f32_16x16x32_bf16 v[66:69], v[172:175], v[212:215], v[66:69]
	v_mfma_f32_16x16x32_bf16 v[70:73], v[172:175], v[216:219], v[70:73]
	v_mfma_f32_16x16x32_bf16 v[74:77], v[172:175], v[220:223], v[74:77]
	v_mfma_f32_16x16x32_bf16 v[78:81], v[172:175], v[224:227], v[78:81]
	v_mfma_f32_16x16x32_bf16 v[82:85], v[176:179], v[212:215], v[82:85]
	v_mfma_f32_16x16x32_bf16 v[86:89], v[176:179], v[216:219], v[86:89]
	v_mfma_f32_16x16x32_bf16 v[90:93], v[176:179], v[220:223], v[90:93]
	v_mfma_f32_16x16x32_bf16 v[94:97], v[176:179], v[224:227], v[94:97]
	v_mfma_f32_16x16x32_bf16 v[98:101], v[180:183], v[212:215], v[98:101]
	v_mfma_f32_16x16x32_bf16 v[102:105], v[180:183], v[216:219], v[102:105]
	v_mfma_f32_16x16x32_bf16 v[106:109], v[180:183], v[220:223], v[106:109]
	v_mfma_f32_16x16x32_bf16 v[110:113], v[180:183], v[224:227], v[110:113]
	v_mfma_f32_16x16x32_bf16 v[114:117], v[184:187], v[212:215], v[114:117]
	v_mfma_f32_16x16x32_bf16 v[118:121], v[184:187], v[216:219], v[118:121]
	v_mfma_f32_16x16x32_bf16 v[122:125], v[184:187], v[220:223], v[122:125]
	v_mfma_f32_16x16x32_bf16 v[126:129], v[184:187], v[224:227], v[126:129]
	s_setprio 0
	v_add_u32_e32 v228, 0x80, v228
	v_add_u32_e32 v229, 0x80, v229
	v_add_u32_e32 v230, 0x80, v230
	v_add_u32_e32 v231, 0x80, v231
	s_waitcnt vmcnt(4)
	s_barrier
	s_setprio 3
	v_add_u32_e32 v234, s24, v232
	v_add_u32_e32 v236, s30, v232
	v_add_u32_e32 v235, s24, v233
	v_add_u32_e32 v237, s30, v233
	ds_read_b128 v[136:139], v234
	ds_read_b128 v[140:143], v234 offset:2048
	ds_read_b128 v[144:147], v234 offset:4096
	ds_read_b128 v[148:151], v234 offset:6144
	ds_read_b128 v[188:191], v236
	ds_read_b128 v[196:199], v236 offset:2048
	ds_read_b128 v[200:203], v236 offset:4096
	ds_read_b128 v[204:207], v236 offset:6144
	ds_read_b128 v[172:175], v235
	ds_read_b128 v[176:179], v235 offset:2048
	ds_read_b128 v[180:183], v235 offset:4096
	ds_read_b128 v[184:187], v235 offset:6144
	ds_read_b128 v[212:215], v237
	ds_read_b128 v[216:219], v237 offset:2048
	ds_read_b128 v[220:223], v237 offset:4096
	ds_read_b128 v[224:227], v237 offset:6144
	s_mov_b32 m0, s51
	s_nop 0
	global_load_lds_dwordx4 v228, s[44:45]
	s_add_i32 m0, s51, 0x400
	s_nop 0
	global_load_lds_dwordx4 v230, s[44:45]
	s_add_i32 m0, s51, 0x2000
	s_nop 0
	global_load_lds_dwordx4 v229, s[44:45]
	s_add_i32 m0, s51, 0x2400
	s_nop 0
	global_load_lds_dwordx4 v231, s[44:45]
	s_add_i32 m0, s51, 0x4000
	s_nop 0
	global_load_lds_dwordx4 v228, s[46:47]
	s_add_i32 m0, s51, 0x4400
	s_nop 0
	global_load_lds_dwordx4 v230, s[46:47]
	s_waitcnt lgkmcnt(8)
	s_setprio 1
	v_mfma_f32_16x16x32_bf16 v[2:5], v[136:139], v[188:191], v[2:5]
	v_mfma_f32_16x16x32_bf16 v[6:9], v[136:139], v[196:199], v[6:9]
	v_mfma_f32_16x16x32_bf16 v[10:13], v[136:139], v[200:203], v[10:13]
	v_mfma_f32_16x16x32_bf16 v[14:17], v[136:139], v[204:207], v[14:17]
	v_mfma_f32_16x16x32_bf16 v[18:21], v[140:143], v[188:191], v[18:21]
	v_mfma_f32_16x16x32_bf16 v[22:25], v[140:143], v[196:199], v[22:25]
	v_mfma_f32_16x16x32_bf16 v[26:29], v[140:143], v[200:203], v[26:29]
	v_mfma_f32_16x16x32_bf16 v[30:33], v[140:143], v[204:207], v[30:33]
	v_mfma_f32_16x16x32_bf16 v[34:37], v[144:147], v[188:191], v[34:37]
	v_mfma_f32_16x16x32_bf16 v[38:41], v[144:147], v[196:199], v[38:41]
	v_mfma_f32_16x16x32_bf16 v[42:45], v[144:147], v[200:203], v[42:45]
	v_mfma_f32_16x16x32_bf16 v[46:49], v[144:147], v[204:207], v[46:49]
	v_mfma_f32_16x16x32_bf16 v[50:53], v[148:151], v[188:191], v[50:53]
	v_mfma_f32_16x16x32_bf16 v[54:57], v[148:151], v[196:199], v[54:57]
	v_mfma_f32_16x16x32_bf16 v[58:61], v[148:151], v[200:203], v[58:61]
	v_mfma_f32_16x16x32_bf16 v[62:65], v[148:151], v[204:207], v[62:65]
	s_waitcnt lgkmcnt(0)
	v_mfma_f32_16x16x32_bf16 v[2:5], v[172:175], v[212:215], v[2:5]
	v_mfma_f32_16x16x32_bf16 v[6:9], v[172:175], v[216:219], v[6:9]
	v_mfma_f32_16x16x32_bf16 v[10:13], v[172:175], v[220:223], v[10:13]
	v_mfma_f32_16x16x32_bf16 v[14:17], v[172:175], v[224:227], v[14:17]
	v_mfma_f32_16x16x32_bf16 v[18:21], v[176:179], v[212:215], v[18:21]
	v_mfma_f32_16x16x32_bf16 v[22:25], v[176:179], v[216:219], v[22:25]
	v_mfma_f32_16x16x32_bf16 v[26:29], v[176:179], v[220:223], v[26:29]
	v_mfma_f32_16x16x32_bf16 v[30:33], v[176:179], v[224:227], v[30:33]
	v_mfma_f32_16x16x32_bf16 v[34:37], v[180:183], v[212:215], v[34:37]
	v_mfma_f32_16x16x32_bf16 v[38:41], v[180:183], v[216:219], v[38:41]
	v_mfma_f32_16x16x32_bf16 v[42:45], v[180:183], v[220:223], v[42:45]
	v_mfma_f32_16x16x32_bf16 v[46:49], v[180:183], v[224:227], v[46:49]
	v_mfma_f32_16x16x32_bf16 v[50:53], v[184:187], v[212:215], v[50:53]
	v_mfma_f32_16x16x32_bf16 v[54:57], v[184:187], v[216:219], v[54:57]
	v_mfma_f32_16x16x32_bf16 v[58:61], v[184:187], v[220:223], v[58:61]
	v_mfma_f32_16x16x32_bf16 v[62:65], v[184:187], v[224:227], v[62:65]
	s_setprio 0
	s_waitcnt vmcnt(6)
	s_barrier
	s_setprio 3
	v_add_u32_e32 v236, s42, v232
	v_add_u32_e32 v237, s42, v233
	ds_read_b128 v[188:191], v236
	ds_read_b128 v[196:199], v236 offset:2048
	ds_read_b128 v[200:203], v236 offset:4096
	ds_read_b128 v[204:207], v236 offset:6144
	ds_read_b128 v[212:215], v237
	ds_read_b128 v[216:219], v237 offset:2048
	ds_read_b128 v[220:223], v237 offset:4096
	ds_read_b128 v[224:227], v237 offset:6144
	s_add_i32 m0, s51, 0x6000
	s_nop 0
	global_load_lds_dwordx4 v229, s[46:47]
	s_add_i32 m0, s51, 0x6400
	s_nop 0
	global_load_lds_dwordx4 v231, s[46:47]
	s_add_i32 m0, s51, 0x8000
	s_nop 0
	global_load_lds_dwordx4 v228, s[48:49]
	s_add_i32 m0, s51, 0x8400
	s_nop 0
	global_load_lds_dwordx4 v230, s[48:49]
	s_add_i32 m0, s51, 0xa000
	s_nop 0
	global_load_lds_dwordx4 v229, s[48:49]
	s_add_i32 m0, s51, 0xa400
	s_nop 0
	global_load_lds_dwordx4 v231, s[48:49]
	s_waitcnt lgkmcnt(4)
	s_setprio 1
	v_mfma_f32_16x16x32_bf16 v[66:69], v[136:139], v[188:191], v[66:69]
	v_mfma_f32_16x16x32_bf16 v[70:73], v[136:139], v[196:199], v[70:73]
	v_mfma_f32_16x16x32_bf16 v[74:77], v[136:139], v[200:203], v[74:77]
	v_mfma_f32_16x16x32_bf16 v[78:81], v[136:139], v[204:207], v[78:81]
	v_mfma_f32_16x16x32_bf16 v[82:85], v[140:143], v[188:191], v[82:85]
	v_mfma_f32_16x16x32_bf16 v[86:89], v[140:143], v[196:199], v[86:89]
	v_mfma_f32_16x16x32_bf16 v[90:93], v[140:143], v[200:203], v[90:93]
	v_mfma_f32_16x16x32_bf16 v[94:97], v[140:143], v[204:207], v[94:97]
	v_mfma_f32_16x16x32_bf16 v[98:101], v[144:147], v[188:191], v[98:101]
	v_mfma_f32_16x16x32_bf16 v[102:105], v[144:147], v[196:199], v[102:105]
	v_mfma_f32_16x16x32_bf16 v[106:109], v[144:147], v[200:203], v[106:109]
	v_mfma_f32_16x16x32_bf16 v[110:113], v[144:147], v[204:207], v[110:113]
	v_mfma_f32_16x16x32_bf16 v[114:117], v[148:151], v[188:191], v[114:117]
	v_mfma_f32_16x16x32_bf16 v[118:121], v[148:151], v[196:199], v[118:121]
	v_mfma_f32_16x16x32_bf16 v[122:125], v[148:151], v[200:203], v[122:125]
	v_mfma_f32_16x16x32_bf16 v[126:129], v[148:151], v[204:207], v[126:129]
	s_waitcnt lgkmcnt(0)
	v_mfma_f32_16x16x32_bf16 v[66:69], v[172:175], v[212:215], v[66:69]
	v_mfma_f32_16x16x32_bf16 v[70:73], v[172:175], v[216:219], v[70:73]
	v_mfma_f32_16x16x32_bf16 v[74:77], v[172:175], v[220:223], v[74:77]
	v_mfma_f32_16x16x32_bf16 v[78:81], v[172:175], v[224:227], v[78:81]
	v_mfma_f32_16x16x32_bf16 v[82:85], v[176:179], v[212:215], v[82:85]
	v_mfma_f32_16x16x32_bf16 v[86:89], v[176:179], v[216:219], v[86:89]
	v_mfma_f32_16x16x32_bf16 v[90:93], v[176:179], v[220:223], v[90:93]
	v_mfma_f32_16x16x32_bf16 v[94:97], v[176:179], v[224:227], v[94:97]
	v_mfma_f32_16x16x32_bf16 v[98:101], v[180:183], v[212:215], v[98:101]
	v_mfma_f32_16x16x32_bf16 v[102:105], v[180:183], v[216:219], v[102:105]
	v_mfma_f32_16x16x32_bf16 v[106:109], v[180:183], v[220:223], v[106:109]
	v_mfma_f32_16x16x32_bf16 v[110:113], v[180:183], v[224:227], v[110:113]
	v_mfma_f32_16x16x32_bf16 v[114:117], v[184:187], v[212:215], v[114:117]
	v_mfma_f32_16x16x32_bf16 v[118:121], v[184:187], v[216:219], v[118:121]
	v_mfma_f32_16x16x32_bf16 v[122:125], v[184:187], v[220:223], v[122:125]
	v_mfma_f32_16x16x32_bf16 v[126:129], v[184:187], v[224:227], v[126:129]
	s_setprio 0
	v_add_u32_e32 v228, 0x80, v228
	v_add_u32_e32 v229, 0x80, v229
	v_add_u32_e32 v230, 0x80, v230
	v_add_u32_e32 v231, 0x80, v231
	s_waitcnt vmcnt(4)
	s_barrier
	s_add_i32 s52, s52, 1
	s_cmp_lt_u32 s52, 10
	s_cbranch_scc1 .Lgu2_loop
	s_setprio 3
	v_add_u32_e32 v234, s22, v232
	v_add_u32_e32 v236, s28, v232
	v_add_u32_e32 v235, s22, v233
	v_add_u32_e32 v237, s28, v233
	ds_read_b128 v[136:139], v234
	ds_read_b128 v[140:143], v234 offset:2048
	ds_read_b128 v[144:147], v234 offset:4096
	ds_read_b128 v[148:151], v234 offset:6144
	ds_read_b128 v[188:191], v236
	ds_read_b128 v[196:199], v236 offset:2048
	ds_read_b128 v[200:203], v236 offset:4096
	ds_read_b128 v[204:207], v236 offset:6144
	ds_read_b128 v[172:175], v235
	ds_read_b128 v[176:179], v235 offset:2048
	ds_read_b128 v[180:183], v235 offset:4096
	ds_read_b128 v[184:187], v235 offset:6144
	ds_read_b128 v[212:215], v237
	ds_read_b128 v[216:219], v237 offset:2048
	ds_read_b128 v[220:223], v237 offset:4096
	ds_read_b128 v[224:227], v237 offset:6144
	s_add_i32 m0, s51, 0xc000
	s_nop 0
	global_load_lds_dwordx4 v228, s[44:45]
	s_add_i32 m0, s51, 0xc400
	s_nop 0
	global_load_lds_dwordx4 v230, s[44:45]
	s_add_i32 m0, s51, 0xe000
	s_nop 0
	global_load_lds_dwordx4 v229, s[44:45]
	s_add_i32 m0, s51, 0xe400
	s_nop 0
	global_load_lds_dwordx4 v231, s[44:45]
	s_add_i32 m0, s51, 0x10000
	s_nop 0
	global_load_lds_dwordx4 v228, s[46:47]
	s_add_i32 m0, s51, 0x10400
	s_nop 0
	global_load_lds_dwordx4 v230, s[46:47]
	s_waitcnt lgkmcnt(8)
	s_setprio 1
	v_mfma_f32_16x16x32_bf16 v[2:5], v[136:139], v[188:191], v[2:5]
	v_mfma_f32_16x16x32_bf16 v[6:9], v[136:139], v[196:199], v[6:9]
	v_mfma_f32_16x16x32_bf16 v[10:13], v[136:139], v[200:203], v[10:13]
	v_mfma_f32_16x16x32_bf16 v[14:17], v[136:139], v[204:207], v[14:17]
	v_mfma_f32_16x16x32_bf16 v[18:21], v[140:143], v[188:191], v[18:21]
	v_mfma_f32_16x16x32_bf16 v[22:25], v[140:143], v[196:199], v[22:25]
	v_mfma_f32_16x16x32_bf16 v[26:29], v[140:143], v[200:203], v[26:29]
	v_mfma_f32_16x16x32_bf16 v[30:33], v[140:143], v[204:207], v[30:33]
	v_mfma_f32_16x16x32_bf16 v[34:37], v[144:147], v[188:191], v[34:37]
	v_mfma_f32_16x16x32_bf16 v[38:41], v[144:147], v[196:199], v[38:41]
	v_mfma_f32_16x16x32_bf16 v[42:45], v[144:147], v[200:203], v[42:45]
	v_mfma_f32_16x16x32_bf16 v[46:49], v[144:147], v[204:207], v[46:49]
	v_mfma_f32_16x16x32_bf16 v[50:53], v[148:151], v[188:191], v[50:53]
	v_mfma_f32_16x16x32_bf16 v[54:57], v[148:151], v[196:199], v[54:57]
	v_mfma_f32_16x16x32_bf16 v[58:61], v[148:151], v[200:203], v[58:61]
	v_mfma_f32_16x16x32_bf16 v[62:65], v[148:151], v[204:207], v[62:65]
	s_waitcnt lgkmcnt(0)
	v_mfma_f32_16x16x32_bf16 v[2:5], v[172:175], v[212:215], v[2:5]
	v_mfma_f32_16x16x32_bf16 v[6:9], v[172:175], v[216:219], v[6:9]
	v_mfma_f32_16x16x32_bf16 v[10:13], v[172:175], v[220:223], v[10:13]
	v_mfma_f32_16x16x32_bf16 v[14:17], v[172:175], v[224:227], v[14:17]
	v_mfma_f32_16x16x32_bf16 v[18:21], v[176:179], v[212:215], v[18:21]
	v_mfma_f32_16x16x32_bf16 v[22:25], v[176:179], v[216:219], v[22:25]
	v_mfma_f32_16x16x32_bf16 v[26:29], v[176:179], v[220:223], v[26:29]
	v_mfma_f32_16x16x32_bf16 v[30:33], v[176:179], v[224:227], v[30:33]
	v_mfma_f32_16x16x32_bf16 v[34:37], v[180:183], v[212:215], v[34:37]
	v_mfma_f32_16x16x32_bf16 v[38:41], v[180:183], v[216:219], v[38:41]
	v_mfma_f32_16x16x32_bf16 v[42:45], v[180:183], v[220:223], v[42:45]
	v_mfma_f32_16x16x32_bf16 v[46:49], v[180:183], v[224:227], v[46:49]
	v_mfma_f32_16x16x32_bf16 v[50:53], v[184:187], v[212:215], v[50:53]
	v_mfma_f32_16x16x32_bf16 v[54:57], v[184:187], v[216:219], v[54:57]
	v_mfma_f32_16x16x32_bf16 v[58:61], v[184:187], v[220:223], v[58:61]
	v_mfma_f32_16x16x32_bf16 v[62:65], v[184:187], v[224:227], v[62:65]
	s_setprio 0
	s_waitcnt vmcnt(6)
	s_barrier
	s_setprio 3
	v_add_u32_e32 v236, s40, v232
	v_add_u32_e32 v237, s40, v233
	ds_read_b128 v[188:191], v236
	ds_read_b128 v[196:199], v236 offset:2048
	ds_read_b128 v[200:203], v236 offset:4096
	ds_read_b128 v[204:207], v236 offset:6144
	ds_read_b128 v[212:215], v237
	ds_read_b128 v[216:219], v237 offset:2048
	ds_read_b128 v[220:223], v237 offset:4096
	ds_read_b128 v[224:227], v237 offset:6144
	s_mov_b32 m0, s51
	s_nop 0
	global_load_lds_dwordx4 v229, s[46:47]
	s_add_i32 m0, s51, 0x400
	s_nop 0
	global_load_lds_dwordx4 v231, s[46:47]
	s_add_i32 m0, s51, 0x2000
	s_nop 0
	global_load_lds_dwordx4 v228, s[48:49]
	s_add_i32 m0, s51, 0x2400
	s_nop 0
	global_load_lds_dwordx4 v230, s[48:49]
	s_add_i32 m0, s51, 0x4000
	s_nop 0
	global_load_lds_dwordx4 v229, s[48:49]
	s_add_i32 m0, s51, 0x4400
	s_nop 0
	global_load_lds_dwordx4 v231, s[48:49]
	s_waitcnt lgkmcnt(4)
	s_setprio 1
	v_mfma_f32_16x16x32_bf16 v[66:69], v[136:139], v[188:191], v[66:69]
	v_mfma_f32_16x16x32_bf16 v[70:73], v[136:139], v[196:199], v[70:73]
	v_mfma_f32_16x16x32_bf16 v[74:77], v[136:139], v[200:203], v[74:77]
	v_mfma_f32_16x16x32_bf16 v[78:81], v[136:139], v[204:207], v[78:81]
	v_mfma_f32_16x16x32_bf16 v[82:85], v[140:143], v[188:191], v[82:85]
	v_mfma_f32_16x16x32_bf16 v[86:89], v[140:143], v[196:199], v[86:89]
	v_mfma_f32_16x16x32_bf16 v[90:93], v[140:143], v[200:203], v[90:93]
	v_mfma_f32_16x16x32_bf16 v[94:97], v[140:143], v[204:207], v[94:97]
	v_mfma_f32_16x16x32_bf16 v[98:101], v[144:147], v[188:191], v[98:101]
	v_mfma_f32_16x16x32_bf16 v[102:105], v[144:147], v[196:199], v[102:105]
	v_mfma_f32_16x16x32_bf16 v[106:109], v[144:147], v[200:203], v[106:109]
	v_mfma_f32_16x16x32_bf16 v[110:113], v[144:147], v[204:207], v[110:113]
	v_mfma_f32_16x16x32_bf16 v[114:117], v[148:151], v[188:191], v[114:117]
	v_mfma_f32_16x16x32_bf16 v[118:121], v[148:151], v[196:199], v[118:121]
	v_mfma_f32_16x16x32_bf16 v[122:125], v[148:151], v[200:203], v[122:125]
	v_mfma_f32_16x16x32_bf16 v[126:129], v[148:151], v[204:207], v[126:129]
	s_waitcnt lgkmcnt(0)
	v_mfma_f32_16x16x32_bf16 v[66:69], v[172:175], v[212:215], v[66:69]
	v_mfma_f32_16x16x32_bf16 v[70:73], v[172:175], v[216:219], v[70:73]
	v_mfma_f32_16x16x32_bf16 v[74:77], v[172:175], v[220:223], v[74:77]
	v_mfma_f32_16x16x32_bf16 v[78:81], v[172:175], v[224:227], v[78:81]
	v_mfma_f32_16x16x32_bf16 v[82:85], v[176:179], v[212:215], v[82:85]
	v_mfma_f32_16x16x32_bf16 v[86:89], v[176:179], v[216:219], v[86:89]
	v_mfma_f32_16x16x32_bf16 v[90:93], v[176:179], v[220:223], v[90:93]
	v_mfma_f32_16x16x32_bf16 v[94:97], v[176:179], v[224:227], v[94:97]
	v_mfma_f32_16x16x32_bf16 v[98:101], v[180:183], v[212:215], v[98:101]
	v_mfma_f32_16x16x32_bf16 v[102:105], v[180:183], v[216:219], v[102:105]
	v_mfma_f32_16x16x32_bf16 v[106:109], v[180:183], v[220:223], v[106:109]
	v_mfma_f32_16x16x32_bf16 v[110:113], v[180:183], v[224:227], v[110:113]
	v_mfma_f32_16x16x32_bf16 v[114:117], v[184:187], v[212:215], v[114:117]
	v_mfma_f32_16x16x32_bf16 v[118:121], v[184:187], v[216:219], v[118:121]
	v_mfma_f32_16x16x32_bf16 v[122:125], v[184:187], v[220:223], v[122:125]
	v_mfma_f32_16x16x32_bf16 v[126:129], v[184:187], v[224:227], v[126:129]
	s_setprio 0
	v_add_u32_e32 v228, 0x80, v228
	v_add_u32_e32 v229, 0x80, v229
	v_add_u32_e32 v230, 0x80, v230
	v_add_u32_e32 v231, 0x80, v231
	s_waitcnt vmcnt(4)
	s_barrier
	s_setprio 3
	v_add_u32_e32 v234, s23, v232
	v_add_u32_e32 v236, s29, v232
	v_add_u32_e32 v235, s23, v233
	v_add_u32_e32 v237, s29, v233
	ds_read_b128 v[136:139], v234
	ds_read_b128 v[140:143], v234 offset:2048
	ds_read_b128 v[144:147], v234 offset:4096
	ds_read_b128 v[148:151], v234 offset:6144
	ds_read_b128 v[188:191], v236
	ds_read_b128 v[196:199], v236 offset:2048
	ds_read_b128 v[200:203], v236 offset:4096
	ds_read_b128 v[204:207], v236 offset:6144
	ds_read_b128 v[172:175], v235
	ds_read_b128 v[176:179], v235 offset:2048
	ds_read_b128 v[180:183], v235 offset:4096
	ds_read_b128 v[184:187], v235 offset:6144
	ds_read_b128 v[212:215], v237
	ds_read_b128 v[216:219], v237 offset:2048
	ds_read_b128 v[220:223], v237 offset:4096
	ds_read_b128 v[224:227], v237 offset:6144
	s_waitcnt lgkmcnt(8)
	s_setprio 1
	v_mfma_f32_16x16x32_bf16 v[2:5], v[136:139], v[188:191], v[2:5]
	v_mfma_f32_16x16x32_bf16 v[6:9], v[136:139], v[196:199], v[6:9]
	v_mfma_f32_16x16x32_bf16 v[10:13], v[136:139], v[200:203], v[10:13]
	v_mfma_f32_16x16x32_bf16 v[14:17], v[136:139], v[204:207], v[14:17]
	v_mfma_f32_16x16x32_bf16 v[18:21], v[140:143], v[188:191], v[18:21]
	v_mfma_f32_16x16x32_bf16 v[22:25], v[140:143], v[196:199], v[22:25]
	v_mfma_f32_16x16x32_bf16 v[26:29], v[140:143], v[200:203], v[26:29]
	v_mfma_f32_16x16x32_bf16 v[30:33], v[140:143], v[204:207], v[30:33]
	v_mfma_f32_16x16x32_bf16 v[34:37], v[144:147], v[188:191], v[34:37]
	v_mfma_f32_16x16x32_bf16 v[38:41], v[144:147], v[196:199], v[38:41]
	v_mfma_f32_16x16x32_bf16 v[42:45], v[144:147], v[200:203], v[42:45]
	v_mfma_f32_16x16x32_bf16 v[46:49], v[144:147], v[204:207], v[46:49]
	v_mfma_f32_16x16x32_bf16 v[50:53], v[148:151], v[188:191], v[50:53]
	v_mfma_f32_16x16x32_bf16 v[54:57], v[148:151], v[196:199], v[54:57]
	v_mfma_f32_16x16x32_bf16 v[58:61], v[148:151], v[200:203], v[58:61]
	v_mfma_f32_16x16x32_bf16 v[62:65], v[148:151], v[204:207], v[62:65]
	s_waitcnt lgkmcnt(0)
	v_mfma_f32_16x16x32_bf16 v[2:5], v[172:175], v[212:215], v[2:5]
	v_mfma_f32_16x16x32_bf16 v[6:9], v[172:175], v[216:219], v[6:9]
	v_mfma_f32_16x16x32_bf16 v[10:13], v[172:175], v[220:223], v[10:13]
	v_mfma_f32_16x16x32_bf16 v[14:17], v[172:175], v[224:227], v[14:17]
	v_mfma_f32_16x16x32_bf16 v[18:21], v[176:179], v[212:215], v[18:21]
	v_mfma_f32_16x16x32_bf16 v[22:25], v[176:179], v[216:219], v[22:25]
	v_mfma_f32_16x16x32_bf16 v[26:29], v[176:179], v[220:223], v[26:29]
	v_mfma_f32_16x16x32_bf16 v[30:33], v[176:179], v[224:227], v[30:33]
	v_mfma_f32_16x16x32_bf16 v[34:37], v[180:183], v[212:215], v[34:37]
	v_mfma_f32_16x16x32_bf16 v[38:41], v[180:183], v[216:219], v[38:41]
	v_mfma_f32_16x16x32_bf16 v[42:45], v[180:183], v[220:223], v[42:45]
	v_mfma_f32_16x16x32_bf16 v[46:49], v[180:183], v[224:227], v[46:49]
	v_mfma_f32_16x16x32_bf16 v[50:53], v[184:187], v[212:215], v[50:53]
	v_mfma_f32_16x16x32_bf16 v[54:57], v[184:187], v[216:219], v[54:57]
	v_mfma_f32_16x16x32_bf16 v[58:61], v[184:187], v[220:223], v[58:61]
	v_mfma_f32_16x16x32_bf16 v[62:65], v[184:187], v[224:227], v[62:65]
	s_setprio 0
	s_waitcnt vmcnt(0)
	s_barrier
	s_setprio 3
	v_add_u32_e32 v236, s41, v232
	v_add_u32_e32 v237, s41, v233
	ds_read_b128 v[188:191], v236
	ds_read_b128 v[196:199], v236 offset:2048
	ds_read_b128 v[200:203], v236 offset:4096
	ds_read_b128 v[204:207], v236 offset:6144
	ds_read_b128 v[212:215], v237
	ds_read_b128 v[216:219], v237 offset:2048
	ds_read_b128 v[220:223], v237 offset:4096
	ds_read_b128 v[224:227], v237 offset:6144
	s_waitcnt lgkmcnt(4)
	s_setprio 1
	v_mfma_f32_16x16x32_bf16 v[66:69], v[136:139], v[188:191], v[66:69]
	v_mfma_f32_16x16x32_bf16 v[70:73], v[136:139], v[196:199], v[70:73]
	v_mfma_f32_16x16x32_bf16 v[74:77], v[136:139], v[200:203], v[74:77]
	v_mfma_f32_16x16x32_bf16 v[78:81], v[136:139], v[204:207], v[78:81]
	v_mfma_f32_16x16x32_bf16 v[82:85], v[140:143], v[188:191], v[82:85]
	v_mfma_f32_16x16x32_bf16 v[86:89], v[140:143], v[196:199], v[86:89]
	v_mfma_f32_16x16x32_bf16 v[90:93], v[140:143], v[200:203], v[90:93]
	v_mfma_f32_16x16x32_bf16 v[94:97], v[140:143], v[204:207], v[94:97]
	v_mfma_f32_16x16x32_bf16 v[98:101], v[144:147], v[188:191], v[98:101]
	v_mfma_f32_16x16x32_bf16 v[102:105], v[144:147], v[196:199], v[102:105]
	v_mfma_f32_16x16x32_bf16 v[106:109], v[144:147], v[200:203], v[106:109]
	v_mfma_f32_16x16x32_bf16 v[110:113], v[144:147], v[204:207], v[110:113]
	v_mfma_f32_16x16x32_bf16 v[114:117], v[148:151], v[188:191], v[114:117]
	v_mfma_f32_16x16x32_bf16 v[118:121], v[148:151], v[196:199], v[118:121]
	v_mfma_f32_16x16x32_bf16 v[122:125], v[148:151], v[200:203], v[122:125]
	v_mfma_f32_16x16x32_bf16 v[126:129], v[148:151], v[204:207], v[126:129]
	s_waitcnt lgkmcnt(0)
	v_mfma_f32_16x16x32_bf16 v[66:69], v[172:175], v[212:215], v[66:69]
	v_mfma_f32_16x16x32_bf16 v[70:73], v[172:175], v[216:219], v[70:73]
	v_mfma_f32_16x16x32_bf16 v[74:77], v[172:175], v[220:223], v[74:77]
	v_mfma_f32_16x16x32_bf16 v[78:81], v[172:175], v[224:227], v[78:81]
	v_mfma_f32_16x16x32_bf16 v[82:85], v[176:179], v[212:215], v[82:85]
	v_mfma_f32_16x16x32_bf16 v[86:89], v[176:179], v[216:219], v[86:89]
	v_mfma_f32_16x16x32_bf16 v[90:93], v[176:179], v[220:223], v[90:93]
	v_mfma_f32_16x16x32_bf16 v[94:97], v[176:179], v[224:227], v[94:97]
	v_mfma_f32_16x16x32_bf16 v[98:101], v[180:183], v[212:215], v[98:101]
	v_mfma_f32_16x16x32_bf16 v[102:105], v[180:183], v[216:219], v[102:105]
	v_mfma_f32_16x16x32_bf16 v[106:109], v[180:183], v[220:223], v[106:109]
	v_mfma_f32_16x16x32_bf16 v[110:113], v[180:183], v[224:227], v[110:113]
	v_mfma_f32_16x16x32_bf16 v[114:117], v[184:187], v[212:215], v[114:117]
	v_mfma_f32_16x16x32_bf16 v[118:121], v[184:187], v[216:219], v[118:121]
	v_mfma_f32_16x16x32_bf16 v[122:125], v[184:187], v[220:223], v[122:125]
	v_mfma_f32_16x16x32_bf16 v[126:129], v[184:187], v[224:227], v[126:129]
	s_setprio 0
	s_nop 7
	s_barrier
	s_mul_i32 s43, s53, 0x2c80
	s_add_i32 s43, s43, s54
	s_add_i32 s55, s55, 1
	s_cmp_lt_u32 s55, 5
	s_cbranch_scc0 .Lgu2_nonext
	s_load_dwordx2 s[44:45], s[12:13], 0x160
	s_load_dwordx2 s[46:47], s[12:13], 0x130
	s_bfe_u32 s53, s21, 0x30006
	s_lshl_b32 s53, s53, 3
	s_and_b32 s56, s21, 7
	s_or_b32 s53, s53, s56
	s_lshl_b32 s53, s53, 7
	s_bfe_u32 s54, s21, 0x30003
	s_lshl_b32 s56, s55, 4
	s_add_i32 s54, s54, s56
	s_lshl_b32 s54, s54, 7
	v_lshrrev_b32_e32 v196, 6, v131
	v_and_b32_e32 v197, 63, v131
	s_nop 0
	v_readfirstlane_b32 s50, v196
	v_lshrrev_b32_e32 v196, 3, v197
	v_lshrrev_b32_e32 v198, 4, v197
	v_and_b32_e32 v199, 7, v197
	s_movk_i32 s56, 0x1080
	v_xor_b32_e32 v200, v199, v198
	v_lshlrev_b32_e32 v200, 4, v200
	v_mad_u32_u24 v228, v196, s56, v200
	v_or_b32_e32 v198, 4, v198
	v_xor_b32_e32 v200, v199, v198
	v_lshlrev_b32_e32 v200, 4, v200
	v_add_u32_e32 v196, 8, v196
	v_mad_u32_u24 v230, v196, s56, v200
	v_add_u32_e32 v229, 0x42000, v228
	v_add_u32_e32 v231, 0x42000, v230
	v_and_b32_e32 v196, 15, v197
	v_lshrrev_b32_e32 v198, 4, v197
	v_bfe_u32 v199, v197, 1, 3
	v_xor_b32_e32 v199, v198, v199
	v_lshlrev_b32_e32 v199, 4, v199
	v_lshl_or_b32 v232, v196, 7, v199
	v_xor_b32_e32 v233, 64, v232
	s_lshr_b32 s56, s50, 1
	s_and_b32 s57, s50, 1
	s_mul_i32 s0, s56, 64*528
	s_lshl_b32 s52, s57, 8
	s_add_i32 s0, s0, s52
	s_add_i32 s0, s0, 16
	v_mul_u32_u24_e32 v198, 4*528, v198
	v_lshl_add_u32 v198, v196, 2, v198
	v_add_u32_e32 v238, s0, v198
	s_add_i32 s22, s56, 0
	s_lshl_b32 s22, s22, 13
	s_add_i32 s22, s22, 16
	s_add_i32 s28, s57, 2
	s_lshl_b32 s28, s28, 13
	s_add_i32 s28, s28, 16
	s_add_i32 s40, s57, 4
	s_lshl_b32 s40, s40, 13
	s_add_i32 s40, s40, 16
	s_add_i32 s23, s56, 6
	s_lshl_b32 s23, s23, 13
	s_add_i32 s23, s23, 16
	s_add_i32 s29, s57, 8
	s_cmp_ge_u32 s29, 9
	s_cselect_b32 s0, 9, 0
	s_sub_i32 s29, s29, s0
	s_lshl_b32 s29, s29, 13
	s_add_i32 s29, s29, 16
	s_add_i32 s41, s57, 1
	s_lshl_b32 s41, s41, 13
	s_add_i32 s41, s41, 16
	s_add_i32 s24, s56, 3
	s_lshl_b32 s24, s24, 13
	s_add_i32 s24, s24, 16
	s_add_i32 s30, s57, 5
	s_lshl_b32 s30, s30, 13
	s_add_i32 s30, s30, 16
	s_add_i32 s42, s57, 7
	s_lshl_b32 s42, s42, 13
	s_add_i32 s42, s42, 16
	s_lshl_b32 s56, s50, 4
	s_add_i32 s57, s53, s56
	s_add_i32 s56, s54, s56
	s_mul_i32 s57, s57, 0x1080
	s_mul_i32 s56, s56, 0x1080
	s_waitcnt lgkmcnt(0)
	s_add_u32 s44, s44, s57
	s_addc_u32 s45, s45, 0
	s_add_u32 s46, s46, s56
	s_addc_u32 s47, s47, 0
	s_add_u32 s48, s46, 0x420000
	s_addc_u32 s49, s47, 0
	s_lshl_b32 s51, s50, 11
	s_add_i32 s51, s51, 16
	s_mov_b32 m0, s51
	s_nop 0
	global_load_lds_dwordx4 v228, s[44:45]
	s_add_i32 m0, s51, 0x400
	s_nop 0
	global_load_lds_dwordx4 v230, s[44:45]
	s_add_i32 m0, s51, 0x2000
	s_nop 0
	global_load_lds_dwordx4 v229, s[44:45]
	s_add_i32 m0, s51, 0x2400
	s_nop 0
	global_load_lds_dwordx4 v231, s[44:45]
	s_add_i32 m0, s51, 0x4000
	s_nop 0
	global_load_lds_dwordx4 v228, s[46:47]
	s_add_i32 m0, s51, 0x4400
	s_nop 0
	global_load_lds_dwordx4 v230, s[46:47]
	s_add_i32 m0, s51, 0x6000
	s_nop 0
	global_load_lds_dwordx4 v229, s[46:47]
	s_add_i32 m0, s51, 0x6400
	s_nop 0
	global_load_lds_dwordx4 v231, s[46:47]
	s_add_i32 m0, s51, 0x8000
	s_nop 0
	global_load_lds_dwordx4 v228, s[48:49]
	s_add_i32 m0, s51, 0x8400
	s_nop 0
	global_load_lds_dwordx4 v230, s[48:49]
	s_add_i32 m0, s51, 0xa000
	s_nop 0
	global_load_lds_dwordx4 v229, s[48:49]
	s_add_i32 m0, s51, 0xa400
	s_nop 0
	global_load_lds_dwordx4 v231, s[48:49]
	v_add_u32_e32 v228, 0x80, v228
	v_add_u32_e32 v229, 0x80, v229
	v_add_u32_e32 v230, 0x80, v230
	v_add_u32_e32 v231, 0x80, v231
.Lgu2_nonext:
	s_load_dwordx2 s[58:59], s[12:13], 0x180
	v_mov_b32_e32 v241, 0x3a000000
	v_mov_b32_e32 v242, 0x358637bd
	v_fma_f32 v152, v152, v241, v242
	v_fma_f32 v153, v153, v241, v242
	v_fma_f32 v154, v154, v241, v242
	v_fma_f32 v155, v155, v241, v242
	v_fma_f32 v244, v244, v241, v242
	v_fma_f32 v245, v245, v241, v242
	v_fma_f32 v246, v246, v241, v242
	v_fma_f32 v247, v247, v241, v242
	v_fma_f32 v248, v248, v241, v242
	v_fma_f32 v249, v249, v241, v242
	v_fma_f32 v250, v250, v241, v242
	v_fma_f32 v251, v251, v241, v242
	v_fma_f32 v252, v252, v241, v242
	v_fma_f32 v253, v253, v241, v242
	v_fma_f32 v254, v254, v241, v242
	v_fma_f32 v255, v255, v241, v242
	v_rsq_f32_e32 v152, v152
	v_rsq_f32_e32 v153, v153
	v_rsq_f32_e32 v154, v154
	v_rsq_f32_e32 v155, v155
	v_rsq_f32_e32 v244, v244
	v_rsq_f32_e32 v245, v245
	v_rsq_f32_e32 v246, v246
	v_rsq_f32_e32 v247, v247
	v_rsq_f32_e32 v248, v248
	v_rsq_f32_e32 v249, v249
	v_rsq_f32_e32 v250, v250
	v_rsq_f32_e32 v251, v251
	v_rsq_f32_e32 v252, v252
	v_rsq_f32_e32 v253, v253
	v_rsq_f32_e32 v254, v254
	v_rsq_f32_e32 v255, v255
	v_and_b32_e32 v241, 63, v131
	v_lshrrev_b32_e32 v242, 4, v241
	v_and_b32_e32 v241, 15, v241
	s_lshr_b32 s56, s50, 1
	s_and_b32 s57, s50, 1
	s_mul_i32 s56, s56, 64*144
	s_lshl_b32 s57, s57, 6
	s_add_i32 s56, s56, s57
	s_add_i32 s56, s56, 49168
	v_mul_u32_u24_e32 v242, 4*144, v242
	v_lshl_add_u32 v242, v241, 1, v242
	v_add_u32_e32 v188, s56, v242
	v_lshrrev_b32_e32 v241, 3, v131
	v_and_b32_e32 v242, 7, v131
	v_lshlrev_b32_e32 v242, 4, v242
	v_mul_u32_u24_e32 v189, 144, v241
	s_mov_b32 s57, 0xc010
	v_add3_u32 v189, v189, v242, s57
	s_movk_i32 s56, 0x2c80
	v_mad_u32_u24 v243, v241, s56, v242
	s_mov_b32 s56, s43
	s_waitcnt lgkmcnt(0)
	s_add_u32 s58, s58, s56
	s_addc_u32 s59, s59, 0
	v_mul_f32_e32 v2, v2, v152
	v_mul_f32_e32 v6, v6, v152
	v_mul_f32_e32 v10, v10, v152
	v_mul_f32_e32 v14, v14, v152
	v_mul_f32_e32 v136, 0xbfb8aa3b, v2
	v_mul_f32_e32 v137, 0xbfb8aa3b, v6
	v_exp_f32_e32 v136, v136
	v_exp_f32_e32 v137, v137
	v_mul_f32_e32 v10, v10, v2
	v_mul_f32_e32 v14, v14, v6
	v_add_f32_e32 v136, 1.0, v136
	v_add_f32_e32 v137, 1.0, v137
	v_rcp_f32_e32 v136, v136
	v_rcp_f32_e32 v137, v137
	s_nop 0
	v_mul_f32_e32 v10, v10, v136
	v_mul_f32_e32 v14, v14, v137
	v_cvt_pk_bf16_f32 v10, v10, v14
	ds_write_b16 v188, v10
	ds_write_b16_d16_hi v188, v10 offset:32
	v_mul_f32_e32 v3, v3, v153
	v_mul_f32_e32 v7, v7, v153
	v_mul_f32_e32 v11, v11, v153
	v_mul_f32_e32 v15, v15, v153
	v_mul_f32_e32 v136, 0xbfb8aa3b, v3
	v_mul_f32_e32 v137, 0xbfb8aa3b, v7
	v_exp_f32_e32 v136, v136
	v_exp_f32_e32 v137, v137
	v_mul_f32_e32 v11, v11, v3
	v_mul_f32_e32 v15, v15, v7
	v_add_f32_e32 v136, 1.0, v136
	v_add_f32_e32 v137, 1.0, v137
	v_rcp_f32_e32 v136, v136
	v_rcp_f32_e32 v137, v137
	s_nop 0
	v_mul_f32_e32 v11, v11, v136
	v_mul_f32_e32 v15, v15, v137
	v_cvt_pk_bf16_f32 v11, v11, v15
	ds_write_b16 v188, v11 offset:144
	ds_write_b16_d16_hi v188, v11 offset:176
	v_mul_f32_e32 v4, v4, v154
	v_mul_f32_e32 v8, v8, v154
	v_mul_f32_e32 v12, v12, v154
	v_mul_f32_e32 v16, v16, v154
	v_mul_f32_e32 v136, 0xbfb8aa3b, v4
	v_mul_f32_e32 v137, 0xbfb8aa3b, v8
	v_exp_f32_e32 v136, v136
	v_exp_f32_e32 v137, v137
	v_mul_f32_e32 v12, v12, v4
	v_mul_f32_e32 v16, v16, v8
	v_add_f32_e32 v136, 1.0, v136
	v_add_f32_e32 v137, 1.0, v137
	v_rcp_f32_e32 v136, v136
	v_rcp_f32_e32 v137, v137
	s_nop 0
	v_mul_f32_e32 v12, v12, v136
	v_mul_f32_e32 v16, v16, v137
	v_cvt_pk_bf16_f32 v12, v12, v16
	ds_write_b16 v188, v12 offset:288
	ds_write_b16_d16_hi v188, v12 offset:320
	v_mul_f32_e32 v5, v5, v155
	v_mul_f32_e32 v9, v9, v155
	v_mul_f32_e32 v13, v13, v155
	v_mul_f32_e32 v17, v17, v155
	v_mul_f32_e32 v136, 0xbfb8aa3b, v5
	v_mul_f32_e32 v137, 0xbfb8aa3b, v9
	v_exp_f32_e32 v136, v136
	v_exp_f32_e32 v137, v137
	v_mul_f32_e32 v13, v13, v5
	v_mul_f32_e32 v17, v17, v9
	v_add_f32_e32 v136, 1.0, v136
	v_add_f32_e32 v137, 1.0, v137
	v_rcp_f32_e32 v136, v136
	v_rcp_f32_e32 v137, v137
	s_nop 0
	v_mul_f32_e32 v13, v13, v136
	v_mul_f32_e32 v17, v17, v137
	v_cvt_pk_bf16_f32 v13, v13, v17
	ds_write_b16 v188, v13 offset:432
	ds_write_b16_d16_hi v188, v13 offset:464
	v_mul_f32_e32 v18, v18, v244
	v_mul_f32_e32 v22, v22, v244
	v_mul_f32_e32 v26, v26, v244
	v_mul_f32_e32 v30, v30, v244
	v_mul_f32_e32 v136, 0xbfb8aa3b, v18
	v_mul_f32_e32 v137, 0xbfb8aa3b, v22
	v_exp_f32_e32 v136, v136
	v_exp_f32_e32 v137, v137
	v_mul_f32_e32 v26, v26, v18
	v_mul_f32_e32 v30, v30, v22
	v_add_f32_e32 v136, 1.0, v136
	v_add_f32_e32 v137, 1.0, v137
	v_rcp_f32_e32 v136, v136
	v_rcp_f32_e32 v137, v137
	s_nop 0
	v_mul_f32_e32 v26, v26, v136
	v_mul_f32_e32 v30, v30, v137
	v_cvt_pk_bf16_f32 v26, v26, v30
	ds_write_b16 v188, v26 offset:2304
	ds_write_b16_d16_hi v188, v26 offset:2336
	v_mul_f32_e32 v19, v19, v245
	v_mul_f32_e32 v23, v23, v245
	v_mul_f32_e32 v27, v27, v245
	v_mul_f32_e32 v31, v31, v245
	v_mul_f32_e32 v136, 0xbfb8aa3b, v19
	v_mul_f32_e32 v137, 0xbfb8aa3b, v23
	v_exp_f32_e32 v136, v136
	v_exp_f32_e32 v137, v137
	v_mul_f32_e32 v27, v27, v19
	v_mul_f32_e32 v31, v31, v23
	v_add_f32_e32 v136, 1.0, v136
	v_add_f32_e32 v137, 1.0, v137
	v_rcp_f32_e32 v136, v136
	v_rcp_f32_e32 v137, v137
	s_nop 0
	v_mul_f32_e32 v27, v27, v136
	v_mul_f32_e32 v31, v31, v137
	v_cvt_pk_bf16_f32 v27, v27, v31
	ds_write_b16 v188, v27 offset:2448
	ds_write_b16_d16_hi v188, v27 offset:2480
	v_mul_f32_e32 v20, v20, v246
	v_mul_f32_e32 v24, v24, v246
	v_mul_f32_e32 v28, v28, v246
	v_mul_f32_e32 v32, v32, v246
	v_mul_f32_e32 v136, 0xbfb8aa3b, v20
	v_mul_f32_e32 v137, 0xbfb8aa3b, v24
	v_exp_f32_e32 v136, v136
	v_exp_f32_e32 v137, v137
	v_mul_f32_e32 v28, v28, v20
	v_mul_f32_e32 v32, v32, v24
	v_add_f32_e32 v136, 1.0, v136
	v_add_f32_e32 v137, 1.0, v137
	v_rcp_f32_e32 v136, v136
	v_rcp_f32_e32 v137, v137
	s_nop 0
	v_mul_f32_e32 v28, v28, v136
	v_mul_f32_e32 v32, v32, v137
	v_cvt_pk_bf16_f32 v28, v28, v32
	ds_write_b16 v188, v28 offset:2592
	ds_write_b16_d16_hi v188, v28 offset:2624
	v_mul_f32_e32 v21, v21, v247
	v_mul_f32_e32 v25, v25, v247
	v_mul_f32_e32 v29, v29, v247
	v_mul_f32_e32 v33, v33, v247
	v_mul_f32_e32 v136, 0xbfb8aa3b, v21
	v_mul_f32_e32 v137, 0xbfb8aa3b, v25
	v_exp_f32_e32 v136, v136
	v_exp_f32_e32 v137, v137
	v_mul_f32_e32 v29, v29, v21
	v_mul_f32_e32 v33, v33, v25
	v_add_f32_e32 v136, 1.0, v136
	v_add_f32_e32 v137, 1.0, v137
	v_rcp_f32_e32 v136, v136
	v_rcp_f32_e32 v137, v137
	s_nop 0
	v_mul_f32_e32 v29, v29, v136
	v_mul_f32_e32 v33, v33, v137
	v_cvt_pk_bf16_f32 v29, v29, v33
	ds_write_b16 v188, v29 offset:2736
	ds_write_b16_d16_hi v188, v29 offset:2768
	v_mul_f32_e32 v34, v34, v248
	v_mul_f32_e32 v38, v38, v248
	v_mul_f32_e32 v42, v42, v248
	v_mul_f32_e32 v46, v46, v248
	v_mul_f32_e32 v136, 0xbfb8aa3b, v34
	v_mul_f32_e32 v137, 0xbfb8aa3b, v38
	v_exp_f32_e32 v136, v136
	v_exp_f32_e32 v137, v137
	v_mul_f32_e32 v42, v42, v34
	v_mul_f32_e32 v46, v46, v38
	v_add_f32_e32 v136, 1.0, v136
	v_add_f32_e32 v137, 1.0, v137
	v_rcp_f32_e32 v136, v136
	v_rcp_f32_e32 v137, v137
	s_nop 0
	v_mul_f32_e32 v42, v42, v136
	v_mul_f32_e32 v46, v46, v137
	v_cvt_pk_bf16_f32 v42, v42, v46
	ds_write_b16 v188, v42 offset:4608
	ds_write_b16_d16_hi v188, v42 offset:4640
	v_mul_f32_e32 v35, v35, v249
	v_mul_f32_e32 v39, v39, v249
	v_mul_f32_e32 v43, v43, v249
	v_mul_f32_e32 v47, v47, v249
	v_mul_f32_e32 v136, 0xbfb8aa3b, v35
	v_mul_f32_e32 v137, 0xbfb8aa3b, v39
	v_exp_f32_e32 v136, v136
	v_exp_f32_e32 v137, v137
	v_mul_f32_e32 v43, v43, v35
	v_mul_f32_e32 v47, v47, v39
	v_add_f32_e32 v136, 1.0, v136
	v_add_f32_e32 v137, 1.0, v137
	v_rcp_f32_e32 v136, v136
	v_rcp_f32_e32 v137, v137
	s_nop 0
	v_mul_f32_e32 v43, v43, v136
	v_mul_f32_e32 v47, v47, v137
	v_cvt_pk_bf16_f32 v43, v43, v47
	ds_write_b16 v188, v43 offset:4752
	ds_write_b16_d16_hi v188, v43 offset:4784
	v_mul_f32_e32 v36, v36, v250
	v_mul_f32_e32 v40, v40, v250
	v_mul_f32_e32 v44, v44, v250
	v_mul_f32_e32 v48, v48, v250
	v_mul_f32_e32 v136, 0xbfb8aa3b, v36
	v_mul_f32_e32 v137, 0xbfb8aa3b, v40
	v_exp_f32_e32 v136, v136
	v_exp_f32_e32 v137, v137
	v_mul_f32_e32 v44, v44, v36
	v_mul_f32_e32 v48, v48, v40
	v_add_f32_e32 v136, 1.0, v136
	v_add_f32_e32 v137, 1.0, v137
	v_rcp_f32_e32 v136, v136
	v_rcp_f32_e32 v137, v137
	s_nop 0
	v_mul_f32_e32 v44, v44, v136
	v_mul_f32_e32 v48, v48, v137
	v_cvt_pk_bf16_f32 v44, v44, v48
	ds_write_b16 v188, v44 offset:4896
	ds_write_b16_d16_hi v188, v44 offset:4928
	v_mul_f32_e32 v37, v37, v251
	v_mul_f32_e32 v41, v41, v251
	v_mul_f32_e32 v45, v45, v251
	v_mul_f32_e32 v49, v49, v251
	v_mul_f32_e32 v136, 0xbfb8aa3b, v37
	v_mul_f32_e32 v137, 0xbfb8aa3b, v41
	v_exp_f32_e32 v136, v136
	v_exp_f32_e32 v137, v137
	v_mul_f32_e32 v45, v45, v37
	v_mul_f32_e32 v49, v49, v41
	v_add_f32_e32 v136, 1.0, v136
	v_add_f32_e32 v137, 1.0, v137
	v_rcp_f32_e32 v136, v136
	v_rcp_f32_e32 v137, v137
	s_nop 0
	v_mul_f32_e32 v45, v45, v136
	v_mul_f32_e32 v49, v49, v137
	v_cvt_pk_bf16_f32 v45, v45, v49
	ds_write_b16 v188, v45 offset:5040
	ds_write_b16_d16_hi v188, v45 offset:5072
	v_mul_f32_e32 v50, v50, v252
	v_mul_f32_e32 v54, v54, v252
	v_mul_f32_e32 v58, v58, v252
	v_mul_f32_e32 v62, v62, v252
	v_mul_f32_e32 v136, 0xbfb8aa3b, v50
	v_mul_f32_e32 v137, 0xbfb8aa3b, v54
	v_exp_f32_e32 v136, v136
	v_exp_f32_e32 v137, v137
	v_mul_f32_e32 v58, v58, v50
	v_mul_f32_e32 v62, v62, v54
	v_add_f32_e32 v136, 1.0, v136
	v_add_f32_e32 v137, 1.0, v137
	v_rcp_f32_e32 v136, v136
	v_rcp_f32_e32 v137, v137
	s_nop 0
	v_mul_f32_e32 v58, v58, v136
	v_mul_f32_e32 v62, v62, v137
	v_cvt_pk_bf16_f32 v58, v58, v62
	ds_write_b16 v188, v58 offset:6912
	ds_write_b16_d16_hi v188, v58 offset:6944
	v_mul_f32_e32 v51, v51, v253
	v_mul_f32_e32 v55, v55, v253
	v_mul_f32_e32 v59, v59, v253
	v_mul_f32_e32 v63, v63, v253
	v_mul_f32_e32 v136, 0xbfb8aa3b, v51
	v_mul_f32_e32 v137, 0xbfb8aa3b, v55
	v_exp_f32_e32 v136, v136
	v_exp_f32_e32 v137, v137
	v_mul_f32_e32 v59, v59, v51
	v_mul_f32_e32 v63, v63, v55
	v_add_f32_e32 v136, 1.0, v136
	v_add_f32_e32 v137, 1.0, v137
	v_rcp_f32_e32 v136, v136
	v_rcp_f32_e32 v137, v137
	s_nop 0
	v_mul_f32_e32 v59, v59, v136
	v_mul_f32_e32 v63, v63, v137
	v_cvt_pk_bf16_f32 v59, v59, v63
	ds_write_b16 v188, v59 offset:7056
	ds_write_b16_d16_hi v188, v59 offset:7088
	v_mul_f32_e32 v52, v52, v254
	v_mul_f32_e32 v56, v56, v254
	v_mul_f32_e32 v60, v60, v254
	v_mul_f32_e32 v64, v64, v254
	v_mul_f32_e32 v136, 0xbfb8aa3b, v52
	v_mul_f32_e32 v137, 0xbfb8aa3b, v56
	v_exp_f32_e32 v136, v136
	v_exp_f32_e32 v137, v137
	v_mul_f32_e32 v60, v60, v52
	v_mul_f32_e32 v64, v64, v56
	v_add_f32_e32 v136, 1.0, v136
	v_add_f32_e32 v137, 1.0, v137
	v_rcp_f32_e32 v136, v136
	v_rcp_f32_e32 v137, v137
	s_nop 0
	v_mul_f32_e32 v60, v60, v136
	v_mul_f32_e32 v64, v64, v137
	v_cvt_pk_bf16_f32 v60, v60, v64
	ds_write_b16 v188, v60 offset:7200
	ds_write_b16_d16_hi v188, v60 offset:7232
	v_mul_f32_e32 v53, v53, v255
	v_mul_f32_e32 v57, v57, v255
	v_mul_f32_e32 v61, v61, v255
	v_mul_f32_e32 v65, v65, v255
	v_mul_f32_e32 v136, 0xbfb8aa3b, v53
	v_mul_f32_e32 v137, 0xbfb8aa3b, v57
	v_exp_f32_e32 v136, v136
	v_exp_f32_e32 v137, v137
	v_mul_f32_e32 v61, v61, v53
	v_mul_f32_e32 v65, v65, v57
	v_add_f32_e32 v136, 1.0, v136
	v_add_f32_e32 v137, 1.0, v137
	v_rcp_f32_e32 v136, v136
	v_rcp_f32_e32 v137, v137
	s_nop 0
	v_mul_f32_e32 v61, v61, v136
	v_mul_f32_e32 v65, v65, v137
	v_cvt_pk_bf16_f32 v61, v61, v65
	ds_write_b16 v188, v61 offset:7344
	ds_write_b16_d16_hi v188, v61 offset:7376
	s_waitcnt lgkmcnt(0)
	s_barrier
	ds_read_b128 v[144:147], v189
	ds_read_b128 v[148:151], v189 offset:4608
	ds_read_b128 v[172:175], v189 offset:9216
	ds_read_b128 v[176:179], v189 offset:13824
	s_mov_b32 s56, s58
	s_mov_b32 s57, s59
	s_waitcnt lgkmcnt(3)
	global_store_dwordx4 v243, v[144:147], s[56:57]
	s_add_u32 s56, s56, 0x59000
	s_addc_u32 s57, s57, 0
	s_waitcnt lgkmcnt(2)
	global_store_dwordx4 v243, v[148:151], s[56:57]
	s_add_u32 s56, s56, 0x59000
	s_addc_u32 s57, s57, 0
	s_waitcnt lgkmcnt(1)
	global_store_dwordx4 v243, v[172:175], s[56:57]
	s_add_u32 s56, s56, 0x59000
	s_addc_u32 s57, s57, 0
	s_waitcnt lgkmcnt(0)
	global_store_dwordx4 v243, v[176:179], s[56:57]
	s_add_u32 s58, s58, 0x400
	s_addc_u32 s59, s59, 0
	s_barrier
	v_mul_f32_e32 v66, v66, v152
	v_mul_f32_e32 v70, v70, v152
	v_mul_f32_e32 v74, v74, v152
	v_mul_f32_e32 v78, v78, v152
	v_mul_f32_e32 v136, 0xbfb8aa3b, v66
	v_mul_f32_e32 v137, 0xbfb8aa3b, v70
	v_exp_f32_e32 v136, v136
	v_exp_f32_e32 v137, v137
	v_mul_f32_e32 v74, v74, v66
	v_mul_f32_e32 v78, v78, v70
	v_add_f32_e32 v136, 1.0, v136
	v_add_f32_e32 v137, 1.0, v137
	v_rcp_f32_e32 v136, v136
	v_rcp_f32_e32 v137, v137
	s_nop 0
	v_mul_f32_e32 v74, v74, v136
	v_mul_f32_e32 v78, v78, v137
	v_cvt_pk_bf16_f32 v74, v74, v78
	ds_write_b16 v188, v74
	ds_write_b16_d16_hi v188, v74 offset:32
	v_mul_f32_e32 v67, v67, v153
	v_mul_f32_e32 v71, v71, v153
	v_mul_f32_e32 v75, v75, v153
	v_mul_f32_e32 v79, v79, v153
	v_mul_f32_e32 v136, 0xbfb8aa3b, v67
	v_mul_f32_e32 v137, 0xbfb8aa3b, v71
	v_exp_f32_e32 v136, v136
	v_exp_f32_e32 v137, v137
	v_mul_f32_e32 v75, v75, v67
	v_mul_f32_e32 v79, v79, v71
	v_add_f32_e32 v136, 1.0, v136
	v_add_f32_e32 v137, 1.0, v137
	v_rcp_f32_e32 v136, v136
	v_rcp_f32_e32 v137, v137
	s_nop 0
	v_mul_f32_e32 v75, v75, v136
	v_mul_f32_e32 v79, v79, v137
	v_cvt_pk_bf16_f32 v75, v75, v79
	ds_write_b16 v188, v75 offset:144
	ds_write_b16_d16_hi v188, v75 offset:176
	v_mul_f32_e32 v68, v68, v154
	v_mul_f32_e32 v72, v72, v154
	v_mul_f32_e32 v76, v76, v154
	v_mul_f32_e32 v80, v80, v154
	v_mul_f32_e32 v136, 0xbfb8aa3b, v68
	v_mul_f32_e32 v137, 0xbfb8aa3b, v72
	v_exp_f32_e32 v136, v136
	v_exp_f32_e32 v137, v137
	v_mul_f32_e32 v76, v76, v68
	v_mul_f32_e32 v80, v80, v72
	v_add_f32_e32 v136, 1.0, v136
	v_add_f32_e32 v137, 1.0, v137
	v_rcp_f32_e32 v136, v136
	v_rcp_f32_e32 v137, v137
	s_nop 0
	v_mul_f32_e32 v76, v76, v136
	v_mul_f32_e32 v80, v80, v137
	v_cvt_pk_bf16_f32 v76, v76, v80
	ds_write_b16 v188, v76 offset:288
	ds_write_b16_d16_hi v188, v76 offset:320
	v_mul_f32_e32 v69, v69, v155
	v_mul_f32_e32 v73, v73, v155
	v_mul_f32_e32 v77, v77, v155
	v_mul_f32_e32 v81, v81, v155
	v_mul_f32_e32 v136, 0xbfb8aa3b, v69
	v_mul_f32_e32 v137, 0xbfb8aa3b, v73
	v_exp_f32_e32 v136, v136
	v_exp_f32_e32 v137, v137
	v_mul_f32_e32 v77, v77, v69
	v_mul_f32_e32 v81, v81, v73
	v_add_f32_e32 v136, 1.0, v136
	v_add_f32_e32 v137, 1.0, v137
	v_rcp_f32_e32 v136, v136
	v_rcp_f32_e32 v137, v137
	s_nop 0
	v_mul_f32_e32 v77, v77, v136
	v_mul_f32_e32 v81, v81, v137
	v_cvt_pk_bf16_f32 v77, v77, v81
	ds_write_b16 v188, v77 offset:432
	ds_write_b16_d16_hi v188, v77 offset:464
	v_mul_f32_e32 v82, v82, v244
	v_mul_f32_e32 v86, v86, v244
	v_mul_f32_e32 v90, v90, v244
	v_mul_f32_e32 v94, v94, v244
	v_mul_f32_e32 v136, 0xbfb8aa3b, v82
	v_mul_f32_e32 v137, 0xbfb8aa3b, v86
	v_exp_f32_e32 v136, v136
	v_exp_f32_e32 v137, v137
	v_mul_f32_e32 v90, v90, v82
	v_mul_f32_e32 v94, v94, v86
	v_add_f32_e32 v136, 1.0, v136
	v_add_f32_e32 v137, 1.0, v137
	v_rcp_f32_e32 v136, v136
	v_rcp_f32_e32 v137, v137
	s_nop 0
	v_mul_f32_e32 v90, v90, v136
	v_mul_f32_e32 v94, v94, v137
	v_cvt_pk_bf16_f32 v90, v90, v94
	ds_write_b16 v188, v90 offset:2304
	ds_write_b16_d16_hi v188, v90 offset:2336
	v_mul_f32_e32 v83, v83, v245
	v_mul_f32_e32 v87, v87, v245
	v_mul_f32_e32 v91, v91, v245
	v_mul_f32_e32 v95, v95, v245
	v_mul_f32_e32 v136, 0xbfb8aa3b, v83
	v_mul_f32_e32 v137, 0xbfb8aa3b, v87
	v_exp_f32_e32 v136, v136
	v_exp_f32_e32 v137, v137
	v_mul_f32_e32 v91, v91, v83
	v_mul_f32_e32 v95, v95, v87
	v_add_f32_e32 v136, 1.0, v136
	v_add_f32_e32 v137, 1.0, v137
	v_rcp_f32_e32 v136, v136
	v_rcp_f32_e32 v137, v137
	s_nop 0
	v_mul_f32_e32 v91, v91, v136
	v_mul_f32_e32 v95, v95, v137
	v_cvt_pk_bf16_f32 v91, v91, v95
	ds_write_b16 v188, v91 offset:2448
	ds_write_b16_d16_hi v188, v91 offset:2480
	v_mul_f32_e32 v84, v84, v246
	v_mul_f32_e32 v88, v88, v246
	v_mul_f32_e32 v92, v92, v246
	v_mul_f32_e32 v96, v96, v246
	v_mul_f32_e32 v136, 0xbfb8aa3b, v84
	v_mul_f32_e32 v137, 0xbfb8aa3b, v88
	v_exp_f32_e32 v136, v136
	v_exp_f32_e32 v137, v137
	v_mul_f32_e32 v92, v92, v84
	v_mul_f32_e32 v96, v96, v88
	v_add_f32_e32 v136, 1.0, v136
	v_add_f32_e32 v137, 1.0, v137
	v_rcp_f32_e32 v136, v136
	v_rcp_f32_e32 v137, v137
	s_nop 0
	v_mul_f32_e32 v92, v92, v136
	v_mul_f32_e32 v96, v96, v137
	v_cvt_pk_bf16_f32 v92, v92, v96
	ds_write_b16 v188, v92 offset:2592
	ds_write_b16_d16_hi v188, v92 offset:2624
	v_mul_f32_e32 v85, v85, v247
	v_mul_f32_e32 v89, v89, v247
	v_mul_f32_e32 v93, v93, v247
	v_mul_f32_e32 v97, v97, v247
	v_mul_f32_e32 v136, 0xbfb8aa3b, v85
	v_mul_f32_e32 v137, 0xbfb8aa3b, v89
	v_exp_f32_e32 v136, v136
	v_exp_f32_e32 v137, v137
	v_mul_f32_e32 v93, v93, v85
	v_mul_f32_e32 v97, v97, v89
	v_add_f32_e32 v136, 1.0, v136
	v_add_f32_e32 v137, 1.0, v137
	v_rcp_f32_e32 v136, v136
	v_rcp_f32_e32 v137, v137
	s_nop 0
	v_mul_f32_e32 v93, v93, v136
	v_mul_f32_e32 v97, v97, v137
	v_cvt_pk_bf16_f32 v93, v93, v97
	ds_write_b16 v188, v93 offset:2736
	ds_write_b16_d16_hi v188, v93 offset:2768
	v_mul_f32_e32 v98, v98, v248
	v_mul_f32_e32 v102, v102, v248
	v_mul_f32_e32 v106, v106, v248
	v_mul_f32_e32 v110, v110, v248
	v_mul_f32_e32 v136, 0xbfb8aa3b, v98
	v_mul_f32_e32 v137, 0xbfb8aa3b, v102
	v_exp_f32_e32 v136, v136
	v_exp_f32_e32 v137, v137
	v_mul_f32_e32 v106, v106, v98
	v_mul_f32_e32 v110, v110, v102
	v_add_f32_e32 v136, 1.0, v136
	v_add_f32_e32 v137, 1.0, v137
	v_rcp_f32_e32 v136, v136
	v_rcp_f32_e32 v137, v137
	s_nop 0
	v_mul_f32_e32 v106, v106, v136
	v_mul_f32_e32 v110, v110, v137
	v_cvt_pk_bf16_f32 v106, v106, v110
	ds_write_b16 v188, v106 offset:4608
	ds_write_b16_d16_hi v188, v106 offset:4640
	v_mul_f32_e32 v99, v99, v249
	v_mul_f32_e32 v103, v103, v249
	v_mul_f32_e32 v107, v107, v249
	v_mul_f32_e32 v111, v111, v249
	v_mul_f32_e32 v136, 0xbfb8aa3b, v99
	v_mul_f32_e32 v137, 0xbfb8aa3b, v103
	v_exp_f32_e32 v136, v136
	v_exp_f32_e32 v137, v137
	v_mul_f32_e32 v107, v107, v99
	v_mul_f32_e32 v111, v111, v103
	v_add_f32_e32 v136, 1.0, v136
	v_add_f32_e32 v137, 1.0, v137
	v_rcp_f32_e32 v136, v136
	v_rcp_f32_e32 v137, v137
	s_nop 0
	v_mul_f32_e32 v107, v107, v136
	v_mul_f32_e32 v111, v111, v137
	v_cvt_pk_bf16_f32 v107, v107, v111
	ds_write_b16 v188, v107 offset:4752
	ds_write_b16_d16_hi v188, v107 offset:4784
	v_mul_f32_e32 v100, v100, v250
	v_mul_f32_e32 v104, v104, v250
	v_mul_f32_e32 v108, v108, v250
	v_mul_f32_e32 v112, v112, v250
	v_mul_f32_e32 v136, 0xbfb8aa3b, v100
	v_mul_f32_e32 v137, 0xbfb8aa3b, v104
	v_exp_f32_e32 v136, v136
	v_exp_f32_e32 v137, v137
	v_mul_f32_e32 v108, v108, v100
	v_mul_f32_e32 v112, v112, v104
	v_add_f32_e32 v136, 1.0, v136
	v_add_f32_e32 v137, 1.0, v137
	v_rcp_f32_e32 v136, v136
	v_rcp_f32_e32 v137, v137
	s_nop 0
	v_mul_f32_e32 v108, v108, v136
	v_mul_f32_e32 v112, v112, v137
	v_cvt_pk_bf16_f32 v108, v108, v112
	ds_write_b16 v188, v108 offset:4896
	ds_write_b16_d16_hi v188, v108 offset:4928
	v_mul_f32_e32 v101, v101, v251
	v_mul_f32_e32 v105, v105, v251
	v_mul_f32_e32 v109, v109, v251
	v_mul_f32_e32 v113, v113, v251
	v_mul_f32_e32 v136, 0xbfb8aa3b, v101
	v_mul_f32_e32 v137, 0xbfb8aa3b, v105
	v_exp_f32_e32 v136, v136
	v_exp_f32_e32 v137, v137
	v_mul_f32_e32 v109, v109, v101
	v_mul_f32_e32 v113, v113, v105
	v_add_f32_e32 v136, 1.0, v136
	v_add_f32_e32 v137, 1.0, v137
	v_rcp_f32_e32 v136, v136
	v_rcp_f32_e32 v137, v137
	s_nop 0
	v_mul_f32_e32 v109, v109, v136
	v_mul_f32_e32 v113, v113, v137
	v_cvt_pk_bf16_f32 v109, v109, v113
	ds_write_b16 v188, v109 offset:5040
	ds_write_b16_d16_hi v188, v109 offset:5072
	v_mul_f32_e32 v114, v114, v252
	v_mul_f32_e32 v118, v118, v252
	v_mul_f32_e32 v122, v122, v252
	v_mul_f32_e32 v126, v126, v252
	v_mul_f32_e32 v136, 0xbfb8aa3b, v114
	v_mul_f32_e32 v137, 0xbfb8aa3b, v118
	v_exp_f32_e32 v136, v136
	v_exp_f32_e32 v137, v137
	v_mul_f32_e32 v122, v122, v114
	v_mul_f32_e32 v126, v126, v118
	v_add_f32_e32 v136, 1.0, v136
	v_add_f32_e32 v137, 1.0, v137
	v_rcp_f32_e32 v136, v136
	v_rcp_f32_e32 v137, v137
	s_nop 0
	v_mul_f32_e32 v122, v122, v136
	v_mul_f32_e32 v126, v126, v137
	v_cvt_pk_bf16_f32 v122, v122, v126
	ds_write_b16 v188, v122 offset:6912
	ds_write_b16_d16_hi v188, v122 offset:6944
	v_mul_f32_e32 v115, v115, v253
	v_mul_f32_e32 v119, v119, v253
	v_mul_f32_e32 v123, v123, v253
	v_mul_f32_e32 v127, v127, v253
	v_mul_f32_e32 v136, 0xbfb8aa3b, v115
	v_mul_f32_e32 v137, 0xbfb8aa3b, v119
	v_exp_f32_e32 v136, v136
	v_exp_f32_e32 v137, v137
	v_mul_f32_e32 v123, v123, v115
	v_mul_f32_e32 v127, v127, v119
	v_add_f32_e32 v136, 1.0, v136
	v_add_f32_e32 v137, 1.0, v137
	v_rcp_f32_e32 v136, v136
	v_rcp_f32_e32 v137, v137
	s_nop 0
	v_mul_f32_e32 v123, v123, v136
	v_mul_f32_e32 v127, v127, v137
	v_cvt_pk_bf16_f32 v123, v123, v127
	ds_write_b16 v188, v123 offset:7056
	ds_write_b16_d16_hi v188, v123 offset:7088
	v_mul_f32_e32 v116, v116, v254
	v_mul_f32_e32 v120, v120, v254
	v_mul_f32_e32 v124, v124, v254
	v_mul_f32_e32 v128, v128, v254
	v_mul_f32_e32 v136, 0xbfb8aa3b, v116
	v_mul_f32_e32 v137, 0xbfb8aa3b, v120
	v_exp_f32_e32 v136, v136
	v_exp_f32_e32 v137, v137
	v_mul_f32_e32 v124, v124, v116
	v_mul_f32_e32 v128, v128, v120
	v_add_f32_e32 v136, 1.0, v136
	v_add_f32_e32 v137, 1.0, v137
	v_rcp_f32_e32 v136, v136
	v_rcp_f32_e32 v137, v137
	s_nop 0
	v_mul_f32_e32 v124, v124, v136
	v_mul_f32_e32 v128, v128, v137
	v_cvt_pk_bf16_f32 v124, v124, v128
	ds_write_b16 v188, v124 offset:7200
	ds_write_b16_d16_hi v188, v124 offset:7232
	v_mul_f32_e32 v117, v117, v255
	v_mul_f32_e32 v121, v121, v255
	v_mul_f32_e32 v125, v125, v255
	v_mul_f32_e32 v129, v129, v255
	v_mul_f32_e32 v136, 0xbfb8aa3b, v117
	v_mul_f32_e32 v137, 0xbfb8aa3b, v121
	v_exp_f32_e32 v136, v136
	v_exp_f32_e32 v137, v137
	v_mul_f32_e32 v125, v125, v117
	v_mul_f32_e32 v129, v129, v121
	v_add_f32_e32 v136, 1.0, v136
	v_add_f32_e32 v137, 1.0, v137
	v_rcp_f32_e32 v136, v136
	v_rcp_f32_e32 v137, v137
	s_nop 0
	v_mul_f32_e32 v125, v125, v136
	v_mul_f32_e32 v129, v129, v137
	v_cvt_pk_bf16_f32 v125, v125, v129
	ds_write_b16 v188, v125 offset:7344
	ds_write_b16_d16_hi v188, v125 offset:7376
	s_waitcnt lgkmcnt(0)
	s_barrier
	ds_read_b128 v[144:147], v189
	ds_read_b128 v[148:151], v189 offset:4608
	ds_read_b128 v[172:175], v189 offset:9216
	ds_read_b128 v[176:179], v189 offset:13824
	s_mov_b32 s56, s58
	s_mov_b32 s57, s59
	s_waitcnt lgkmcnt(3)
	global_store_dwordx4 v243, v[144:147], s[56:57]
	s_add_u32 s56, s56, 0x59000
	s_addc_u32 s57, s57, 0
	s_waitcnt lgkmcnt(2)
	global_store_dwordx4 v243, v[148:151], s[56:57]
	s_add_u32 s56, s56, 0x59000
	s_addc_u32 s57, s57, 0
	s_waitcnt lgkmcnt(1)
	global_store_dwordx4 v243, v[172:175], s[56:57]
	s_add_u32 s56, s56, 0x59000
	s_addc_u32 s57, s57, 0
	s_waitcnt lgkmcnt(0)
	global_store_dwordx4 v243, v[176:179], s[56:57]
	s_cmp_lt_u32 s55, 5
	s_barrier
	s_cbranch_scc0 .Lgu2_lastp
	v_mov_b32_e32 v2, 0
	v_mov_b32_e32 v3, 0
	v_mov_b32_e32 v4, 0
	v_mov_b32_e32 v5, 0
	v_mov_b32_e32 v6, 0
	v_mov_b32_e32 v7, 0
	v_mov_b32_e32 v8, 0
	v_mov_b32_e32 v9, 0
	v_mov_b32_e32 v10, 0
	v_mov_b32_e32 v11, 0
	v_mov_b32_e32 v12, 0
	v_mov_b32_e32 v13, 0
	v_mov_b32_e32 v14, 0
	v_mov_b32_e32 v15, 0
	v_mov_b32_e32 v16, 0
	v_mov_b32_e32 v17, 0
	v_mov_b32_e32 v18, 0
	v_mov_b32_e32 v19, 0
	v_mov_b32_e32 v20, 0
	v_mov_b32_e32 v21, 0
	v_mov_b32_e32 v22, 0
	v_mov_b32_e32 v23, 0
	v_mov_b32_e32 v24, 0
	v_mov_b32_e32 v25, 0
	v_mov_b32_e32 v26, 0
	v_mov_b32_e32 v27, 0
	v_mov_b32_e32 v28, 0
	v_mov_b32_e32 v29, 0
	v_mov_b32_e32 v30, 0
	v_mov_b32_e32 v31, 0
	v_mov_b32_e32 v32, 0
	v_mov_b32_e32 v33, 0
	v_mov_b32_e32 v34, 0
	v_mov_b32_e32 v35, 0
	v_mov_b32_e32 v36, 0
	v_mov_b32_e32 v37, 0
	v_mov_b32_e32 v38, 0
	v_mov_b32_e32 v39, 0
	v_mov_b32_e32 v40, 0
	v_mov_b32_e32 v41, 0
	v_mov_b32_e32 v42, 0
	v_mov_b32_e32 v43, 0
	v_mov_b32_e32 v44, 0
	v_mov_b32_e32 v45, 0
	v_mov_b32_e32 v46, 0
	v_mov_b32_e32 v47, 0
	v_mov_b32_e32 v48, 0
	v_mov_b32_e32 v49, 0
	v_mov_b32_e32 v50, 0
	v_mov_b32_e32 v51, 0
	v_mov_b32_e32 v52, 0
	v_mov_b32_e32 v53, 0
	v_mov_b32_e32 v54, 0
	v_mov_b32_e32 v55, 0
	v_mov_b32_e32 v56, 0
	v_mov_b32_e32 v57, 0
	v_mov_b32_e32 v58, 0
	v_mov_b32_e32 v59, 0
	v_mov_b32_e32 v60, 0
	v_mov_b32_e32 v61, 0
	v_mov_b32_e32 v62, 0
	v_mov_b32_e32 v63, 0
	v_mov_b32_e32 v64, 0
	v_mov_b32_e32 v65, 0
	v_mov_b32_e32 v66, 0
	v_mov_b32_e32 v67, 0
	v_mov_b32_e32 v68, 0
	v_mov_b32_e32 v69, 0
	v_mov_b32_e32 v70, 0
	v_mov_b32_e32 v71, 0
	v_mov_b32_e32 v72, 0
	v_mov_b32_e32 v73, 0
	v_mov_b32_e32 v74, 0
	v_mov_b32_e32 v75, 0
	v_mov_b32_e32 v76, 0
	v_mov_b32_e32 v77, 0
	v_mov_b32_e32 v78, 0
	v_mov_b32_e32 v79, 0
	v_mov_b32_e32 v80, 0
	v_mov_b32_e32 v81, 0
	v_mov_b32_e32 v82, 0
	v_mov_b32_e32 v83, 0
	v_mov_b32_e32 v84, 0
	v_mov_b32_e32 v85, 0
	v_mov_b32_e32 v86, 0
	v_mov_b32_e32 v87, 0
	v_mov_b32_e32 v88, 0
	v_mov_b32_e32 v89, 0
	v_mov_b32_e32 v90, 0
	v_mov_b32_e32 v91, 0
	v_mov_b32_e32 v92, 0
	v_mov_b32_e32 v93, 0
	v_mov_b32_e32 v94, 0
	v_mov_b32_e32 v95, 0
	v_mov_b32_e32 v96, 0
	v_mov_b32_e32 v97, 0
	v_mov_b32_e32 v98, 0
	v_mov_b32_e32 v99, 0
	v_mov_b32_e32 v100, 0
	v_mov_b32_e32 v101, 0
	v_mov_b32_e32 v102, 0
	v_mov_b32_e32 v103, 0
	v_mov_b32_e32 v104, 0
	v_mov_b32_e32 v105, 0
	v_mov_b32_e32 v106, 0
	v_mov_b32_e32 v107, 0
	v_mov_b32_e32 v108, 0
	v_mov_b32_e32 v109, 0
	v_mov_b32_e32 v110, 0
	v_mov_b32_e32 v111, 0
	v_mov_b32_e32 v112, 0
	v_mov_b32_e32 v113, 0
	v_mov_b32_e32 v114, 0
	v_mov_b32_e32 v115, 0
	v_mov_b32_e32 v116, 0
	v_mov_b32_e32 v117, 0
	v_mov_b32_e32 v118, 0
	v_mov_b32_e32 v119, 0
	v_mov_b32_e32 v120, 0
	v_mov_b32_e32 v121, 0
	v_mov_b32_e32 v122, 0
	v_mov_b32_e32 v123, 0
	v_mov_b32_e32 v124, 0
	v_mov_b32_e32 v125, 0
	v_mov_b32_e32 v126, 0
	v_mov_b32_e32 v127, 0
	v_mov_b32_e32 v128, 0
	v_mov_b32_e32 v129, 0
	s_load_dwordx2 s[56:57], s[12:13], 0x1d0
	v_bfe_u32 v241, v131, 4, 2
	s_lshr_b32 s0, s50, 1
	s_lshl_b32 s0, s0, 6
	s_add_i32 s0, s0, s53
	s_lshl_b32 s0, s0, 2
	v_lshlrev_b32_e32 v241, 4, v241
	s_waitcnt lgkmcnt(0)
	s_add_u32 s56, s56, s0
	s_addc_u32 s57, s57, 0
	global_load_dwordx4 v[152:155], v241, s[56:57]
	global_load_dwordx4 v[244:247], v241, s[56:57] offset:64
	global_load_dwordx4 v[248:251], v241, s[56:57] offset:128
	global_load_dwordx4 v[252:255], v241, s[56:57] offset:192
	s_waitcnt vmcnt(12)
	s_barrier
	s_mov_b32 s52, 0
	s_setprio 3
	v_add_u32_e32 v234, s22, v232
	v_add_u32_e32 v236, s28, v232
	v_add_u32_e32 v235, s22, v233
	v_add_u32_e32 v237, s28, v233
	ds_read_b128 v[136:139], v234
	ds_read_b128 v[140:143], v234 offset:2048
	ds_read_b128 v[144:147], v234 offset:4096
	ds_read_b128 v[148:151], v234 offset:6144
	ds_read_b128 v[188:191], v236
	ds_read_b128 v[196:199], v236 offset:2048
	ds_read_b128 v[200:203], v236 offset:4096
	ds_read_b128 v[204:207], v236 offset:6144
	ds_read_b128 v[172:175], v235
	ds_read_b128 v[176:179], v235 offset:2048
	ds_read_b128 v[180:183], v235 offset:4096
	ds_read_b128 v[184:187], v235 offset:6144
	ds_read_b128 v[212:215], v237
	ds_read_b128 v[216:219], v237 offset:2048
	ds_read_b128 v[220:223], v237 offset:4096
	ds_read_b128 v[224:227], v237 offset:6144
	s_add_i32 m0, s51, 0xc000
	s_nop 0
	global_load_lds_dwordx4 v228, s[44:45]
	s_add_i32 m0, s51, 0xc400
	s_nop 0
	global_load_lds_dwordx4 v230, s[44:45]
	s_add_i32 m0, s51, 0xe000
	s_nop 0
	global_load_lds_dwordx4 v229, s[44:45]
	s_add_i32 m0, s51, 0xe400
	s_nop 0
	global_load_lds_dwordx4 v231, s[44:45]
	s_add_i32 m0, s51, 0x10000
	s_nop 0
	global_load_lds_dwordx4 v228, s[46:47]
	s_add_i32 m0, s51, 0x10400
	s_nop 0
	global_load_lds_dwordx4 v230, s[46:47]
	s_waitcnt lgkmcnt(8)
	s_setprio 1
	v_mfma_f32_16x16x32_bf16 v[2:5], v[136:139], v[188:191], v[2:5]
	v_mfma_f32_16x16x32_bf16 v[6:9], v[136:139], v[196:199], v[6:9]
	v_mfma_f32_16x16x32_bf16 v[10:13], v[136:139], v[200:203], v[10:13]
	v_mfma_f32_16x16x32_bf16 v[14:17], v[136:139], v[204:207], v[14:17]
	v_mfma_f32_16x16x32_bf16 v[18:21], v[140:143], v[188:191], v[18:21]
	v_mfma_f32_16x16x32_bf16 v[22:25], v[140:143], v[196:199], v[22:25]
	v_mfma_f32_16x16x32_bf16 v[26:29], v[140:143], v[200:203], v[26:29]
	v_mfma_f32_16x16x32_bf16 v[30:33], v[140:143], v[204:207], v[30:33]
	v_mfma_f32_16x16x32_bf16 v[34:37], v[144:147], v[188:191], v[34:37]
	v_mfma_f32_16x16x32_bf16 v[38:41], v[144:147], v[196:199], v[38:41]
	v_mfma_f32_16x16x32_bf16 v[42:45], v[144:147], v[200:203], v[42:45]
	v_mfma_f32_16x16x32_bf16 v[46:49], v[144:147], v[204:207], v[46:49]
	v_mfma_f32_16x16x32_bf16 v[50:53], v[148:151], v[188:191], v[50:53]
	v_mfma_f32_16x16x32_bf16 v[54:57], v[148:151], v[196:199], v[54:57]
	v_mfma_f32_16x16x32_bf16 v[58:61], v[148:151], v[200:203], v[58:61]
	v_mfma_f32_16x16x32_bf16 v[62:65], v[148:151], v[204:207], v[62:65]
	s_waitcnt lgkmcnt(0)
	v_mfma_f32_16x16x32_bf16 v[2:5], v[172:175], v[212:215], v[2:5]
	v_mfma_f32_16x16x32_bf16 v[6:9], v[172:175], v[216:219], v[6:9]
	v_mfma_f32_16x16x32_bf16 v[10:13], v[172:175], v[220:223], v[10:13]
	v_mfma_f32_16x16x32_bf16 v[14:17], v[172:175], v[224:227], v[14:17]
	v_mfma_f32_16x16x32_bf16 v[18:21], v[176:179], v[212:215], v[18:21]
	v_mfma_f32_16x16x32_bf16 v[22:25], v[176:179], v[216:219], v[22:25]
	v_mfma_f32_16x16x32_bf16 v[26:29], v[176:179], v[220:223], v[26:29]
	v_mfma_f32_16x16x32_bf16 v[30:33], v[176:179], v[224:227], v[30:33]
	v_mfma_f32_16x16x32_bf16 v[34:37], v[180:183], v[212:215], v[34:37]
	v_mfma_f32_16x16x32_bf16 v[38:41], v[180:183], v[216:219], v[38:41]
	v_mfma_f32_16x16x32_bf16 v[42:45], v[180:183], v[220:223], v[42:45]
	v_mfma_f32_16x16x32_bf16 v[46:49], v[180:183], v[224:227], v[46:49]
	v_mfma_f32_16x16x32_bf16 v[50:53], v[184:187], v[212:215], v[50:53]
	v_mfma_f32_16x16x32_bf16 v[54:57], v[184:187], v[216:219], v[54:57]
	v_mfma_f32_16x16x32_bf16 v[58:61], v[184:187], v[220:223], v[58:61]
	v_mfma_f32_16x16x32_bf16 v[62:65], v[184:187], v[224:227], v[62:65]
	s_setprio 0
	s_waitcnt vmcnt(18)
	s_barrier
	s_branch .Lgu2_loop_a0

.Lres1_loop:
	s_setprio 3
	v_add_u32_e32 v234, s22, v232
	v_add_u32_e32 v236, s28, v232
	v_add_u32_e32 v235, s22, v233
	v_add_u32_e32 v237, s28, v233
	ds_read_b128 v[136:139], v234
	ds_read_b128 v[140:143], v234 offset:2048
	ds_read_b128 v[144:147], v234 offset:4096
	ds_read_b128 v[148:151], v234 offset:6144
	ds_read_b128 v[188:191], v236
	ds_read_b128 v[196:199], v236 offset:2048
	ds_read_b128 v[200:203], v236 offset:4096
	ds_read_b128 v[204:207], v236 offset:6144
	ds_read_b128 v[172:175], v235
	ds_read_b128 v[176:179], v235 offset:2048
	ds_read_b128 v[180:183], v235 offset:4096
	ds_read_b128 v[184:187], v235 offset:6144
	ds_read_b128 v[212:215], v237
	ds_read_b128 v[216:219], v237 offset:2048
	ds_read_b128 v[220:223], v237 offset:4096
	ds_read_b128 v[224:227], v237 offset:6144
	s_add_i32 m0, s51, 0xc000
	s_nop 0
	global_load_lds_dwordx4 v228, s[44:45]
	s_add_i32 m0, s51, 0xc400
	s_nop 0
	global_load_lds_dwordx4 v230, s[44:45]
	s_add_i32 m0, s51, 0xe000
	s_nop 0
	global_load_lds_dwordx4 v229, s[44:45]
	s_add_i32 m0, s51, 0xe400
	s_nop 0
	global_load_lds_dwordx4 v231, s[44:45]
	s_add_i32 m0, s51, 0x10000
	s_nop 0
	global_load_lds_dwordx4 v228, s[46:47]
	s_add_i32 m0, s51, 0x10400
	s_nop 0
	global_load_lds_dwordx4 v230, s[46:47]
	s_waitcnt lgkmcnt(8)
	s_setprio 1
	v_mfma_f32_16x16x32_bf16 v[2:5], v[136:139], v[188:191], v[2:5]
	v_mfma_f32_16x16x32_bf16 v[6:9], v[136:139], v[196:199], v[6:9]
	v_mfma_f32_16x16x32_bf16 v[10:13], v[136:139], v[200:203], v[10:13]
	v_mfma_f32_16x16x32_bf16 v[14:17], v[136:139], v[204:207], v[14:17]
	v_mfma_f32_16x16x32_bf16 v[18:21], v[140:143], v[188:191], v[18:21]
	v_mfma_f32_16x16x32_bf16 v[22:25], v[140:143], v[196:199], v[22:25]
	v_mfma_f32_16x16x32_bf16 v[26:29], v[140:143], v[200:203], v[26:29]
	v_mfma_f32_16x16x32_bf16 v[30:33], v[140:143], v[204:207], v[30:33]
	v_mfma_f32_16x16x32_bf16 v[34:37], v[144:147], v[188:191], v[34:37]
	v_mfma_f32_16x16x32_bf16 v[38:41], v[144:147], v[196:199], v[38:41]
	v_mfma_f32_16x16x32_bf16 v[42:45], v[144:147], v[200:203], v[42:45]
	v_mfma_f32_16x16x32_bf16 v[46:49], v[144:147], v[204:207], v[46:49]
	v_mfma_f32_16x16x32_bf16 v[50:53], v[148:151], v[188:191], v[50:53]
	v_mfma_f32_16x16x32_bf16 v[54:57], v[148:151], v[196:199], v[54:57]
	v_mfma_f32_16x16x32_bf16 v[58:61], v[148:151], v[200:203], v[58:61]
	v_mfma_f32_16x16x32_bf16 v[62:65], v[148:151], v[204:207], v[62:65]
	s_waitcnt lgkmcnt(0)
	v_mfma_f32_16x16x32_bf16 v[2:5], v[172:175], v[212:215], v[2:5]
	v_mfma_f32_16x16x32_bf16 v[6:9], v[172:175], v[216:219], v[6:9]
	v_mfma_f32_16x16x32_bf16 v[10:13], v[172:175], v[220:223], v[10:13]
	v_mfma_f32_16x16x32_bf16 v[14:17], v[172:175], v[224:227], v[14:17]
	v_mfma_f32_16x16x32_bf16 v[18:21], v[176:179], v[212:215], v[18:21]
	v_mfma_f32_16x16x32_bf16 v[22:25], v[176:179], v[216:219], v[22:25]
	v_mfma_f32_16x16x32_bf16 v[26:29], v[176:179], v[220:223], v[26:29]
	v_mfma_f32_16x16x32_bf16 v[30:33], v[176:179], v[224:227], v[30:33]
	v_mfma_f32_16x16x32_bf16 v[34:37], v[180:183], v[212:215], v[34:37]
	v_mfma_f32_16x16x32_bf16 v[38:41], v[180:183], v[216:219], v[38:41]
	v_mfma_f32_16x16x32_bf16 v[42:45], v[180:183], v[220:223], v[42:45]
	v_mfma_f32_16x16x32_bf16 v[46:49], v[180:183], v[224:227], v[46:49]
	v_mfma_f32_16x16x32_bf16 v[50:53], v[184:187], v[212:215], v[50:53]
	v_mfma_f32_16x16x32_bf16 v[54:57], v[184:187], v[216:219], v[54:57]
	v_mfma_f32_16x16x32_bf16 v[58:61], v[184:187], v[220:223], v[58:61]
	v_mfma_f32_16x16x32_bf16 v[62:65], v[184:187], v[224:227], v[62:65]
	s_setprio 0
	s_waitcnt vmcnt(6)
	s_barrier
	s_setprio 3
	v_add_u32_e32 v236, s40, v232
	v_add_u32_e32 v237, s40, v233
	ds_read_b128 v[188:191], v236
	ds_read_b128 v[196:199], v236 offset:2048
	ds_read_b128 v[200:203], v236 offset:4096
	ds_read_b128 v[204:207], v236 offset:6144
	ds_read_b128 v[212:215], v237
	ds_read_b128 v[216:219], v237 offset:2048
	ds_read_b128 v[220:223], v237 offset:4096
	ds_read_b128 v[224:227], v237 offset:6144
	s_mov_b32 m0, s51
	s_nop 0
	global_load_lds_dwordx4 v229, s[46:47]
	s_add_i32 m0, s51, 0x400
	s_nop 0
	global_load_lds_dwordx4 v231, s[46:47]
	s_add_i32 m0, s51, 0x2000
	s_nop 0
	global_load_lds_dwordx4 v228, s[48:49]
	s_add_i32 m0, s51, 0x2400
	s_nop 0
	global_load_lds_dwordx4 v230, s[48:49]
	s_add_i32 m0, s51, 0x4000
	s_nop 0
	global_load_lds_dwordx4 v229, s[48:49]
	s_add_i32 m0, s51, 0x4400
	s_nop 0
	global_load_lds_dwordx4 v231, s[48:49]
	s_waitcnt lgkmcnt(4)
	s_setprio 1
	v_mfma_f32_16x16x32_bf16 v[66:69], v[136:139], v[188:191], v[66:69]
	v_mfma_f32_16x16x32_bf16 v[70:73], v[136:139], v[196:199], v[70:73]
	v_mfma_f32_16x16x32_bf16 v[74:77], v[136:139], v[200:203], v[74:77]
	v_mfma_f32_16x16x32_bf16 v[78:81], v[136:139], v[204:207], v[78:81]
	v_mfma_f32_16x16x32_bf16 v[82:85], v[140:143], v[188:191], v[82:85]
	v_mfma_f32_16x16x32_bf16 v[86:89], v[140:143], v[196:199], v[86:89]
	v_mfma_f32_16x16x32_bf16 v[90:93], v[140:143], v[200:203], v[90:93]
	v_mfma_f32_16x16x32_bf16 v[94:97], v[140:143], v[204:207], v[94:97]
	v_mfma_f32_16x16x32_bf16 v[98:101], v[144:147], v[188:191], v[98:101]
	v_mfma_f32_16x16x32_bf16 v[102:105], v[144:147], v[196:199], v[102:105]
	v_mfma_f32_16x16x32_bf16 v[106:109], v[144:147], v[200:203], v[106:109]
	v_mfma_f32_16x16x32_bf16 v[110:113], v[144:147], v[204:207], v[110:113]
	v_mfma_f32_16x16x32_bf16 v[114:117], v[148:151], v[188:191], v[114:117]
	v_mfma_f32_16x16x32_bf16 v[118:121], v[148:151], v[196:199], v[118:121]
	v_mfma_f32_16x16x32_bf16 v[122:125], v[148:151], v[200:203], v[122:125]
	v_mfma_f32_16x16x32_bf16 v[126:129], v[148:151], v[204:207], v[126:129]
	s_waitcnt lgkmcnt(0)
	v_mfma_f32_16x16x32_bf16 v[66:69], v[172:175], v[212:215], v[66:69]
	v_mfma_f32_16x16x32_bf16 v[70:73], v[172:175], v[216:219], v[70:73]
	v_mfma_f32_16x16x32_bf16 v[74:77], v[172:175], v[220:223], v[74:77]
	v_mfma_f32_16x16x32_bf16 v[78:81], v[172:175], v[224:227], v[78:81]
	v_mfma_f32_16x16x32_bf16 v[82:85], v[176:179], v[212:215], v[82:85]
	v_mfma_f32_16x16x32_bf16 v[86:89], v[176:179], v[216:219], v[86:89]
	v_mfma_f32_16x16x32_bf16 v[90:93], v[176:179], v[220:223], v[90:93]
	v_mfma_f32_16x16x32_bf16 v[94:97], v[176:179], v[224:227], v[94:97]
	v_mfma_f32_16x16x32_bf16 v[98:101], v[180:183], v[212:215], v[98:101]
	v_mfma_f32_16x16x32_bf16 v[102:105], v[180:183], v[216:219], v[102:105]
	v_mfma_f32_16x16x32_bf16 v[106:109], v[180:183], v[220:223], v[106:109]
	v_mfma_f32_16x16x32_bf16 v[110:113], v[180:183], v[224:227], v[110:113]
	v_mfma_f32_16x16x32_bf16 v[114:117], v[184:187], v[212:215], v[114:117]
	v_mfma_f32_16x16x32_bf16 v[118:121], v[184:187], v[216:219], v[118:121]
	v_mfma_f32_16x16x32_bf16 v[122:125], v[184:187], v[220:223], v[122:125]
	v_mfma_f32_16x16x32_bf16 v[126:129], v[184:187], v[224:227], v[126:129]
	s_setprio 0
	v_add_u32_e32 v228, 0x80, v228
	v_add_u32_e32 v229, 0x80, v229
	v_add_u32_e32 v230, 0x80, v230
	v_add_u32_e32 v231, 0x80, v231
	s_waitcnt vmcnt(4)
	s_barrier
	s_setprio 3
	v_add_u32_e32 v234, s23, v232
	v_add_u32_e32 v236, s29, v232
	v_add_u32_e32 v235, s23, v233
	v_add_u32_e32 v237, s29, v233
	ds_read_b128 v[136:139], v234
	ds_read_b128 v[140:143], v234 offset:2048
	ds_read_b128 v[144:147], v234 offset:4096
	ds_read_b128 v[148:151], v234 offset:6144
	ds_read_b128 v[188:191], v236
	ds_read_b128 v[196:199], v236 offset:2048
	ds_read_b128 v[200:203], v236 offset:4096
	ds_read_b128 v[204:207], v236 offset:6144
	ds_read_b128 v[172:175], v235
	ds_read_b128 v[176:179], v235 offset:2048
	ds_read_b128 v[180:183], v235 offset:4096
	ds_read_b128 v[184:187], v235 offset:6144
	ds_read_b128 v[212:215], v237
	ds_read_b128 v[216:219], v237 offset:2048
	ds_read_b128 v[220:223], v237 offset:4096
	ds_read_b128 v[224:227], v237 offset:6144
	s_add_i32 m0, s51, 0x6000
	s_nop 0
	global_load_lds_dwordx4 v228, s[44:45]
	s_add_i32 m0, s51, 0x6400
	s_nop 0
	global_load_lds_dwordx4 v230, s[44:45]
	s_add_i32 m0, s51, 0x8000
	s_nop 0
	global_load_lds_dwordx4 v229, s[44:45]
	s_add_i32 m0, s51, 0x8400
	s_nop 0
	global_load_lds_dwordx4 v231, s[44:45]
	s_add_i32 m0, s51, 0xa000
	s_nop 0
	global_load_lds_dwordx4 v228, s[46:47]
	s_add_i32 m0, s51, 0xa400
	s_nop 0
	global_load_lds_dwordx4 v230, s[46:47]
	s_waitcnt lgkmcnt(8)
	s_setprio 1
	v_mfma_f32_16x16x32_bf16 v[2:5], v[136:139], v[188:191], v[2:5]
	v_mfma_f32_16x16x32_bf16 v[6:9], v[136:139], v[196:199], v[6:9]
	v_mfma_f32_16x16x32_bf16 v[10:13], v[136:139], v[200:203], v[10:13]
	v_mfma_f32_16x16x32_bf16 v[14:17], v[136:139], v[204:207], v[14:17]
	v_mfma_f32_16x16x32_bf16 v[18:21], v[140:143], v[188:191], v[18:21]
	v_mfma_f32_16x16x32_bf16 v[22:25], v[140:143], v[196:199], v[22:25]
	v_mfma_f32_16x16x32_bf16 v[26:29], v[140:143], v[200:203], v[26:29]
	v_mfma_f32_16x16x32_bf16 v[30:33], v[140:143], v[204:207], v[30:33]
	v_mfma_f32_16x16x32_bf16 v[34:37], v[144:147], v[188:191], v[34:37]
	v_mfma_f32_16x16x32_bf16 v[38:41], v[144:147], v[196:199], v[38:41]
	v_mfma_f32_16x16x32_bf16 v[42:45], v[144:147], v[200:203], v[42:45]
	v_mfma_f32_16x16x32_bf16 v[46:49], v[144:147], v[204:207], v[46:49]
	v_mfma_f32_16x16x32_bf16 v[50:53], v[148:151], v[188:191], v[50:53]
	v_mfma_f32_16x16x32_bf16 v[54:57], v[148:151], v[196:199], v[54:57]
	v_mfma_f32_16x16x32_bf16 v[58:61], v[148:151], v[200:203], v[58:61]
	v_mfma_f32_16x16x32_bf16 v[62:65], v[148:151], v[204:207], v[62:65]
	s_waitcnt lgkmcnt(0)
	v_mfma_f32_16x16x32_bf16 v[2:5], v[172:175], v[212:215], v[2:5]
	v_mfma_f32_16x16x32_bf16 v[6:9], v[172:175], v[216:219], v[6:9]
	v_mfma_f32_16x16x32_bf16 v[10:13], v[172:175], v[220:223], v[10:13]
	v_mfma_f32_16x16x32_bf16 v[14:17], v[172:175], v[224:227], v[14:17]
	v_mfma_f32_16x16x32_bf16 v[18:21], v[176:179], v[212:215], v[18:21]
	v_mfma_f32_16x16x32_bf16 v[22:25], v[176:179], v[216:219], v[22:25]
	v_mfma_f32_16x16x32_bf16 v[26:29], v[176:179], v[220:223], v[26:29]
	v_mfma_f32_16x16x32_bf16 v[30:33], v[176:179], v[224:227], v[30:33]
	v_mfma_f32_16x16x32_bf16 v[34:37], v[180:183], v[212:215], v[34:37]
	v_mfma_f32_16x16x32_bf16 v[38:41], v[180:183], v[216:219], v[38:41]
	v_mfma_f32_16x16x32_bf16 v[42:45], v[180:183], v[220:223], v[42:45]
	v_mfma_f32_16x16x32_bf16 v[46:49], v[180:183], v[224:227], v[46:49]
	v_mfma_f32_16x16x32_bf16 v[50:53], v[184:187], v[212:215], v[50:53]
	v_mfma_f32_16x16x32_bf16 v[54:57], v[184:187], v[216:219], v[54:57]
	v_mfma_f32_16x16x32_bf16 v[58:61], v[184:187], v[220:223], v[58:61]
	v_mfma_f32_16x16x32_bf16 v[62:65], v[184:187], v[224:227], v[62:65]
	s_setprio 0
	s_waitcnt vmcnt(6)
	s_barrier
	s_setprio 3
	v_add_u32_e32 v236, s41, v232
	v_add_u32_e32 v237, s41, v233
	ds_read_b128 v[188:191], v236
	ds_read_b128 v[196:199], v236 offset:2048
	ds_read_b128 v[200:203], v236 offset:4096
	ds_read_b128 v[204:207], v236 offset:6144
	ds_read_b128 v[212:215], v237
	ds_read_b128 v[216:219], v237 offset:2048
	ds_read_b128 v[220:223], v237 offset:4096
	ds_read_b128 v[224:227], v237 offset:6144
	s_add_i32 m0, s51, 0xc000
	s_nop 0
	global_load_lds_dwordx4 v229, s[46:47]
	s_add_i32 m0, s51, 0xc400
	s_nop 0
	global_load_lds_dwordx4 v231, s[46:47]
	s_add_i32 m0, s51, 0xe000
	s_nop 0
	global_load_lds_dwordx4 v228, s[48:49]
	s_add_i32 m0, s51, 0xe400
	s_nop 0
	global_load_lds_dwordx4 v230, s[48:49]
	s_add_i32 m0, s51, 0x10000
	s_nop 0
	global_load_lds_dwordx4 v229, s[48:49]
	s_add_i32 m0, s51, 0x10400
	s_nop 0
	global_load_lds_dwordx4 v231, s[48:49]
	s_waitcnt lgkmcnt(4)
	s_setprio 1
	v_mfma_f32_16x16x32_bf16 v[66:69], v[136:139], v[188:191], v[66:69]
	v_mfma_f32_16x16x32_bf16 v[70:73], v[136:139], v[196:199], v[70:73]
	v_mfma_f32_16x16x32_bf16 v[74:77], v[136:139], v[200:203], v[74:77]
	v_mfma_f32_16x16x32_bf16 v[78:81], v[136:139], v[204:207], v[78:81]
	v_mfma_f32_16x16x32_bf16 v[82:85], v[140:143], v[188:191], v[82:85]
	v_mfma_f32_16x16x32_bf16 v[86:89], v[140:143], v[196:199], v[86:89]
	v_mfma_f32_16x16x32_bf16 v[90:93], v[140:143], v[200:203], v[90:93]
	v_mfma_f32_16x16x32_bf16 v[94:97], v[140:143], v[204:207], v[94:97]
	v_mfma_f32_16x16x32_bf16 v[98:101], v[144:147], v[188:191], v[98:101]
	v_mfma_f32_16x16x32_bf16 v[102:105], v[144:147], v[196:199], v[102:105]
	v_mfma_f32_16x16x32_bf16 v[106:109], v[144:147], v[200:203], v[106:109]
	v_mfma_f32_16x16x32_bf16 v[110:113], v[144:147], v[204:207], v[110:113]
	v_mfma_f32_16x16x32_bf16 v[114:117], v[148:151], v[188:191], v[114:117]
	v_mfma_f32_16x16x32_bf16 v[118:121], v[148:151], v[196:199], v[118:121]
	v_mfma_f32_16x16x32_bf16 v[122:125], v[148:151], v[200:203], v[122:125]
	v_mfma_f32_16x16x32_bf16 v[126:129], v[148:151], v[204:207], v[126:129]
	s_waitcnt lgkmcnt(0)
	v_mfma_f32_16x16x32_bf16 v[66:69], v[172:175], v[212:215], v[66:69]
	v_mfma_f32_16x16x32_bf16 v[70:73], v[172:175], v[216:219], v[70:73]
	v_mfma_f32_16x16x32_bf16 v[74:77], v[172:175], v[220:223], v[74:77]
	v_mfma_f32_16x16x32_bf16 v[78:81], v[172:175], v[224:227], v[78:81]
	v_mfma_f32_16x16x32_bf16 v[82:85], v[176:179], v[212:215], v[82:85]
	v_mfma_f32_16x16x32_bf16 v[86:89], v[176:179], v[216:219], v[86:89]
	v_mfma_f32_16x16x32_bf16 v[90:93], v[176:179], v[220:223], v[90:93]
	v_mfma_f32_16x16x32_bf16 v[94:97], v[176:179], v[224:227], v[94:97]
	v_mfma_f32_16x16x32_bf16 v[98:101], v[180:183], v[212:215], v[98:101]
	v_mfma_f32_16x16x32_bf16 v[102:105], v[180:183], v[216:219], v[102:105]
	v_mfma_f32_16x16x32_bf16 v[106:109], v[180:183], v[220:223], v[106:109]
	v_mfma_f32_16x16x32_bf16 v[110:113], v[180:183], v[224:227], v[110:113]
	v_mfma_f32_16x16x32_bf16 v[114:117], v[184:187], v[212:215], v[114:117]
	v_mfma_f32_16x16x32_bf16 v[118:121], v[184:187], v[216:219], v[118:121]
	v_mfma_f32_16x16x32_bf16 v[122:125], v[184:187], v[220:223], v[122:125]
	v_mfma_f32_16x16x32_bf16 v[126:129], v[184:187], v[224:227], v[126:129]
	s_setprio 0
	v_add_u32_e32 v228, 0x80, v228
	v_add_u32_e32 v229, 0x80, v229
	v_add_u32_e32 v230, 0x80, v230
	v_add_u32_e32 v231, 0x80, v231
	s_waitcnt vmcnt(4)
	s_barrier
	s_setprio 3
	v_add_u32_e32 v234, s24, v232
	v_add_u32_e32 v236, s30, v232
	v_add_u32_e32 v235, s24, v233
	v_add_u32_e32 v237, s30, v233
	ds_read_b128 v[136:139], v234
	ds_read_b128 v[140:143], v234 offset:2048
	ds_read_b128 v[144:147], v234 offset:4096
	ds_read_b128 v[148:151], v234 offset:6144
	ds_read_b128 v[188:191], v236
	ds_read_b128 v[196:199], v236 offset:2048
	ds_read_b128 v[200:203], v236 offset:4096
	ds_read_b128 v[204:207], v236 offset:6144
	ds_read_b128 v[172:175], v235
	ds_read_b128 v[176:179], v235 offset:2048
	ds_read_b128 v[180:183], v235 offset:4096
	ds_read_b128 v[184:187], v235 offset:6144
	ds_read_b128 v[212:215], v237
	ds_read_b128 v[216:219], v237 offset:2048
	ds_read_b128 v[220:223], v237 offset:4096
	ds_read_b128 v[224:227], v237 offset:6144
	s_mov_b32 m0, s51
	s_nop 0
	global_load_lds_dwordx4 v228, s[44:45]
	s_add_i32 m0, s51, 0x400
	s_nop 0
	global_load_lds_dwordx4 v230, s[44:45]
	s_add_i32 m0, s51, 0x2000
	s_nop 0
	global_load_lds_dwordx4 v229, s[44:45]
	s_add_i32 m0, s51, 0x2400
	s_nop 0
	global_load_lds_dwordx4 v231, s[44:45]
	s_add_i32 m0, s51, 0x4000
	s_nop 0
	global_load_lds_dwordx4 v228, s[46:47]
	s_add_i32 m0, s51, 0x4400
	s_nop 0
	global_load_lds_dwordx4 v230, s[46:47]
	s_waitcnt lgkmcnt(8)
	s_setprio 1
	v_mfma_f32_16x16x32_bf16 v[2:5], v[136:139], v[188:191], v[2:5]
	v_mfma_f32_16x16x32_bf16 v[6:9], v[136:139], v[196:199], v[6:9]
	v_mfma_f32_16x16x32_bf16 v[10:13], v[136:139], v[200:203], v[10:13]
	v_mfma_f32_16x16x32_bf16 v[14:17], v[136:139], v[204:207], v[14:17]
	v_mfma_f32_16x16x32_bf16 v[18:21], v[140:143], v[188:191], v[18:21]
	v_mfma_f32_16x16x32_bf16 v[22:25], v[140:143], v[196:199], v[22:25]
	v_mfma_f32_16x16x32_bf16 v[26:29], v[140:143], v[200:203], v[26:29]
	v_mfma_f32_16x16x32_bf16 v[30:33], v[140:143], v[204:207], v[30:33]
	v_mfma_f32_16x16x32_bf16 v[34:37], v[144:147], v[188:191], v[34:37]
	v_mfma_f32_16x16x32_bf16 v[38:41], v[144:147], v[196:199], v[38:41]
	v_mfma_f32_16x16x32_bf16 v[42:45], v[144:147], v[200:203], v[42:45]
	v_mfma_f32_16x16x32_bf16 v[46:49], v[144:147], v[204:207], v[46:49]
	v_mfma_f32_16x16x32_bf16 v[50:53], v[148:151], v[188:191], v[50:53]
	v_mfma_f32_16x16x32_bf16 v[54:57], v[148:151], v[196:199], v[54:57]
	v_mfma_f32_16x16x32_bf16 v[58:61], v[148:151], v[200:203], v[58:61]
	v_mfma_f32_16x16x32_bf16 v[62:65], v[148:151], v[204:207], v[62:65]
	s_waitcnt lgkmcnt(0)
	v_mfma_f32_16x16x32_bf16 v[2:5], v[172:175], v[212:215], v[2:5]
	v_mfma_f32_16x16x32_bf16 v[6:9], v[172:175], v[216:219], v[6:9]
	v_mfma_f32_16x16x32_bf16 v[10:13], v[172:175], v[220:223], v[10:13]
	v_mfma_f32_16x16x32_bf16 v[14:17], v[172:175], v[224:227], v[14:17]
	v_mfma_f32_16x16x32_bf16 v[18:21], v[176:179], v[212:215], v[18:21]
	v_mfma_f32_16x16x32_bf16 v[22:25], v[176:179], v[216:219], v[22:25]
	v_mfma_f32_16x16x32_bf16 v[26:29], v[176:179], v[220:223], v[26:29]
	v_mfma_f32_16x16x32_bf16 v[30:33], v[176:179], v[224:227], v[30:33]
	v_mfma_f32_16x16x32_bf16 v[34:37], v[180:183], v[212:215], v[34:37]
	v_mfma_f32_16x16x32_bf16 v[38:41], v[180:183], v[216:219], v[38:41]
	v_mfma_f32_16x16x32_bf16 v[42:45], v[180:183], v[220:223], v[42:45]
	v_mfma_f32_16x16x32_bf16 v[46:49], v[180:183], v[224:227], v[46:49]
	v_mfma_f32_16x16x32_bf16 v[50:53], v[184:187], v[212:215], v[50:53]
	v_mfma_f32_16x16x32_bf16 v[54:57], v[184:187], v[216:219], v[54:57]
	v_mfma_f32_16x16x32_bf16 v[58:61], v[184:187], v[220:223], v[58:61]
	v_mfma_f32_16x16x32_bf16 v[62:65], v[184:187], v[224:227], v[62:65]
	s_setprio 0
	s_waitcnt vmcnt(6)
	s_barrier
	s_setprio 3
	v_add_u32_e32 v236, s42, v232
	v_add_u32_e32 v237, s42, v233
	ds_read_b128 v[188:191], v236
	ds_read_b128 v[196:199], v236 offset:2048
	ds_read_b128 v[200:203], v236 offset:4096
	ds_read_b128 v[204:207], v236 offset:6144
	ds_read_b128 v[212:215], v237
	ds_read_b128 v[216:219], v237 offset:2048
	ds_read_b128 v[220:223], v237 offset:4096
	ds_read_b128 v[224:227], v237 offset:6144
	s_add_i32 m0, s51, 0x6000
	s_nop 0
	global_load_lds_dwordx4 v229, s[46:47]
	s_add_i32 m0, s51, 0x6400
	s_nop 0
	global_load_lds_dwordx4 v231, s[46:47]
	s_add_i32 m0, s51, 0x8000
	s_nop 0
	global_load_lds_dwordx4 v228, s[48:49]
	s_add_i32 m0, s51, 0x8400
	s_nop 0
	global_load_lds_dwordx4 v230, s[48:49]
	s_add_i32 m0, s51, 0xa000
	s_nop 0
	global_load_lds_dwordx4 v229, s[48:49]
	s_add_i32 m0, s51, 0xa400
	s_nop 0
	global_load_lds_dwordx4 v231, s[48:49]
	s_waitcnt lgkmcnt(4)
	s_setprio 1
	v_mfma_f32_16x16x32_bf16 v[66:69], v[136:139], v[188:191], v[66:69]
	v_mfma_f32_16x16x32_bf16 v[70:73], v[136:139], v[196:199], v[70:73]
	v_mfma_f32_16x16x32_bf16 v[74:77], v[136:139], v[200:203], v[74:77]
	v_mfma_f32_16x16x32_bf16 v[78:81], v[136:139], v[204:207], v[78:81]
	v_mfma_f32_16x16x32_bf16 v[82:85], v[140:143], v[188:191], v[82:85]
	v_mfma_f32_16x16x32_bf16 v[86:89], v[140:143], v[196:199], v[86:89]
	v_mfma_f32_16x16x32_bf16 v[90:93], v[140:143], v[200:203], v[90:93]
	v_mfma_f32_16x16x32_bf16 v[94:97], v[140:143], v[204:207], v[94:97]
	v_mfma_f32_16x16x32_bf16 v[98:101], v[144:147], v[188:191], v[98:101]
	v_mfma_f32_16x16x32_bf16 v[102:105], v[144:147], v[196:199], v[102:105]
	v_mfma_f32_16x16x32_bf16 v[106:109], v[144:147], v[200:203], v[106:109]
	v_mfma_f32_16x16x32_bf16 v[110:113], v[144:147], v[204:207], v[110:113]
	v_mfma_f32_16x16x32_bf16 v[114:117], v[148:151], v[188:191], v[114:117]
	v_mfma_f32_16x16x32_bf16 v[118:121], v[148:151], v[196:199], v[118:121]
	v_mfma_f32_16x16x32_bf16 v[122:125], v[148:151], v[200:203], v[122:125]
	v_mfma_f32_16x16x32_bf16 v[126:129], v[148:151], v[204:207], v[126:129]
	s_waitcnt lgkmcnt(0)
	v_mfma_f32_16x16x32_bf16 v[66:69], v[172:175], v[212:215], v[66:69]
	v_mfma_f32_16x16x32_bf16 v[70:73], v[172:175], v[216:219], v[70:73]
	v_mfma_f32_16x16x32_bf16 v[74:77], v[172:175], v[220:223], v[74:77]
	v_mfma_f32_16x16x32_bf16 v[78:81], v[172:175], v[224:227], v[78:81]
	v_mfma_f32_16x16x32_bf16 v[82:85], v[176:179], v[212:215], v[82:85]
	v_mfma_f32_16x16x32_bf16 v[86:89], v[176:179], v[216:219], v[86:89]
	v_mfma_f32_16x16x32_bf16 v[90:93], v[176:179], v[220:223], v[90:93]
	v_mfma_f32_16x16x32_bf16 v[94:97], v[176:179], v[224:227], v[94:97]
	v_mfma_f32_16x16x32_bf16 v[98:101], v[180:183], v[212:215], v[98:101]
	v_mfma_f32_16x16x32_bf16 v[102:105], v[180:183], v[216:219], v[102:105]
	v_mfma_f32_16x16x32_bf16 v[106:109], v[180:183], v[220:223], v[106:109]
	v_mfma_f32_16x16x32_bf16 v[110:113], v[180:183], v[224:227], v[110:113]
	v_mfma_f32_16x16x32_bf16 v[114:117], v[184:187], v[212:215], v[114:117]
	v_mfma_f32_16x16x32_bf16 v[118:121], v[184:187], v[216:219], v[118:121]
	v_mfma_f32_16x16x32_bf16 v[122:125], v[184:187], v[220:223], v[122:125]
	v_mfma_f32_16x16x32_bf16 v[126:129], v[184:187], v[224:227], v[126:129]
	s_setprio 0
	v_add_u32_e32 v228, 0x80, v228
	v_add_u32_e32 v229, 0x80, v229
	v_add_u32_e32 v230, 0x80, v230
	v_add_u32_e32 v231, 0x80, v231
	s_waitcnt vmcnt(4)
	s_barrier
	s_add_i32 s52, s52, 1
	s_cmp_lt_u32 s52, 10
	s_cbranch_scc1 .Lres1_loop
	s_setprio 3
	v_add_u32_e32 v234, s22, v232
	v_add_u32_e32 v236, s28, v232
	v_add_u32_e32 v235, s22, v233
	v_add_u32_e32 v237, s28, v233
	ds_read_b128 v[136:139], v234
	ds_read_b128 v[140:143], v234 offset:2048
	ds_read_b128 v[144:147], v234 offset:4096
	ds_read_b128 v[148:151], v234 offset:6144
	ds_read_b128 v[188:191], v236
	ds_read_b128 v[196:199], v236 offset:2048
	ds_read_b128 v[200:203], v236 offset:4096
	ds_read_b128 v[204:207], v236 offset:6144
	ds_read_b128 v[172:175], v235
	ds_read_b128 v[176:179], v235 offset:2048
	ds_read_b128 v[180:183], v235 offset:4096
	ds_read_b128 v[184:187], v235 offset:6144
	ds_read_b128 v[212:215], v237
	ds_read_b128 v[216:219], v237 offset:2048
	ds_read_b128 v[220:223], v237 offset:4096
	ds_read_b128 v[224:227], v237 offset:6144
	s_add_i32 m0, s51, 0xc000
	s_nop 0
	global_load_lds_dwordx4 v228, s[44:45]
	s_add_i32 m0, s51, 0xc400
	s_nop 0
	global_load_lds_dwordx4 v230, s[44:45]
	s_add_i32 m0, s51, 0xe000
	s_nop 0
	global_load_lds_dwordx4 v229, s[44:45]
	s_add_i32 m0, s51, 0xe400
	s_nop 0
	global_load_lds_dwordx4 v231, s[44:45]
	s_add_i32 m0, s51, 0x10000
	s_nop 0
	global_load_lds_dwordx4 v228, s[46:47]
	s_add_i32 m0, s51, 0x10400
	s_nop 0
	global_load_lds_dwordx4 v230, s[46:47]
	s_waitcnt lgkmcnt(8)
	s_setprio 1
	v_mfma_f32_16x16x32_bf16 v[2:5], v[136:139], v[188:191], v[2:5]
	v_mfma_f32_16x16x32_bf16 v[6:9], v[136:139], v[196:199], v[6:9]
	v_mfma_f32_16x16x32_bf16 v[10:13], v[136:139], v[200:203], v[10:13]
	v_mfma_f32_16x16x32_bf16 v[14:17], v[136:139], v[204:207], v[14:17]
	v_mfma_f32_16x16x32_bf16 v[18:21], v[140:143], v[188:191], v[18:21]
	v_mfma_f32_16x16x32_bf16 v[22:25], v[140:143], v[196:199], v[22:25]
	v_mfma_f32_16x16x32_bf16 v[26:29], v[140:143], v[200:203], v[26:29]
	v_mfma_f32_16x16x32_bf16 v[30:33], v[140:143], v[204:207], v[30:33]
	v_mfma_f32_16x16x32_bf16 v[34:37], v[144:147], v[188:191], v[34:37]
	v_mfma_f32_16x16x32_bf16 v[38:41], v[144:147], v[196:199], v[38:41]
	v_mfma_f32_16x16x32_bf16 v[42:45], v[144:147], v[200:203], v[42:45]
	v_mfma_f32_16x16x32_bf16 v[46:49], v[144:147], v[204:207], v[46:49]
	v_mfma_f32_16x16x32_bf16 v[50:53], v[148:151], v[188:191], v[50:53]
	v_mfma_f32_16x16x32_bf16 v[54:57], v[148:151], v[196:199], v[54:57]
	v_mfma_f32_16x16x32_bf16 v[58:61], v[148:151], v[200:203], v[58:61]
	v_mfma_f32_16x16x32_bf16 v[62:65], v[148:151], v[204:207], v[62:65]
	s_waitcnt lgkmcnt(0)
	v_mfma_f32_16x16x32_bf16 v[2:5], v[172:175], v[212:215], v[2:5]
	v_mfma_f32_16x16x32_bf16 v[6:9], v[172:175], v[216:219], v[6:9]
	v_mfma_f32_16x16x32_bf16 v[10:13], v[172:175], v[220:223], v[10:13]
	v_mfma_f32_16x16x32_bf16 v[14:17], v[172:175], v[224:227], v[14:17]
	v_mfma_f32_16x16x32_bf16 v[18:21], v[176:179], v[212:215], v[18:21]
	v_mfma_f32_16x16x32_bf16 v[22:25], v[176:179], v[216:219], v[22:25]
	v_mfma_f32_16x16x32_bf16 v[26:29], v[176:179], v[220:223], v[26:29]
	v_mfma_f32_16x16x32_bf16 v[30:33], v[176:179], v[224:227], v[30:33]
	v_mfma_f32_16x16x32_bf16 v[34:37], v[180:183], v[212:215], v[34:37]
	v_mfma_f32_16x16x32_bf16 v[38:41], v[180:183], v[216:219], v[38:41]
	v_mfma_f32_16x16x32_bf16 v[42:45], v[180:183], v[220:223], v[42:45]
	v_mfma_f32_16x16x32_bf16 v[46:49], v[180:183], v[224:227], v[46:49]
	v_mfma_f32_16x16x32_bf16 v[50:53], v[184:187], v[212:215], v[50:53]
	v_mfma_f32_16x16x32_bf16 v[54:57], v[184:187], v[216:219], v[54:57]
	v_mfma_f32_16x16x32_bf16 v[58:61], v[184:187], v[220:223], v[58:61]
	v_mfma_f32_16x16x32_bf16 v[62:65], v[184:187], v[224:227], v[62:65]
	s_setprio 0
	s_waitcnt vmcnt(6)
	s_barrier
	s_setprio 3
	v_add_u32_e32 v236, s40, v232
	v_add_u32_e32 v237, s40, v233
	ds_read_b128 v[188:191], v236
	ds_read_b128 v[196:199], v236 offset:2048
	ds_read_b128 v[200:203], v236 offset:4096
	ds_read_b128 v[204:207], v236 offset:6144
	ds_read_b128 v[212:215], v237
	ds_read_b128 v[216:219], v237 offset:2048
	ds_read_b128 v[220:223], v237 offset:4096
	ds_read_b128 v[224:227], v237 offset:6144
	s_mov_b32 m0, s51
	s_nop 0
	global_load_lds_dwordx4 v229, s[46:47]
	s_add_i32 m0, s51, 0x400
	s_nop 0
	global_load_lds_dwordx4 v231, s[46:47]
	s_add_i32 m0, s51, 0x2000
	s_nop 0
	global_load_lds_dwordx4 v228, s[48:49]
	s_add_i32 m0, s51, 0x2400
	s_nop 0
	global_load_lds_dwordx4 v230, s[48:49]
	s_add_i32 m0, s51, 0x4000
	s_nop 0
	global_load_lds_dwordx4 v229, s[48:49]
	s_add_i32 m0, s51, 0x4400
	s_nop 0
	global_load_lds_dwordx4 v231, s[48:49]
	s_waitcnt lgkmcnt(4)
	s_setprio 1
	v_mfma_f32_16x16x32_bf16 v[66:69], v[136:139], v[188:191], v[66:69]
	v_mfma_f32_16x16x32_bf16 v[70:73], v[136:139], v[196:199], v[70:73]
	v_mfma_f32_16x16x32_bf16 v[74:77], v[136:139], v[200:203], v[74:77]
	v_mfma_f32_16x16x32_bf16 v[78:81], v[136:139], v[204:207], v[78:81]
	v_mfma_f32_16x16x32_bf16 v[82:85], v[140:143], v[188:191], v[82:85]
	v_mfma_f32_16x16x32_bf16 v[86:89], v[140:143], v[196:199], v[86:89]
	v_mfma_f32_16x16x32_bf16 v[90:93], v[140:143], v[200:203], v[90:93]
	v_mfma_f32_16x16x32_bf16 v[94:97], v[140:143], v[204:207], v[94:97]
	v_mfma_f32_16x16x32_bf16 v[98:101], v[144:147], v[188:191], v[98:101]
	v_mfma_f32_16x16x32_bf16 v[102:105], v[144:147], v[196:199], v[102:105]
	v_mfma_f32_16x16x32_bf16 v[106:109], v[144:147], v[200:203], v[106:109]
	v_mfma_f32_16x16x32_bf16 v[110:113], v[144:147], v[204:207], v[110:113]
	v_mfma_f32_16x16x32_bf16 v[114:117], v[148:151], v[188:191], v[114:117]
	v_mfma_f32_16x16x32_bf16 v[118:121], v[148:151], v[196:199], v[118:121]
	v_mfma_f32_16x16x32_bf16 v[122:125], v[148:151], v[200:203], v[122:125]
	v_mfma_f32_16x16x32_bf16 v[126:129], v[148:151], v[204:207], v[126:129]
	s_waitcnt lgkmcnt(0)
	v_mfma_f32_16x16x32_bf16 v[66:69], v[172:175], v[212:215], v[66:69]
	v_mfma_f32_16x16x32_bf16 v[70:73], v[172:175], v[216:219], v[70:73]
	v_mfma_f32_16x16x32_bf16 v[74:77], v[172:175], v[220:223], v[74:77]
	v_mfma_f32_16x16x32_bf16 v[78:81], v[172:175], v[224:227], v[78:81]
	v_mfma_f32_16x16x32_bf16 v[82:85], v[176:179], v[212:215], v[82:85]
	v_mfma_f32_16x16x32_bf16 v[86:89], v[176:179], v[216:219], v[86:89]
	v_mfma_f32_16x16x32_bf16 v[90:93], v[176:179], v[220:223], v[90:93]
	v_mfma_f32_16x16x32_bf16 v[94:97], v[176:179], v[224:227], v[94:97]
	v_mfma_f32_16x16x32_bf16 v[98:101], v[180:183], v[212:215], v[98:101]
	v_mfma_f32_16x16x32_bf16 v[102:105], v[180:183], v[216:219], v[102:105]
	v_mfma_f32_16x16x32_bf16 v[106:109], v[180:183], v[220:223], v[106:109]
	v_mfma_f32_16x16x32_bf16 v[110:113], v[180:183], v[224:227], v[110:113]
	v_mfma_f32_16x16x32_bf16 v[114:117], v[184:187], v[212:215], v[114:117]
	v_mfma_f32_16x16x32_bf16 v[118:121], v[184:187], v[216:219], v[118:121]
	v_mfma_f32_16x16x32_bf16 v[122:125], v[184:187], v[220:223], v[122:125]
	v_mfma_f32_16x16x32_bf16 v[126:129], v[184:187], v[224:227], v[126:129]
	s_setprio 0
	v_add_u32_e32 v228, 0x80, v228
	v_add_u32_e32 v229, 0x80, v229
	v_add_u32_e32 v230, 0x80, v230
	v_add_u32_e32 v231, 0x80, v231
	s_waitcnt vmcnt(4)
	s_barrier
	s_setprio 3
	v_add_u32_e32 v234, s23, v232
	v_add_u32_e32 v236, s29, v232
	v_add_u32_e32 v235, s23, v233
	v_add_u32_e32 v237, s29, v233
	ds_read_b128 v[136:139], v234
	ds_read_b128 v[140:143], v234 offset:2048
	ds_read_b128 v[144:147], v234 offset:4096
	ds_read_b128 v[148:151], v234 offset:6144
	ds_read_b128 v[188:191], v236
	ds_read_b128 v[196:199], v236 offset:2048
	ds_read_b128 v[200:203], v236 offset:4096
	ds_read_b128 v[204:207], v236 offset:6144
	ds_read_b128 v[172:175], v235
	ds_read_b128 v[176:179], v235 offset:2048
	ds_read_b128 v[180:183], v235 offset:4096
	ds_read_b128 v[184:187], v235 offset:6144
	ds_read_b128 v[212:215], v237
	ds_read_b128 v[216:219], v237 offset:2048
	ds_read_b128 v[220:223], v237 offset:4096
	ds_read_b128 v[224:227], v237 offset:6144
	s_waitcnt lgkmcnt(8)
	s_setprio 1
	v_mfma_f32_16x16x32_bf16 v[2:5], v[136:139], v[188:191], v[2:5]
	v_mfma_f32_16x16x32_bf16 v[6:9], v[136:139], v[196:199], v[6:9]
	v_mfma_f32_16x16x32_bf16 v[10:13], v[136:139], v[200:203], v[10:13]
	v_mfma_f32_16x16x32_bf16 v[14:17], v[136:139], v[204:207], v[14:17]
	v_mfma_f32_16x16x32_bf16 v[18:21], v[140:143], v[188:191], v[18:21]
	v_mfma_f32_16x16x32_bf16 v[22:25], v[140:143], v[196:199], v[22:25]
	v_mfma_f32_16x16x32_bf16 v[26:29], v[140:143], v[200:203], v[26:29]
	v_mfma_f32_16x16x32_bf16 v[30:33], v[140:143], v[204:207], v[30:33]
	v_mfma_f32_16x16x32_bf16 v[34:37], v[144:147], v[188:191], v[34:37]
	v_mfma_f32_16x16x32_bf16 v[38:41], v[144:147], v[196:199], v[38:41]
	v_mfma_f32_16x16x32_bf16 v[42:45], v[144:147], v[200:203], v[42:45]
	v_mfma_f32_16x16x32_bf16 v[46:49], v[144:147], v[204:207], v[46:49]
	v_mfma_f32_16x16x32_bf16 v[50:53], v[148:151], v[188:191], v[50:53]
	v_mfma_f32_16x16x32_bf16 v[54:57], v[148:151], v[196:199], v[54:57]
	v_mfma_f32_16x16x32_bf16 v[58:61], v[148:151], v[200:203], v[58:61]
	v_mfma_f32_16x16x32_bf16 v[62:65], v[148:151], v[204:207], v[62:65]
	s_waitcnt lgkmcnt(0)
	v_mfma_f32_16x16x32_bf16 v[2:5], v[172:175], v[212:215], v[2:5]
	v_mfma_f32_16x16x32_bf16 v[6:9], v[172:175], v[216:219], v[6:9]
	v_mfma_f32_16x16x32_bf16 v[10:13], v[172:175], v[220:223], v[10:13]
	v_mfma_f32_16x16x32_bf16 v[14:17], v[172:175], v[224:227], v[14:17]
	v_mfma_f32_16x16x32_bf16 v[18:21], v[176:179], v[212:215], v[18:21]
	v_mfma_f32_16x16x32_bf16 v[22:25], v[176:179], v[216:219], v[22:25]
	v_mfma_f32_16x16x32_bf16 v[26:29], v[176:179], v[220:223], v[26:29]
	v_mfma_f32_16x16x32_bf16 v[30:33], v[176:179], v[224:227], v[30:33]
	v_mfma_f32_16x16x32_bf16 v[34:37], v[180:183], v[212:215], v[34:37]
	v_mfma_f32_16x16x32_bf16 v[38:41], v[180:183], v[216:219], v[38:41]
	v_mfma_f32_16x16x32_bf16 v[42:45], v[180:183], v[220:223], v[42:45]
	v_mfma_f32_16x16x32_bf16 v[46:49], v[180:183], v[224:227], v[46:49]
	v_mfma_f32_16x16x32_bf16 v[50:53], v[184:187], v[212:215], v[50:53]
	v_mfma_f32_16x16x32_bf16 v[54:57], v[184:187], v[216:219], v[54:57]
	v_mfma_f32_16x16x32_bf16 v[58:61], v[184:187], v[220:223], v[58:61]
	v_mfma_f32_16x16x32_bf16 v[62:65], v[184:187], v[224:227], v[62:65]
	s_setprio 0
	s_waitcnt vmcnt(0)
	s_barrier
	s_setprio 3
	v_add_u32_e32 v236, s41, v232
	v_add_u32_e32 v237, s41, v233
	ds_read_b128 v[188:191], v236
	ds_read_b128 v[196:199], v236 offset:2048
	ds_read_b128 v[200:203], v236 offset:4096
	ds_read_b128 v[204:207], v236 offset:6144
	ds_read_b128 v[212:215], v237
	ds_read_b128 v[216:219], v237 offset:2048
	ds_read_b128 v[220:223], v237 offset:4096
	ds_read_b128 v[224:227], v237 offset:6144
	s_waitcnt lgkmcnt(4)
	s_setprio 1
	v_mfma_f32_16x16x32_bf16 v[66:69], v[136:139], v[188:191], v[66:69]
	v_mfma_f32_16x16x32_bf16 v[70:73], v[136:139], v[196:199], v[70:73]
	v_mfma_f32_16x16x32_bf16 v[74:77], v[136:139], v[200:203], v[74:77]
	v_mfma_f32_16x16x32_bf16 v[78:81], v[136:139], v[204:207], v[78:81]
	v_mfma_f32_16x16x32_bf16 v[82:85], v[140:143], v[188:191], v[82:85]
	v_mfma_f32_16x16x32_bf16 v[86:89], v[140:143], v[196:199], v[86:89]
	v_mfma_f32_16x16x32_bf16 v[90:93], v[140:143], v[200:203], v[90:93]
	v_mfma_f32_16x16x32_bf16 v[94:97], v[140:143], v[204:207], v[94:97]
	v_mfma_f32_16x16x32_bf16 v[98:101], v[144:147], v[188:191], v[98:101]
	v_mfma_f32_16x16x32_bf16 v[102:105], v[144:147], v[196:199], v[102:105]
	v_mfma_f32_16x16x32_bf16 v[106:109], v[144:147], v[200:203], v[106:109]
	v_mfma_f32_16x16x32_bf16 v[110:113], v[144:147], v[204:207], v[110:113]
	v_mfma_f32_16x16x32_bf16 v[114:117], v[148:151], v[188:191], v[114:117]
	v_mfma_f32_16x16x32_bf16 v[118:121], v[148:151], v[196:199], v[118:121]
	v_mfma_f32_16x16x32_bf16 v[122:125], v[148:151], v[200:203], v[122:125]
	v_mfma_f32_16x16x32_bf16 v[126:129], v[148:151], v[204:207], v[126:129]
	s_waitcnt lgkmcnt(0)
	v_mfma_f32_16x16x32_bf16 v[66:69], v[172:175], v[212:215], v[66:69]
	v_mfma_f32_16x16x32_bf16 v[70:73], v[172:175], v[216:219], v[70:73]
	v_mfma_f32_16x16x32_bf16 v[74:77], v[172:175], v[220:223], v[74:77]
	v_mfma_f32_16x16x32_bf16 v[78:81], v[172:175], v[224:227], v[78:81]
	v_mfma_f32_16x16x32_bf16 v[82:85], v[176:179], v[212:215], v[82:85]
	v_mfma_f32_16x16x32_bf16 v[86:89], v[176:179], v[216:219], v[86:89]
	v_mfma_f32_16x16x32_bf16 v[90:93], v[176:179], v[220:223], v[90:93]
	v_mfma_f32_16x16x32_bf16 v[94:97], v[176:179], v[224:227], v[94:97]
	v_mfma_f32_16x16x32_bf16 v[98:101], v[180:183], v[212:215], v[98:101]
	v_mfma_f32_16x16x32_bf16 v[102:105], v[180:183], v[216:219], v[102:105]
	v_mfma_f32_16x16x32_bf16 v[106:109], v[180:183], v[220:223], v[106:109]
	v_mfma_f32_16x16x32_bf16 v[110:113], v[180:183], v[224:227], v[110:113]
	v_mfma_f32_16x16x32_bf16 v[114:117], v[184:187], v[212:215], v[114:117]
	v_mfma_f32_16x16x32_bf16 v[118:121], v[184:187], v[216:219], v[118:121]
	v_mfma_f32_16x16x32_bf16 v[122:125], v[184:187], v[220:223], v[122:125]
	v_mfma_f32_16x16x32_bf16 v[126:129], v[184:187], v[224:227], v[126:129]
	s_setprio 0
	s_nop 7
	s_barrier
	s_load_dwordx2 s[44:45], s[12:13], 0x0
	s_load_dwordx2 s[58:59], s[12:13], 0x100
	s_load_dwordx2 s[46:47], s[12:13], 0x160
	s_load_dwordx2 s[48:49], s[12:13], 0x1c8
	v_lshrrev_b32_e32 v241, 5, v131
	v_and_b32_e32 v242, 31, v131
	v_lshlrev_b32_e32 v243, 4, v242
	s_movk_i32 s56, 0x210
	v_mad_u32_u24 v239, v241, s56, v243
	v_add_u32_e32 v239, 16, v239
	v_lshlrev_b32_e32 v240, 13, v241
	v_or_b32_e32 v240, v240, v243
	v_lshlrev_b32_e32 v244, 3, v242
	v_mad_u32_u24 v244, v241, s81, v244
	v_lshlrev_b32_e32 v245, 2, v241
	s_lshl_b32 s56, s53, 13
	s_lshl_b32 s57, s54, 2
	s_add_i32 s56, s56, s57
	s_mul_i32 s57, s53, s81
	s_lshl_b32 s0, s54, 1
	s_add_i32 s57, s57, s0
	s_lshl_b32 s0, s53, 2
	s_waitcnt lgkmcnt(0)
	s_add_u32 s44, s44, s56
	s_addc_u32 s45, s45, 0
	s_add_u32 s58, s58, s56
	s_addc_u32 s59, s59, 0
	s_add_u32 s46, s46, s57
	s_addc_u32 s47, s47, 0
	s_add_u32 s48, s48, s0
	s_addc_u32 s49, s49, 0
	s_mov_b32 s56, s44
	s_mov_b32 s57, s45
	global_load_dwordx4 v[136:139], v240, s[56:57]
	s_add_u32 s56, s56, 0x10000
	s_addc_u32 s57, s57, 0
	global_load_dwordx4 v[140:143], v240, s[56:57]
	s_add_u32 s56, s56, 0x10000
	s_addc_u32 s57, s57, 0
	global_load_dwordx4 v[144:147], v240, s[56:57]
	s_add_u32 s56, s56, 0x10000
	s_addc_u32 s57, s57, 0
	global_load_dwordx4 v[148:151], v240, s[56:57]
	s_add_u32 s56, s56, 0x10000
	s_addc_u32 s57, s57, 0
	global_load_dwordx4 v[172:175], v240, s[56:57]
	s_add_u32 s56, s56, 0x10000
	s_addc_u32 s57, s57, 0
	global_load_dwordx4 v[176:179], v240, s[56:57]
	s_add_u32 s56, s56, 0x10000
	s_addc_u32 s57, s57, 0
	global_load_dwordx4 v[180:183], v240, s[56:57]
	s_add_u32 s56, s56, 0x10000
	s_addc_u32 s57, s57, 0
	global_load_dwordx4 v[184:187], v240, s[56:57]
	s_add_u32 s56, s56, 0x10000
	s_addc_u32 s57, s57, 0
	global_load_dwordx4 v[188:191], v240, s[56:57]
	s_add_u32 s56, s56, 0x10000
	s_addc_u32 s57, s57, 0
	global_load_dwordx4 v[196:199], v240, s[56:57]
	s_add_u32 s56, s56, 0x10000
	s_addc_u32 s57, s57, 0
	global_load_dwordx4 v[200:203], v240, s[56:57]
	s_add_u32 s56, s56, 0x10000
	s_addc_u32 s57, s57, 0
	global_load_dwordx4 v[204:207], v240, s[56:57]
	s_add_u32 s56, s56, 0x10000
	s_addc_u32 s57, s57, 0
	global_load_dwordx4 v[212:215], v240, s[56:57]
	s_add_u32 s56, s56, 0x10000
	s_addc_u32 s57, s57, 0
	global_load_dwordx4 v[216:219], v240, s[56:57]
	s_add_u32 s56, s56, 0x10000
	s_addc_u32 s57, s57, 0
	global_load_dwordx4 v[220:223], v240, s[56:57]
	s_add_u32 s56, s56, 0x10000
	s_addc_u32 s57, s57, 0
	global_load_dwordx4 v[224:227], v240, s[56:57]
	ds_write_b32 v238, v2
	ds_write_b32 v238, v3 offset:528
	ds_write_b32 v238, v4 offset:1056
	ds_write_b32 v238, v5 offset:1584
	ds_write_b32 v238, v6 offset:64
	ds_write_b32 v238, v7 offset:592
	ds_write_b32 v238, v8 offset:1120
	ds_write_b32 v238, v9 offset:1648
	ds_write_b32 v238, v10 offset:128
	ds_write_b32 v238, v11 offset:656
	ds_write_b32 v238, v12 offset:1184
	ds_write_b32 v238, v13 offset:1712
	ds_write_b32 v238, v14 offset:192
	ds_write_b32 v238, v15 offset:720
	ds_write_b32 v238, v16 offset:1248
	ds_write_b32 v238, v17 offset:1776
	ds_write_b32 v238, v18 offset:8448
	ds_write_b32 v238, v19 offset:8976
	ds_write_b32 v238, v20 offset:9504
	ds_write_b32 v238, v21 offset:10032
	ds_write_b32 v238, v22 offset:8512
	ds_write_b32 v238, v23 offset:9040
	ds_write_b32 v238, v24 offset:9568
	ds_write_b32 v238, v25 offset:10096
	ds_write_b32 v238, v26 offset:8576
	ds_write_b32 v238, v27 offset:9104
	ds_write_b32 v238, v28 offset:9632
	ds_write_b32 v238, v29 offset:10160
	ds_write_b32 v238, v30 offset:8640
	ds_write_b32 v238, v31 offset:9168
	ds_write_b32 v238, v32 offset:9696
	ds_write_b32 v238, v33 offset:10224
	ds_write_b32 v238, v34 offset:16896
	ds_write_b32 v238, v35 offset:17424
	ds_write_b32 v238, v36 offset:17952
	ds_write_b32 v238, v37 offset:18480
	ds_write_b32 v238, v38 offset:16960
	ds_write_b32 v238, v39 offset:17488
	ds_write_b32 v238, v40 offset:18016
	ds_write_b32 v238, v41 offset:18544
	ds_write_b32 v238, v42 offset:17024
	ds_write_b32 v238, v43 offset:17552
	ds_write_b32 v238, v44 offset:18080
	ds_write_b32 v238, v45 offset:18608
	ds_write_b32 v238, v46 offset:17088
	ds_write_b32 v238, v47 offset:17616
	ds_write_b32 v238, v48 offset:18144
	ds_write_b32 v238, v49 offset:18672
	ds_write_b32 v238, v50 offset:25344
	ds_write_b32 v238, v51 offset:25872
	ds_write_b32 v238, v52 offset:26400
	ds_write_b32 v238, v53 offset:26928
	ds_write_b32 v238, v54 offset:25408
	ds_write_b32 v238, v55 offset:25936
	ds_write_b32 v238, v56 offset:26464
	ds_write_b32 v238, v57 offset:26992
	ds_write_b32 v238, v58 offset:25472
	ds_write_b32 v238, v59 offset:26000
	ds_write_b32 v238, v60 offset:26528
	ds_write_b32 v238, v61 offset:27056
	ds_write_b32 v238, v62 offset:25536
	ds_write_b32 v238, v63 offset:26064
	ds_write_b32 v238, v64 offset:26592
	ds_write_b32 v238, v65 offset:27120
	s_waitcnt lgkmcnt(0)
	s_barrier
	ds_read_b128 v[2:5], v239
	ds_read_b128 v[6:9], v239 offset:4224
	ds_read_b128 v[10:13], v239 offset:8448
	ds_read_b128 v[14:17], v239 offset:12672
	ds_read_b128 v[18:21], v239 offset:16896
	ds_read_b128 v[22:25], v239 offset:21120
	ds_read_b128 v[26:29], v239 offset:25344
	ds_read_b128 v[30:33], v239 offset:29568
	ds_read_b128 v[34:37], v239 offset:33792
	ds_read_b128 v[38:41], v239 offset:38016
	ds_read_b128 v[42:45], v239 offset:42240
	ds_read_b128 v[46:49], v239 offset:46464
	ds_read_b128 v[50:53], v239 offset:50688
	ds_read_b128 v[54:57], v239 offset:54912
	ds_read_b128 v[58:61], v239 offset:59136
	ds_read_b128 v[62:65], v239 offset:63360
	s_waitcnt vmcnt(15) lgkmcnt(15)
	v_pk_add_f32 v[2:3], v[2:3], v[136:137]
	v_pk_add_f32 v[4:5], v[4:5], v[138:139]
	v_cvt_pk_bf16_f32 v136, v2, v3
	v_cvt_pk_bf16_f32 v137, v4, v5
	v_mul_f32_e32 v138, v2, v2
	v_fmac_f32_e32 v138, v3, v3
	v_fmac_f32_e32 v138, v4, v4
	v_fmac_f32_e32 v138, v5, v5
	s_waitcnt vmcnt(14) lgkmcnt(14)
	v_pk_add_f32 v[6:7], v[6:7], v[140:141]
	v_pk_add_f32 v[8:9], v[8:9], v[142:143]
	v_cvt_pk_bf16_f32 v140, v6, v7
	v_cvt_pk_bf16_f32 v141, v8, v9
	v_mul_f32_e32 v142, v6, v6
	v_fmac_f32_e32 v142, v7, v7
	v_fmac_f32_e32 v142, v8, v8
	v_fmac_f32_e32 v142, v9, v9
	s_waitcnt vmcnt(13) lgkmcnt(13)
	v_pk_add_f32 v[10:11], v[10:11], v[144:145]
	v_pk_add_f32 v[12:13], v[12:13], v[146:147]
	v_cvt_pk_bf16_f32 v144, v10, v11
	v_cvt_pk_bf16_f32 v145, v12, v13
	v_mul_f32_e32 v146, v10, v10
	v_fmac_f32_e32 v146, v11, v11
	v_fmac_f32_e32 v146, v12, v12
	v_fmac_f32_e32 v146, v13, v13
	s_waitcnt vmcnt(12) lgkmcnt(12)
	v_pk_add_f32 v[14:15], v[14:15], v[148:149]
	v_pk_add_f32 v[16:17], v[16:17], v[150:151]
	v_cvt_pk_bf16_f32 v148, v14, v15
	v_cvt_pk_bf16_f32 v149, v16, v17
	v_mul_f32_e32 v150, v14, v14
	v_fmac_f32_e32 v150, v15, v15
	v_fmac_f32_e32 v150, v16, v16
	v_fmac_f32_e32 v150, v17, v17
	s_waitcnt vmcnt(11) lgkmcnt(11)
	v_pk_add_f32 v[18:19], v[18:19], v[172:173]
	v_pk_add_f32 v[20:21], v[20:21], v[174:175]
	v_cvt_pk_bf16_f32 v172, v18, v19
	v_cvt_pk_bf16_f32 v173, v20, v21
	v_mul_f32_e32 v174, v18, v18
	v_fmac_f32_e32 v174, v19, v19
	v_fmac_f32_e32 v174, v20, v20
	v_fmac_f32_e32 v174, v21, v21
	s_waitcnt vmcnt(10) lgkmcnt(10)
	v_pk_add_f32 v[22:23], v[22:23], v[176:177]
	v_pk_add_f32 v[24:25], v[24:25], v[178:179]
	v_cvt_pk_bf16_f32 v176, v22, v23
	v_cvt_pk_bf16_f32 v177, v24, v25
	v_mul_f32_e32 v178, v22, v22
	v_fmac_f32_e32 v178, v23, v23
	v_fmac_f32_e32 v178, v24, v24
	v_fmac_f32_e32 v178, v25, v25
	s_waitcnt vmcnt(9) lgkmcnt(9)
	v_pk_add_f32 v[26:27], v[26:27], v[180:181]
	v_pk_add_f32 v[28:29], v[28:29], v[182:183]
	v_cvt_pk_bf16_f32 v180, v26, v27
	v_cvt_pk_bf16_f32 v181, v28, v29
	v_mul_f32_e32 v182, v26, v26
	v_fmac_f32_e32 v182, v27, v27
	v_fmac_f32_e32 v182, v28, v28
	v_fmac_f32_e32 v182, v29, v29
	s_waitcnt vmcnt(8) lgkmcnt(8)
	v_pk_add_f32 v[30:31], v[30:31], v[184:185]
	v_pk_add_f32 v[32:33], v[32:33], v[186:187]
	v_cvt_pk_bf16_f32 v184, v30, v31
	v_cvt_pk_bf16_f32 v185, v32, v33
	v_mul_f32_e32 v186, v30, v30
	v_fmac_f32_e32 v186, v31, v31
	v_fmac_f32_e32 v186, v32, v32
	v_fmac_f32_e32 v186, v33, v33
	s_waitcnt vmcnt(7) lgkmcnt(7)
	v_pk_add_f32 v[34:35], v[34:35], v[188:189]
	v_pk_add_f32 v[36:37], v[36:37], v[190:191]
	v_cvt_pk_bf16_f32 v188, v34, v35
	v_cvt_pk_bf16_f32 v189, v36, v37
	v_mul_f32_e32 v190, v34, v34
	v_fmac_f32_e32 v190, v35, v35
	v_fmac_f32_e32 v190, v36, v36
	v_fmac_f32_e32 v190, v37, v37
	s_waitcnt vmcnt(6) lgkmcnt(6)
	v_pk_add_f32 v[38:39], v[38:39], v[196:197]
	v_pk_add_f32 v[40:41], v[40:41], v[198:199]
	v_cvt_pk_bf16_f32 v196, v38, v39
	v_cvt_pk_bf16_f32 v197, v40, v41
	v_mul_f32_e32 v198, v38, v38
	v_fmac_f32_e32 v198, v39, v39
	v_fmac_f32_e32 v198, v40, v40
	v_fmac_f32_e32 v198, v41, v41
	s_waitcnt vmcnt(5) lgkmcnt(5)
	v_pk_add_f32 v[42:43], v[42:43], v[200:201]
	v_pk_add_f32 v[44:45], v[44:45], v[202:203]
	v_cvt_pk_bf16_f32 v200, v42, v43
	v_cvt_pk_bf16_f32 v201, v44, v45
	v_mul_f32_e32 v202, v42, v42
	v_fmac_f32_e32 v202, v43, v43
	v_fmac_f32_e32 v202, v44, v44
	v_fmac_f32_e32 v202, v45, v45
	s_waitcnt vmcnt(4) lgkmcnt(4)
	v_pk_add_f32 v[46:47], v[46:47], v[204:205]
	v_pk_add_f32 v[48:49], v[48:49], v[206:207]
	v_cvt_pk_bf16_f32 v204, v46, v47
	v_cvt_pk_bf16_f32 v205, v48, v49
	v_mul_f32_e32 v206, v46, v46
	v_fmac_f32_e32 v206, v47, v47
	v_fmac_f32_e32 v206, v48, v48
	v_fmac_f32_e32 v206, v49, v49
	s_waitcnt vmcnt(3) lgkmcnt(3)
	v_pk_add_f32 v[50:51], v[50:51], v[212:213]
	v_pk_add_f32 v[52:53], v[52:53], v[214:215]
	v_cvt_pk_bf16_f32 v212, v50, v51
	v_cvt_pk_bf16_f32 v213, v52, v53
	v_mul_f32_e32 v214, v50, v50
	v_fmac_f32_e32 v214, v51, v51
	v_fmac_f32_e32 v214, v52, v52
	v_fmac_f32_e32 v214, v53, v53
	s_waitcnt vmcnt(2) lgkmcnt(2)
	v_pk_add_f32 v[54:55], v[54:55], v[216:217]
	v_pk_add_f32 v[56:57], v[56:57], v[218:219]
	v_cvt_pk_bf16_f32 v216, v54, v55
	v_cvt_pk_bf16_f32 v217, v56, v57
	v_mul_f32_e32 v218, v54, v54
	v_fmac_f32_e32 v218, v55, v55
	v_fmac_f32_e32 v218, v56, v56
	v_fmac_f32_e32 v218, v57, v57
	s_waitcnt vmcnt(1) lgkmcnt(1)
	v_pk_add_f32 v[58:59], v[58:59], v[220:221]
	v_pk_add_f32 v[60:61], v[60:61], v[222:223]
	v_cvt_pk_bf16_f32 v220, v58, v59
	v_cvt_pk_bf16_f32 v221, v60, v61
	v_mul_f32_e32 v222, v58, v58
	v_fmac_f32_e32 v222, v59, v59
	v_fmac_f32_e32 v222, v60, v60
	v_fmac_f32_e32 v222, v61, v61
	s_waitcnt vmcnt(0) lgkmcnt(0)
	v_pk_add_f32 v[62:63], v[62:63], v[224:225]
	v_pk_add_f32 v[64:65], v[64:65], v[226:227]
	v_cvt_pk_bf16_f32 v224, v62, v63
	v_cvt_pk_bf16_f32 v225, v64, v65
	v_mul_f32_e32 v226, v62, v62
	v_fmac_f32_e32 v226, v63, v63
	v_fmac_f32_e32 v226, v64, v64
	v_fmac_f32_e32 v226, v65, v65
	s_mov_b32 s56, s58
	s_mov_b32 s57, s59
	s_mov_b32 s40, s46
	s_mov_b32 s41, s47
	global_store_dwordx4 v240, v[2:5], s[56:57]
	global_store_dwordx2 v244, v[136:137], s[40:41]
	s_add_u32 s56, s56, 0x10000
	s_addc_u32 s57, s57, 0
	s_add_u32 s40, s40, 0x8400
	s_addc_u32 s41, s41, 0
	global_store_dwordx4 v240, v[6:9], s[56:57]
	global_store_dwordx2 v244, v[140:141], s[40:41]
	s_add_u32 s56, s56, 0x10000
	s_addc_u32 s57, s57, 0
	s_add_u32 s40, s40, 0x8400
	s_addc_u32 s41, s41, 0
	global_store_dwordx4 v240, v[10:13], s[56:57]
	global_store_dwordx2 v244, v[144:145], s[40:41]
	s_add_u32 s56, s56, 0x10000
	s_addc_u32 s57, s57, 0
	s_add_u32 s40, s40, 0x8400
	s_addc_u32 s41, s41, 0
	global_store_dwordx4 v240, v[14:17], s[56:57]
	global_store_dwordx2 v244, v[148:149], s[40:41]
	s_add_u32 s56, s56, 0x10000
	s_addc_u32 s57, s57, 0
	s_add_u32 s40, s40, 0x8400
	s_addc_u32 s41, s41, 0
	global_store_dwordx4 v240, v[18:21], s[56:57]
	global_store_dwordx2 v244, v[172:173], s[40:41]
	s_add_u32 s56, s56, 0x10000
	s_addc_u32 s57, s57, 0
	s_add_u32 s40, s40, 0x8400
	s_addc_u32 s41, s41, 0
	global_store_dwordx4 v240, v[22:25], s[56:57]
	global_store_dwordx2 v244, v[176:177], s[40:41]
	s_add_u32 s56, s56, 0x10000
	s_addc_u32 s57, s57, 0
	s_add_u32 s40, s40, 0x8400
	s_addc_u32 s41, s41, 0
	global_store_dwordx4 v240, v[26:29], s[56:57]
	global_store_dwordx2 v244, v[180:181], s[40:41]
	s_add_u32 s56, s56, 0x10000
	s_addc_u32 s57, s57, 0
	s_add_u32 s40, s40, 0x8400
	s_addc_u32 s41, s41, 0
	global_store_dwordx4 v240, v[30:33], s[56:57]
	global_store_dwordx2 v244, v[184:185], s[40:41]
	s_add_u32 s56, s56, 0x10000
	s_addc_u32 s57, s57, 0
	s_add_u32 s40, s40, 0x8400
	s_addc_u32 s41, s41, 0
	global_store_dwordx4 v240, v[34:37], s[56:57]
	global_store_dwordx2 v244, v[188:189], s[40:41]
	s_add_u32 s56, s56, 0x10000
	s_addc_u32 s57, s57, 0
	s_add_u32 s40, s40, 0x8400
	s_addc_u32 s41, s41, 0
	global_store_dwordx4 v240, v[38:41], s[56:57]
	global_store_dwordx2 v244, v[196:197], s[40:41]
	s_add_u32 s56, s56, 0x10000
	s_addc_u32 s57, s57, 0
	s_add_u32 s40, s40, 0x8400
	s_addc_u32 s41, s41, 0
	global_store_dwordx4 v240, v[42:45], s[56:57]
	global_store_dwordx2 v244, v[200:201], s[40:41]
	s_add_u32 s56, s56, 0x10000
	s_addc_u32 s57, s57, 0
	s_add_u32 s40, s40, 0x8400
	s_addc_u32 s41, s41, 0
	global_store_dwordx4 v240, v[46:49], s[56:57]
	global_store_dwordx2 v244, v[204:205], s[40:41]
	s_add_u32 s56, s56, 0x10000
	s_addc_u32 s57, s57, 0
	s_add_u32 s40, s40, 0x8400
	s_addc_u32 s41, s41, 0
	global_store_dwordx4 v240, v[50:53], s[56:57]
	global_store_dwordx2 v244, v[212:213], s[40:41]
	s_add_u32 s56, s56, 0x10000
	s_addc_u32 s57, s57, 0
	s_add_u32 s40, s40, 0x8400
	s_addc_u32 s41, s41, 0
	global_store_dwordx4 v240, v[54:57], s[56:57]
	global_store_dwordx2 v244, v[216:217], s[40:41]
	s_add_u32 s56, s56, 0x10000
	s_addc_u32 s57, s57, 0
	s_add_u32 s40, s40, 0x8400
	s_addc_u32 s41, s41, 0
	global_store_dwordx4 v240, v[58:61], s[56:57]
	global_store_dwordx2 v244, v[220:221], s[40:41]
	s_add_u32 s56, s56, 0x10000
	s_addc_u32 s57, s57, 0
	s_add_u32 s40, s40, 0x8400
	s_addc_u32 s41, s41, 0
	global_store_dwordx4 v240, v[62:65], s[56:57]
	global_store_dwordx2 v244, v[224:225], s[40:41]
	v_add_f32_dpp v138, v138, v138 quad_perm:[1,0,3,2] row_mask:0xf bank_mask:0xf
	v_add_f32_dpp v142, v142, v142 quad_perm:[1,0,3,2] row_mask:0xf bank_mask:0xf
	v_add_f32_dpp v146, v146, v146 quad_perm:[1,0,3,2] row_mask:0xf bank_mask:0xf
	v_add_f32_dpp v150, v150, v150 quad_perm:[1,0,3,2] row_mask:0xf bank_mask:0xf
	v_add_f32_dpp v174, v174, v174 quad_perm:[1,0,3,2] row_mask:0xf bank_mask:0xf
	v_add_f32_dpp v178, v178, v178 quad_perm:[1,0,3,2] row_mask:0xf bank_mask:0xf
	v_add_f32_dpp v182, v182, v182 quad_perm:[1,0,3,2] row_mask:0xf bank_mask:0xf
	v_add_f32_dpp v186, v186, v186 quad_perm:[1,0,3,2] row_mask:0xf bank_mask:0xf
	v_add_f32_dpp v190, v190, v190 quad_perm:[1,0,3,2] row_mask:0xf bank_mask:0xf
	v_add_f32_dpp v198, v198, v198 quad_perm:[1,0,3,2] row_mask:0xf bank_mask:0xf
	v_add_f32_dpp v202, v202, v202 quad_perm:[1,0,3,2] row_mask:0xf bank_mask:0xf
	v_add_f32_dpp v206, v206, v206 quad_perm:[1,0,3,2] row_mask:0xf bank_mask:0xf
	v_add_f32_dpp v214, v214, v214 quad_perm:[1,0,3,2] row_mask:0xf bank_mask:0xf
	v_add_f32_dpp v218, v218, v218 quad_perm:[1,0,3,2] row_mask:0xf bank_mask:0xf
	v_add_f32_dpp v222, v222, v222 quad_perm:[1,0,3,2] row_mask:0xf bank_mask:0xf
	v_add_f32_dpp v226, v226, v226 quad_perm:[1,0,3,2] row_mask:0xf bank_mask:0xf
	v_add_f32_dpp v138, v138, v138 quad_perm:[2,3,0,1] row_mask:0xf bank_mask:0xf
	v_add_f32_dpp v142, v142, v142 quad_perm:[2,3,0,1] row_mask:0xf bank_mask:0xf
	v_add_f32_dpp v146, v146, v146 quad_perm:[2,3,0,1] row_mask:0xf bank_mask:0xf
	v_add_f32_dpp v150, v150, v150 quad_perm:[2,3,0,1] row_mask:0xf bank_mask:0xf
	v_add_f32_dpp v174, v174, v174 quad_perm:[2,3,0,1] row_mask:0xf bank_mask:0xf
	v_add_f32_dpp v178, v178, v178 quad_perm:[2,3,0,1] row_mask:0xf bank_mask:0xf
	v_add_f32_dpp v182, v182, v182 quad_perm:[2,3,0,1] row_mask:0xf bank_mask:0xf
	v_add_f32_dpp v186, v186, v186 quad_perm:[2,3,0,1] row_mask:0xf bank_mask:0xf
	v_add_f32_dpp v190, v190, v190 quad_perm:[2,3,0,1] row_mask:0xf bank_mask:0xf
	v_add_f32_dpp v198, v198, v198 quad_perm:[2,3,0,1] row_mask:0xf bank_mask:0xf
	v_add_f32_dpp v202, v202, v202 quad_perm:[2,3,0,1] row_mask:0xf bank_mask:0xf
	v_add_f32_dpp v206, v206, v206 quad_perm:[2,3,0,1] row_mask:0xf bank_mask:0xf
	v_add_f32_dpp v214, v214, v214 quad_perm:[2,3,0,1] row_mask:0xf bank_mask:0xf
	v_add_f32_dpp v218, v218, v218 quad_perm:[2,3,0,1] row_mask:0xf bank_mask:0xf
	v_add_f32_dpp v222, v222, v222 quad_perm:[2,3,0,1] row_mask:0xf bank_mask:0xf
	v_add_f32_dpp v226, v226, v226 quad_perm:[2,3,0,1] row_mask:0xf bank_mask:0xf
	v_add_f32_dpp v138, v138, v138 row_half_mirror row_mask:0xf bank_mask:0xf
	v_add_f32_dpp v142, v142, v142 row_half_mirror row_mask:0xf bank_mask:0xf
	v_add_f32_dpp v146, v146, v146 row_half_mirror row_mask:0xf bank_mask:0xf
	v_add_f32_dpp v150, v150, v150 row_half_mirror row_mask:0xf bank_mask:0xf
	v_add_f32_dpp v174, v174, v174 row_half_mirror row_mask:0xf bank_mask:0xf
	v_add_f32_dpp v178, v178, v178 row_half_mirror row_mask:0xf bank_mask:0xf
	v_add_f32_dpp v182, v182, v182 row_half_mirror row_mask:0xf bank_mask:0xf
	v_add_f32_dpp v186, v186, v186 row_half_mirror row_mask:0xf bank_mask:0xf
	v_add_f32_dpp v190, v190, v190 row_half_mirror row_mask:0xf bank_mask:0xf
	v_add_f32_dpp v198, v198, v198 row_half_mirror row_mask:0xf bank_mask:0xf
	v_add_f32_dpp v202, v202, v202 row_half_mirror row_mask:0xf bank_mask:0xf
	v_add_f32_dpp v206, v206, v206 row_half_mirror row_mask:0xf bank_mask:0xf
	v_add_f32_dpp v214, v214, v214 row_half_mirror row_mask:0xf bank_mask:0xf
	v_add_f32_dpp v218, v218, v218 row_half_mirror row_mask:0xf bank_mask:0xf
	v_add_f32_dpp v222, v222, v222 row_half_mirror row_mask:0xf bank_mask:0xf
	v_add_f32_dpp v226, v226, v226 row_half_mirror row_mask:0xf bank_mask:0xf
	v_add_f32_dpp v138, v138, v138 row_mirror row_mask:0xf bank_mask:0xf
	v_add_f32_dpp v142, v142, v142 row_mirror row_mask:0xf bank_mask:0xf
	v_add_f32_dpp v146, v146, v146 row_mirror row_mask:0xf bank_mask:0xf
	v_add_f32_dpp v150, v150, v150 row_mirror row_mask:0xf bank_mask:0xf
	v_add_f32_dpp v174, v174, v174 row_mirror row_mask:0xf bank_mask:0xf
	v_add_f32_dpp v178, v178, v178 row_mirror row_mask:0xf bank_mask:0xf
	v_add_f32_dpp v182, v182, v182 row_mirror row_mask:0xf bank_mask:0xf
	v_add_f32_dpp v186, v186, v186 row_mirror row_mask:0xf bank_mask:0xf
	v_add_f32_dpp v190, v190, v190 row_mirror row_mask:0xf bank_mask:0xf
	v_add_f32_dpp v198, v198, v198 row_mirror row_mask:0xf bank_mask:0xf
	v_add_f32_dpp v202, v202, v202 row_mirror row_mask:0xf bank_mask:0xf
	v_add_f32_dpp v206, v206, v206 row_mirror row_mask:0xf bank_mask:0xf
	v_add_f32_dpp v214, v214, v214 row_mirror row_mask:0xf bank_mask:0xf
	v_add_f32_dpp v218, v218, v218 row_mirror row_mask:0xf bank_mask:0xf
	v_add_f32_dpp v222, v222, v222 row_mirror row_mask:0xf bank_mask:0xf
	v_add_f32_dpp v226, v226, v226 row_mirror row_mask:0xf bank_mask:0xf
	v_add_f32_dpp v138, v138, v138 row_bcast:15 row_mask:0xa bank_mask:0xf
	v_add_f32_dpp v142, v142, v142 row_bcast:15 row_mask:0xa bank_mask:0xf
	v_add_f32_dpp v146, v146, v146 row_bcast:15 row_mask:0xa bank_mask:0xf
	v_add_f32_dpp v150, v150, v150 row_bcast:15 row_mask:0xa bank_mask:0xf
	v_add_f32_dpp v174, v174, v174 row_bcast:15 row_mask:0xa bank_mask:0xf
	v_add_f32_dpp v178, v178, v178 row_bcast:15 row_mask:0xa bank_mask:0xf
	v_add_f32_dpp v182, v182, v182 row_bcast:15 row_mask:0xa bank_mask:0xf
	v_add_f32_dpp v186, v186, v186 row_bcast:15 row_mask:0xa bank_mask:0xf
	v_add_f32_dpp v190, v190, v190 row_bcast:15 row_mask:0xa bank_mask:0xf
	v_add_f32_dpp v198, v198, v198 row_bcast:15 row_mask:0xa bank_mask:0xf
	v_add_f32_dpp v202, v202, v202 row_bcast:15 row_mask:0xa bank_mask:0xf
	v_add_f32_dpp v206, v206, v206 row_bcast:15 row_mask:0xa bank_mask:0xf
	v_add_f32_dpp v214, v214, v214 row_bcast:15 row_mask:0xa bank_mask:0xf
	v_add_f32_dpp v218, v218, v218 row_bcast:15 row_mask:0xa bank_mask:0xf
	v_add_f32_dpp v222, v222, v222 row_bcast:15 row_mask:0xa bank_mask:0xf
	v_add_f32_dpp v226, v226, v226 row_bcast:15 row_mask:0xa bank_mask:0xf
	s_mov_b32 exec_lo, 0x10000
	s_mov_b32 exec_hi, 0x10000
	global_atomic_add_f32 v245, v138, s[48:49]
	global_atomic_add_f32 v245, v142, s[48:49] offset:32
	global_atomic_add_f32 v245, v146, s[48:49] offset:64
	global_atomic_add_f32 v245, v150, s[48:49] offset:96
	global_atomic_add_f32 v245, v174, s[48:49] offset:128
	global_atomic_add_f32 v245, v178, s[48:49] offset:160
	global_atomic_add_f32 v245, v182, s[48:49] offset:192
	global_atomic_add_f32 v245, v186, s[48:49] offset:224
	global_atomic_add_f32 v245, v190, s[48:49] offset:256
	global_atomic_add_f32 v245, v198, s[48:49] offset:288
	global_atomic_add_f32 v245, v202, s[48:49] offset:320
	global_atomic_add_f32 v245, v206, s[48:49] offset:352
	global_atomic_add_f32 v245, v214, s[48:49] offset:384
	global_atomic_add_f32 v245, v218, s[48:49] offset:416
	global_atomic_add_f32 v245, v222, s[48:49] offset:448
	global_atomic_add_f32 v245, v226, s[48:49] offset:480
	s_mov_b64 exec, -1
	s_add_u32 s44, s44, 0x1000
	s_addc_u32 s45, s45, 0
	s_add_u32 s58, s58, 0x1000
	s_addc_u32 s59, s59, 0
	s_add_u32 s46, s46, 0x800
	s_addc_u32 s47, s47, 0
	s_waitcnt lgkmcnt(0)
	s_barrier
	s_mov_b32 s56, s44
	s_mov_b32 s57, s45
	global_load_dwordx4 v[136:139], v240, s[56:57]
	s_add_u32 s56, s56, 0x10000
	s_addc_u32 s57, s57, 0
	global_load_dwordx4 v[140:143], v240, s[56:57]
	s_add_u32 s56, s56, 0x10000
	s_addc_u32 s57, s57, 0
	global_load_dwordx4 v[144:147], v240, s[56:57]
	s_add_u32 s56, s56, 0x10000
	s_addc_u32 s57, s57, 0
	global_load_dwordx4 v[148:151], v240, s[56:57]
	s_add_u32 s56, s56, 0x10000
	s_addc_u32 s57, s57, 0
	global_load_dwordx4 v[172:175], v240, s[56:57]
	s_add_u32 s56, s56, 0x10000
	s_addc_u32 s57, s57, 0
	global_load_dwordx4 v[176:179], v240, s[56:57]
	s_add_u32 s56, s56, 0x10000
	s_addc_u32 s57, s57, 0
	global_load_dwordx4 v[180:183], v240, s[56:57]
	s_add_u32 s56, s56, 0x10000
	s_addc_u32 s57, s57, 0
	global_load_dwordx4 v[184:187], v240, s[56:57]
	s_add_u32 s56, s56, 0x10000
	s_addc_u32 s57, s57, 0
	global_load_dwordx4 v[188:191], v240, s[56:57]
	s_add_u32 s56, s56, 0x10000
	s_addc_u32 s57, s57, 0
	global_load_dwordx4 v[196:199], v240, s[56:57]
	s_add_u32 s56, s56, 0x10000
	s_addc_u32 s57, s57, 0
	global_load_dwordx4 v[200:203], v240, s[56:57]
	s_add_u32 s56, s56, 0x10000
	s_addc_u32 s57, s57, 0
	global_load_dwordx4 v[204:207], v240, s[56:57]
	s_add_u32 s56, s56, 0x10000
	s_addc_u32 s57, s57, 0
	global_load_dwordx4 v[212:215], v240, s[56:57]
	s_add_u32 s56, s56, 0x10000
	s_addc_u32 s57, s57, 0
	global_load_dwordx4 v[216:219], v240, s[56:57]
	s_add_u32 s56, s56, 0x10000
	s_addc_u32 s57, s57, 0
	global_load_dwordx4 v[220:223], v240, s[56:57]
	s_add_u32 s56, s56, 0x10000
	s_addc_u32 s57, s57, 0
	global_load_dwordx4 v[224:227], v240, s[56:57]
	ds_write_b32 v238, v66
	ds_write_b32 v238, v67 offset:528
	ds_write_b32 v238, v68 offset:1056
	ds_write_b32 v238, v69 offset:1584
	ds_write_b32 v238, v70 offset:64
	ds_write_b32 v238, v71 offset:592
	ds_write_b32 v238, v72 offset:1120
	ds_write_b32 v238, v73 offset:1648
	ds_write_b32 v238, v74 offset:128
	ds_write_b32 v238, v75 offset:656
	ds_write_b32 v238, v76 offset:1184
	ds_write_b32 v238, v77 offset:1712
	ds_write_b32 v238, v78 offset:192
	ds_write_b32 v238, v79 offset:720
	ds_write_b32 v238, v80 offset:1248
	ds_write_b32 v238, v81 offset:1776
	ds_write_b32 v238, v82 offset:8448
	ds_write_b32 v238, v83 offset:8976
	ds_write_b32 v238, v84 offset:9504
	ds_write_b32 v238, v85 offset:10032
	ds_write_b32 v238, v86 offset:8512
	ds_write_b32 v238, v87 offset:9040
	ds_write_b32 v238, v88 offset:9568
	ds_write_b32 v238, v89 offset:10096
	ds_write_b32 v238, v90 offset:8576
	ds_write_b32 v238, v91 offset:9104
	ds_write_b32 v238, v92 offset:9632
	ds_write_b32 v238, v93 offset:10160
	ds_write_b32 v238, v94 offset:8640
	ds_write_b32 v238, v95 offset:9168
	ds_write_b32 v238, v96 offset:9696
	ds_write_b32 v238, v97 offset:10224
	ds_write_b32 v238, v98 offset:16896
	ds_write_b32 v238, v99 offset:17424
	ds_write_b32 v238, v100 offset:17952
	ds_write_b32 v238, v101 offset:18480
	ds_write_b32 v238, v102 offset:16960
	ds_write_b32 v238, v103 offset:17488
	ds_write_b32 v238, v104 offset:18016
	ds_write_b32 v238, v105 offset:18544
	ds_write_b32 v238, v106 offset:17024
	ds_write_b32 v238, v107 offset:17552
	ds_write_b32 v238, v108 offset:18080
	ds_write_b32 v238, v109 offset:18608
	ds_write_b32 v238, v110 offset:17088
	ds_write_b32 v238, v111 offset:17616
	ds_write_b32 v238, v112 offset:18144
	ds_write_b32 v238, v113 offset:18672
	ds_write_b32 v238, v114 offset:25344
	ds_write_b32 v238, v115 offset:25872
	ds_write_b32 v238, v116 offset:26400
	ds_write_b32 v238, v117 offset:26928
	ds_write_b32 v238, v118 offset:25408
	ds_write_b32 v238, v119 offset:25936
	ds_write_b32 v238, v120 offset:26464
	ds_write_b32 v238, v121 offset:26992
	ds_write_b32 v238, v122 offset:25472
	ds_write_b32 v238, v123 offset:26000
	ds_write_b32 v238, v124 offset:26528
	ds_write_b32 v238, v125 offset:27056
	ds_write_b32 v238, v126 offset:25536
	ds_write_b32 v238, v127 offset:26064
	ds_write_b32 v238, v128 offset:26592
	ds_write_b32 v238, v129 offset:27120
	s_waitcnt lgkmcnt(0)
	s_barrier
	ds_read_b128 v[66:69], v239
	ds_read_b128 v[70:73], v239 offset:4224
	ds_read_b128 v[74:77], v239 offset:8448
	ds_read_b128 v[78:81], v239 offset:12672
	ds_read_b128 v[82:85], v239 offset:16896
	ds_read_b128 v[86:89], v239 offset:21120
	ds_read_b128 v[90:93], v239 offset:25344
	ds_read_b128 v[94:97], v239 offset:29568
	ds_read_b128 v[98:101], v239 offset:33792
	ds_read_b128 v[102:105], v239 offset:38016
	ds_read_b128 v[106:109], v239 offset:42240
	ds_read_b128 v[110:113], v239 offset:46464
	ds_read_b128 v[114:117], v239 offset:50688
	ds_read_b128 v[118:121], v239 offset:54912
	ds_read_b128 v[122:125], v239 offset:59136
	ds_read_b128 v[126:129], v239 offset:63360
	s_waitcnt vmcnt(15) lgkmcnt(15)
	v_pk_add_f32 v[66:67], v[66:67], v[136:137]
	v_pk_add_f32 v[68:69], v[68:69], v[138:139]
	v_cvt_pk_bf16_f32 v136, v66, v67
	v_cvt_pk_bf16_f32 v137, v68, v69
	v_mul_f32_e32 v138, v66, v66
	v_fmac_f32_e32 v138, v67, v67
	v_fmac_f32_e32 v138, v68, v68
	v_fmac_f32_e32 v138, v69, v69
	s_waitcnt vmcnt(14) lgkmcnt(14)
	v_pk_add_f32 v[70:71], v[70:71], v[140:141]
	v_pk_add_f32 v[72:73], v[72:73], v[142:143]
	v_cvt_pk_bf16_f32 v140, v70, v71
	v_cvt_pk_bf16_f32 v141, v72, v73
	v_mul_f32_e32 v142, v70, v70
	v_fmac_f32_e32 v142, v71, v71
	v_fmac_f32_e32 v142, v72, v72
	v_fmac_f32_e32 v142, v73, v73
	s_waitcnt vmcnt(13) lgkmcnt(13)
	v_pk_add_f32 v[74:75], v[74:75], v[144:145]
	v_pk_add_f32 v[76:77], v[76:77], v[146:147]
	v_cvt_pk_bf16_f32 v144, v74, v75
	v_cvt_pk_bf16_f32 v145, v76, v77
	v_mul_f32_e32 v146, v74, v74
	v_fmac_f32_e32 v146, v75, v75
	v_fmac_f32_e32 v146, v76, v76
	v_fmac_f32_e32 v146, v77, v77
	s_waitcnt vmcnt(12) lgkmcnt(12)
	v_pk_add_f32 v[78:79], v[78:79], v[148:149]
	v_pk_add_f32 v[80:81], v[80:81], v[150:151]
	v_cvt_pk_bf16_f32 v148, v78, v79
	v_cvt_pk_bf16_f32 v149, v80, v81
	v_mul_f32_e32 v150, v78, v78
	v_fmac_f32_e32 v150, v79, v79
	v_fmac_f32_e32 v150, v80, v80
	v_fmac_f32_e32 v150, v81, v81
	s_waitcnt vmcnt(11) lgkmcnt(11)
	v_pk_add_f32 v[82:83], v[82:83], v[172:173]
	v_pk_add_f32 v[84:85], v[84:85], v[174:175]
	v_cvt_pk_bf16_f32 v172, v82, v83
	v_cvt_pk_bf16_f32 v173, v84, v85
	v_mul_f32_e32 v174, v82, v82
	v_fmac_f32_e32 v174, v83, v83
	v_fmac_f32_e32 v174, v84, v84
	v_fmac_f32_e32 v174, v85, v85
	s_waitcnt vmcnt(10) lgkmcnt(10)
	v_pk_add_f32 v[86:87], v[86:87], v[176:177]
	v_pk_add_f32 v[88:89], v[88:89], v[178:179]
	v_cvt_pk_bf16_f32 v176, v86, v87
	v_cvt_pk_bf16_f32 v177, v88, v89
	v_mul_f32_e32 v178, v86, v86
	v_fmac_f32_e32 v178, v87, v87
	v_fmac_f32_e32 v178, v88, v88
	v_fmac_f32_e32 v178, v89, v89
	s_waitcnt vmcnt(9) lgkmcnt(9)
	v_pk_add_f32 v[90:91], v[90:91], v[180:181]
	v_pk_add_f32 v[92:93], v[92:93], v[182:183]
	v_cvt_pk_bf16_f32 v180, v90, v91
	v_cvt_pk_bf16_f32 v181, v92, v93
	v_mul_f32_e32 v182, v90, v90
	v_fmac_f32_e32 v182, v91, v91
	v_fmac_f32_e32 v182, v92, v92
	v_fmac_f32_e32 v182, v93, v93
	s_waitcnt vmcnt(8) lgkmcnt(8)
	v_pk_add_f32 v[94:95], v[94:95], v[184:185]
	v_pk_add_f32 v[96:97], v[96:97], v[186:187]
	v_cvt_pk_bf16_f32 v184, v94, v95
	v_cvt_pk_bf16_f32 v185, v96, v97
	v_mul_f32_e32 v186, v94, v94
	v_fmac_f32_e32 v186, v95, v95
	v_fmac_f32_e32 v186, v96, v96
	v_fmac_f32_e32 v186, v97, v97
	s_waitcnt vmcnt(7) lgkmcnt(7)
	v_pk_add_f32 v[98:99], v[98:99], v[188:189]
	v_pk_add_f32 v[100:101], v[100:101], v[190:191]
	v_cvt_pk_bf16_f32 v188, v98, v99
	v_cvt_pk_bf16_f32 v189, v100, v101
	v_mul_f32_e32 v190, v98, v98
	v_fmac_f32_e32 v190, v99, v99
	v_fmac_f32_e32 v190, v100, v100
	v_fmac_f32_e32 v190, v101, v101
	s_waitcnt vmcnt(6) lgkmcnt(6)
	v_pk_add_f32 v[102:103], v[102:103], v[196:197]
	v_pk_add_f32 v[104:105], v[104:105], v[198:199]
	v_cvt_pk_bf16_f32 v196, v102, v103
	v_cvt_pk_bf16_f32 v197, v104, v105
	v_mul_f32_e32 v198, v102, v102
	v_fmac_f32_e32 v198, v103, v103
	v_fmac_f32_e32 v198, v104, v104
	v_fmac_f32_e32 v198, v105, v105
	s_waitcnt vmcnt(5) lgkmcnt(5)
	v_pk_add_f32 v[106:107], v[106:107], v[200:201]
	v_pk_add_f32 v[108:109], v[108:109], v[202:203]
	v_cvt_pk_bf16_f32 v200, v106, v107
	v_cvt_pk_bf16_f32 v201, v108, v109
	v_mul_f32_e32 v202, v106, v106
	v_fmac_f32_e32 v202, v107, v107
	v_fmac_f32_e32 v202, v108, v108
	v_fmac_f32_e32 v202, v109, v109
	s_waitcnt vmcnt(4) lgkmcnt(4)
	v_pk_add_f32 v[110:111], v[110:111], v[204:205]
	v_pk_add_f32 v[112:113], v[112:113], v[206:207]
	v_cvt_pk_bf16_f32 v204, v110, v111
	v_cvt_pk_bf16_f32 v205, v112, v113
	v_mul_f32_e32 v206, v110, v110
	v_fmac_f32_e32 v206, v111, v111
	v_fmac_f32_e32 v206, v112, v112
	v_fmac_f32_e32 v206, v113, v113
	s_waitcnt vmcnt(3) lgkmcnt(3)
	v_pk_add_f32 v[114:115], v[114:115], v[212:213]
	v_pk_add_f32 v[116:117], v[116:117], v[214:215]
	v_cvt_pk_bf16_f32 v212, v114, v115
	v_cvt_pk_bf16_f32 v213, v116, v117
	v_mul_f32_e32 v214, v114, v114
	v_fmac_f32_e32 v214, v115, v115
	v_fmac_f32_e32 v214, v116, v116
	v_fmac_f32_e32 v214, v117, v117
	s_waitcnt vmcnt(2) lgkmcnt(2)
	v_pk_add_f32 v[118:119], v[118:119], v[216:217]
	v_pk_add_f32 v[120:121], v[120:121], v[218:219]
	v_cvt_pk_bf16_f32 v216, v118, v119
	v_cvt_pk_bf16_f32 v217, v120, v121
	v_mul_f32_e32 v218, v118, v118
	v_fmac_f32_e32 v218, v119, v119
	v_fmac_f32_e32 v218, v120, v120
	v_fmac_f32_e32 v218, v121, v121
	s_waitcnt vmcnt(1) lgkmcnt(1)
	v_pk_add_f32 v[122:123], v[122:123], v[220:221]
	v_pk_add_f32 v[124:125], v[124:125], v[222:223]
	v_cvt_pk_bf16_f32 v220, v122, v123
	v_cvt_pk_bf16_f32 v221, v124, v125
	v_mul_f32_e32 v222, v122, v122
	v_fmac_f32_e32 v222, v123, v123
	v_fmac_f32_e32 v222, v124, v124
	v_fmac_f32_e32 v222, v125, v125
	s_waitcnt vmcnt(0) lgkmcnt(0)
	v_pk_add_f32 v[126:127], v[126:127], v[224:225]
	v_pk_add_f32 v[128:129], v[128:129], v[226:227]
	v_cvt_pk_bf16_f32 v224, v126, v127
	v_cvt_pk_bf16_f32 v225, v128, v129
	v_mul_f32_e32 v226, v126, v126
	v_fmac_f32_e32 v226, v127, v127
	v_fmac_f32_e32 v226, v128, v128
	v_fmac_f32_e32 v226, v129, v129
	s_mov_b32 s56, s58
	s_mov_b32 s57, s59
	s_mov_b32 s40, s46
	s_mov_b32 s41, s47
	global_store_dwordx4 v240, v[66:69], s[56:57]
	global_store_dwordx2 v244, v[136:137], s[40:41]
	s_add_u32 s56, s56, 0x10000
	s_addc_u32 s57, s57, 0
	s_add_u32 s40, s40, 0x8400
	s_addc_u32 s41, s41, 0
	global_store_dwordx4 v240, v[70:73], s[56:57]
	global_store_dwordx2 v244, v[140:141], s[40:41]
	s_add_u32 s56, s56, 0x10000
	s_addc_u32 s57, s57, 0
	s_add_u32 s40, s40, 0x8400
	s_addc_u32 s41, s41, 0
	global_store_dwordx4 v240, v[74:77], s[56:57]
	global_store_dwordx2 v244, v[144:145], s[40:41]
	s_add_u32 s56, s56, 0x10000
	s_addc_u32 s57, s57, 0
	s_add_u32 s40, s40, 0x8400
	s_addc_u32 s41, s41, 0
	global_store_dwordx4 v240, v[78:81], s[56:57]
	global_store_dwordx2 v244, v[148:149], s[40:41]
	s_add_u32 s56, s56, 0x10000
	s_addc_u32 s57, s57, 0
	s_add_u32 s40, s40, 0x8400
	s_addc_u32 s41, s41, 0
	global_store_dwordx4 v240, v[82:85], s[56:57]
	global_store_dwordx2 v244, v[172:173], s[40:41]
	s_add_u32 s56, s56, 0x10000
	s_addc_u32 s57, s57, 0
	s_add_u32 s40, s40, 0x8400
	s_addc_u32 s41, s41, 0
	global_store_dwordx4 v240, v[86:89], s[56:57]
	global_store_dwordx2 v244, v[176:177], s[40:41]
	s_add_u32 s56, s56, 0x10000
	s_addc_u32 s57, s57, 0
	s_add_u32 s40, s40, 0x8400
	s_addc_u32 s41, s41, 0
	global_store_dwordx4 v240, v[90:93], s[56:57]
	global_store_dwordx2 v244, v[180:181], s[40:41]
	s_add_u32 s56, s56, 0x10000
	s_addc_u32 s57, s57, 0
	s_add_u32 s40, s40, 0x8400
	s_addc_u32 s41, s41, 0
	global_store_dwordx4 v240, v[94:97], s[56:57]
	global_store_dwordx2 v244, v[184:185], s[40:41]
	s_add_u32 s56, s56, 0x10000
	s_addc_u32 s57, s57, 0
	s_add_u32 s40, s40, 0x8400
	s_addc_u32 s41, s41, 0
	global_store_dwordx4 v240, v[98:101], s[56:57]
	global_store_dwordx2 v244, v[188:189], s[40:41]
	s_add_u32 s56, s56, 0x10000
	s_addc_u32 s57, s57, 0
	s_add_u32 s40, s40, 0x8400
	s_addc_u32 s41, s41, 0
	global_store_dwordx4 v240, v[102:105], s[56:57]
	global_store_dwordx2 v244, v[196:197], s[40:41]
	s_add_u32 s56, s56, 0x10000
	s_addc_u32 s57, s57, 0
	s_add_u32 s40, s40, 0x8400
	s_addc_u32 s41, s41, 0
	global_store_dwordx4 v240, v[106:109], s[56:57]
	global_store_dwordx2 v244, v[200:201], s[40:41]
	s_add_u32 s56, s56, 0x10000
	s_addc_u32 s57, s57, 0
	s_add_u32 s40, s40, 0x8400
	s_addc_u32 s41, s41, 0
	global_store_dwordx4 v240, v[110:113], s[56:57]
	global_store_dwordx2 v244, v[204:205], s[40:41]
	s_add_u32 s56, s56, 0x10000
	s_addc_u32 s57, s57, 0
	s_add_u32 s40, s40, 0x8400
	s_addc_u32 s41, s41, 0
	global_store_dwordx4 v240, v[114:117], s[56:57]
	global_store_dwordx2 v244, v[212:213], s[40:41]
	s_add_u32 s56, s56, 0x10000
	s_addc_u32 s57, s57, 0
	s_add_u32 s40, s40, 0x8400
	s_addc_u32 s41, s41, 0
	global_store_dwordx4 v240, v[118:121], s[56:57]
	global_store_dwordx2 v244, v[216:217], s[40:41]
	s_add_u32 s56, s56, 0x10000
	s_addc_u32 s57, s57, 0
	s_add_u32 s40, s40, 0x8400
	s_addc_u32 s41, s41, 0
	global_store_dwordx4 v240, v[122:125], s[56:57]
	global_store_dwordx2 v244, v[220:221], s[40:41]
	s_add_u32 s56, s56, 0x10000
	s_addc_u32 s57, s57, 0
	s_add_u32 s40, s40, 0x8400
	s_addc_u32 s41, s41, 0
	global_store_dwordx4 v240, v[126:129], s[56:57]
	global_store_dwordx2 v244, v[224:225], s[40:41]
	v_add_f32_dpp v138, v138, v138 quad_perm:[1,0,3,2] row_mask:0xf bank_mask:0xf
	v_add_f32_dpp v142, v142, v142 quad_perm:[1,0,3,2] row_mask:0xf bank_mask:0xf
	v_add_f32_dpp v146, v146, v146 quad_perm:[1,0,3,2] row_mask:0xf bank_mask:0xf
	v_add_f32_dpp v150, v150, v150 quad_perm:[1,0,3,2] row_mask:0xf bank_mask:0xf
	v_add_f32_dpp v174, v174, v174 quad_perm:[1,0,3,2] row_mask:0xf bank_mask:0xf
	v_add_f32_dpp v178, v178, v178 quad_perm:[1,0,3,2] row_mask:0xf bank_mask:0xf
	v_add_f32_dpp v182, v182, v182 quad_perm:[1,0,3,2] row_mask:0xf bank_mask:0xf
	v_add_f32_dpp v186, v186, v186 quad_perm:[1,0,3,2] row_mask:0xf bank_mask:0xf
	v_add_f32_dpp v190, v190, v190 quad_perm:[1,0,3,2] row_mask:0xf bank_mask:0xf
	v_add_f32_dpp v198, v198, v198 quad_perm:[1,0,3,2] row_mask:0xf bank_mask:0xf
	v_add_f32_dpp v202, v202, v202 quad_perm:[1,0,3,2] row_mask:0xf bank_mask:0xf
	v_add_f32_dpp v206, v206, v206 quad_perm:[1,0,3,2] row_mask:0xf bank_mask:0xf
	v_add_f32_dpp v214, v214, v214 quad_perm:[1,0,3,2] row_mask:0xf bank_mask:0xf
	v_add_f32_dpp v218, v218, v218 quad_perm:[1,0,3,2] row_mask:0xf bank_mask:0xf
	v_add_f32_dpp v222, v222, v222 quad_perm:[1,0,3,2] row_mask:0xf bank_mask:0xf
	v_add_f32_dpp v226, v226, v226 quad_perm:[1,0,3,2] row_mask:0xf bank_mask:0xf
	v_add_f32_dpp v138, v138, v138 quad_perm:[2,3,0,1] row_mask:0xf bank_mask:0xf
	v_add_f32_dpp v142, v142, v142 quad_perm:[2,3,0,1] row_mask:0xf bank_mask:0xf
	v_add_f32_dpp v146, v146, v146 quad_perm:[2,3,0,1] row_mask:0xf bank_mask:0xf
	v_add_f32_dpp v150, v150, v150 quad_perm:[2,3,0,1] row_mask:0xf bank_mask:0xf
	v_add_f32_dpp v174, v174, v174 quad_perm:[2,3,0,1] row_mask:0xf bank_mask:0xf
	v_add_f32_dpp v178, v178, v178 quad_perm:[2,3,0,1] row_mask:0xf bank_mask:0xf
	v_add_f32_dpp v182, v182, v182 quad_perm:[2,3,0,1] row_mask:0xf bank_mask:0xf
	v_add_f32_dpp v186, v186, v186 quad_perm:[2,3,0,1] row_mask:0xf bank_mask:0xf
	v_add_f32_dpp v190, v190, v190 quad_perm:[2,3,0,1] row_mask:0xf bank_mask:0xf
	v_add_f32_dpp v198, v198, v198 quad_perm:[2,3,0,1] row_mask:0xf bank_mask:0xf
	v_add_f32_dpp v202, v202, v202 quad_perm:[2,3,0,1] row_mask:0xf bank_mask:0xf
	v_add_f32_dpp v206, v206, v206 quad_perm:[2,3,0,1] row_mask:0xf bank_mask:0xf
	v_add_f32_dpp v214, v214, v214 quad_perm:[2,3,0,1] row_mask:0xf bank_mask:0xf
	v_add_f32_dpp v218, v218, v218 quad_perm:[2,3,0,1] row_mask:0xf bank_mask:0xf
	v_add_f32_dpp v222, v222, v222 quad_perm:[2,3,0,1] row_mask:0xf bank_mask:0xf
	v_add_f32_dpp v226, v226, v226 quad_perm:[2,3,0,1] row_mask:0xf bank_mask:0xf
	v_add_f32_dpp v138, v138, v138 row_half_mirror row_mask:0xf bank_mask:0xf
	v_add_f32_dpp v142, v142, v142 row_half_mirror row_mask:0xf bank_mask:0xf
	v_add_f32_dpp v146, v146, v146 row_half_mirror row_mask:0xf bank_mask:0xf
	v_add_f32_dpp v150, v150, v150 row_half_mirror row_mask:0xf bank_mask:0xf
	v_add_f32_dpp v174, v174, v174 row_half_mirror row_mask:0xf bank_mask:0xf
	v_add_f32_dpp v178, v178, v178 row_half_mirror row_mask:0xf bank_mask:0xf
	v_add_f32_dpp v182, v182, v182 row_half_mirror row_mask:0xf bank_mask:0xf
	v_add_f32_dpp v186, v186, v186 row_half_mirror row_mask:0xf bank_mask:0xf
	v_add_f32_dpp v190, v190, v190 row_half_mirror row_mask:0xf bank_mask:0xf
	v_add_f32_dpp v198, v198, v198 row_half_mirror row_mask:0xf bank_mask:0xf
	v_add_f32_dpp v202, v202, v202 row_half_mirror row_mask:0xf bank_mask:0xf
	v_add_f32_dpp v206, v206, v206 row_half_mirror row_mask:0xf bank_mask:0xf
	v_add_f32_dpp v214, v214, v214 row_half_mirror row_mask:0xf bank_mask:0xf
	v_add_f32_dpp v218, v218, v218 row_half_mirror row_mask:0xf bank_mask:0xf
	v_add_f32_dpp v222, v222, v222 row_half_mirror row_mask:0xf bank_mask:0xf
	v_add_f32_dpp v226, v226, v226 row_half_mirror row_mask:0xf bank_mask:0xf
	v_add_f32_dpp v138, v138, v138 row_mirror row_mask:0xf bank_mask:0xf
	v_add_f32_dpp v142, v142, v142 row_mirror row_mask:0xf bank_mask:0xf
	v_add_f32_dpp v146, v146, v146 row_mirror row_mask:0xf bank_mask:0xf
	v_add_f32_dpp v150, v150, v150 row_mirror row_mask:0xf bank_mask:0xf
	v_add_f32_dpp v174, v174, v174 row_mirror row_mask:0xf bank_mask:0xf
	v_add_f32_dpp v178, v178, v178 row_mirror row_mask:0xf bank_mask:0xf
	v_add_f32_dpp v182, v182, v182 row_mirror row_mask:0xf bank_mask:0xf
	v_add_f32_dpp v186, v186, v186 row_mirror row_mask:0xf bank_mask:0xf
	v_add_f32_dpp v190, v190, v190 row_mirror row_mask:0xf bank_mask:0xf
	v_add_f32_dpp v198, v198, v198 row_mirror row_mask:0xf bank_mask:0xf
	v_add_f32_dpp v202, v202, v202 row_mirror row_mask:0xf bank_mask:0xf
	v_add_f32_dpp v206, v206, v206 row_mirror row_mask:0xf bank_mask:0xf
	v_add_f32_dpp v214, v214, v214 row_mirror row_mask:0xf bank_mask:0xf
	v_add_f32_dpp v218, v218, v218 row_mirror row_mask:0xf bank_mask:0xf
	v_add_f32_dpp v222, v222, v222 row_mirror row_mask:0xf bank_mask:0xf
	v_add_f32_dpp v226, v226, v226 row_mirror row_mask:0xf bank_mask:0xf
	v_add_f32_dpp v138, v138, v138 row_bcast:15 row_mask:0xa bank_mask:0xf
	v_add_f32_dpp v142, v142, v142 row_bcast:15 row_mask:0xa bank_mask:0xf
	v_add_f32_dpp v146, v146, v146 row_bcast:15 row_mask:0xa bank_mask:0xf
	v_add_f32_dpp v150, v150, v150 row_bcast:15 row_mask:0xa bank_mask:0xf
	v_add_f32_dpp v174, v174, v174 row_bcast:15 row_mask:0xa bank_mask:0xf
	v_add_f32_dpp v178, v178, v178 row_bcast:15 row_mask:0xa bank_mask:0xf
	v_add_f32_dpp v182, v182, v182 row_bcast:15 row_mask:0xa bank_mask:0xf
	v_add_f32_dpp v186, v186, v186 row_bcast:15 row_mask:0xa bank_mask:0xf
	v_add_f32_dpp v190, v190, v190 row_bcast:15 row_mask:0xa bank_mask:0xf
	v_add_f32_dpp v198, v198, v198 row_bcast:15 row_mask:0xa bank_mask:0xf
	v_add_f32_dpp v202, v202, v202 row_bcast:15 row_mask:0xa bank_mask:0xf
	v_add_f32_dpp v206, v206, v206 row_bcast:15 row_mask:0xa bank_mask:0xf
	v_add_f32_dpp v214, v214, v214 row_bcast:15 row_mask:0xa bank_mask:0xf
	v_add_f32_dpp v218, v218, v218 row_bcast:15 row_mask:0xa bank_mask:0xf
	v_add_f32_dpp v222, v222, v222 row_bcast:15 row_mask:0xa bank_mask:0xf
	v_add_f32_dpp v226, v226, v226 row_bcast:15 row_mask:0xa bank_mask:0xf
	s_mov_b32 exec_lo, 0x10000
	s_mov_b32 exec_hi, 0x10000
	global_atomic_add_f32 v245, v138, s[48:49]
	global_atomic_add_f32 v245, v142, s[48:49] offset:32
	global_atomic_add_f32 v245, v146, s[48:49] offset:64
	global_atomic_add_f32 v245, v150, s[48:49] offset:96
	global_atomic_add_f32 v245, v174, s[48:49] offset:128
	global_atomic_add_f32 v245, v178, s[48:49] offset:160
	global_atomic_add_f32 v245, v182, s[48:49] offset:192
	global_atomic_add_f32 v245, v186, s[48:49] offset:224
	global_atomic_add_f32 v245, v190, s[48:49] offset:256
	global_atomic_add_f32 v245, v198, s[48:49] offset:288
	global_atomic_add_f32 v245, v202, s[48:49] offset:320
	global_atomic_add_f32 v245, v206, s[48:49] offset:352
	global_atomic_add_f32 v245, v214, s[48:49] offset:384
	global_atomic_add_f32 v245, v218, s[48:49] offset:416
	global_atomic_add_f32 v245, v222, s[48:49] offset:448
	global_atomic_add_f32 v245, v226, s[48:49] offset:480
	s_mov_b64 exec, -1
	s_add_i32 s21, s21, s72
	s_cmpk_lt_i32 s21, 0x200
	s_waitcnt lgkmcnt(0)
	s_barrier
	s_cbranch_scc1 .Lres1_tile

.Lin2_loop:
	s_setprio 3
	v_add_u32_e32 v234, s22, v232
	v_add_u32_e32 v236, s28, v232
	v_add_u32_e32 v235, s22, v233
	v_add_u32_e32 v237, s28, v233
	ds_read_b128 v[136:139], v234
	ds_read_b128 v[140:143], v234 offset:2048
	ds_read_b128 v[144:147], v234 offset:4096
	ds_read_b128 v[148:151], v234 offset:6144
	ds_read_b128 v[188:191], v236
	ds_read_b128 v[196:199], v236 offset:2048
	ds_read_b128 v[200:203], v236 offset:4096
	ds_read_b128 v[204:207], v236 offset:6144
	ds_read_b128 v[172:175], v235
	ds_read_b128 v[176:179], v235 offset:2048
	ds_read_b128 v[180:183], v235 offset:4096
	ds_read_b128 v[184:187], v235 offset:6144
	ds_read_b128 v[212:215], v237
	ds_read_b128 v[216:219], v237 offset:2048
	ds_read_b128 v[220:223], v237 offset:4096
	ds_read_b128 v[224:227], v237 offset:6144
	s_add_i32 m0, s51, 0xc000
	s_nop 0
	global_load_lds_dwordx4 v228, s[44:45]
	s_add_i32 m0, s51, 0xc400
	s_nop 0
	global_load_lds_dwordx4 v230, s[44:45]
	s_add_i32 m0, s51, 0xe000
	s_nop 0
	global_load_lds_dwordx4 v229, s[44:45]
	s_add_i32 m0, s51, 0xe400
	s_nop 0
	global_load_lds_dwordx4 v231, s[44:45]
	s_add_i32 m0, s51, 0x10000
	s_nop 0
	global_load_lds_dwordx4 v228, s[46:47]
	s_add_i32 m0, s51, 0x10400
	s_nop 0
	global_load_lds_dwordx4 v230, s[46:47]
	s_waitcnt lgkmcnt(8)
	s_setprio 1
	v_mfma_f32_16x16x32_bf16 v[2:5], v[136:139], v[188:191], v[2:5]
	v_mfma_f32_16x16x32_bf16 v[6:9], v[136:139], v[196:199], v[6:9]
	v_mfma_f32_16x16x32_bf16 v[10:13], v[136:139], v[200:203], v[10:13]
	v_mfma_f32_16x16x32_bf16 v[14:17], v[136:139], v[204:207], v[14:17]
	v_mfma_f32_16x16x32_bf16 v[18:21], v[140:143], v[188:191], v[18:21]
	v_mfma_f32_16x16x32_bf16 v[22:25], v[140:143], v[196:199], v[22:25]
	v_mfma_f32_16x16x32_bf16 v[26:29], v[140:143], v[200:203], v[26:29]
	v_mfma_f32_16x16x32_bf16 v[30:33], v[140:143], v[204:207], v[30:33]
	v_mfma_f32_16x16x32_bf16 v[34:37], v[144:147], v[188:191], v[34:37]
	v_mfma_f32_16x16x32_bf16 v[38:41], v[144:147], v[196:199], v[38:41]
	v_mfma_f32_16x16x32_bf16 v[42:45], v[144:147], v[200:203], v[42:45]
	v_mfma_f32_16x16x32_bf16 v[46:49], v[144:147], v[204:207], v[46:49]
	v_mfma_f32_16x16x32_bf16 v[50:53], v[148:151], v[188:191], v[50:53]
	v_mfma_f32_16x16x32_bf16 v[54:57], v[148:151], v[196:199], v[54:57]
	v_mfma_f32_16x16x32_bf16 v[58:61], v[148:151], v[200:203], v[58:61]
	v_mfma_f32_16x16x32_bf16 v[62:65], v[148:151], v[204:207], v[62:65]
	s_waitcnt lgkmcnt(0)
	v_mfma_f32_16x16x32_bf16 v[2:5], v[172:175], v[212:215], v[2:5]
	v_mfma_f32_16x16x32_bf16 v[6:9], v[172:175], v[216:219], v[6:9]
	v_mfma_f32_16x16x32_bf16 v[10:13], v[172:175], v[220:223], v[10:13]
	v_mfma_f32_16x16x32_bf16 v[14:17], v[172:175], v[224:227], v[14:17]
	v_mfma_f32_16x16x32_bf16 v[18:21], v[176:179], v[212:215], v[18:21]
	v_mfma_f32_16x16x32_bf16 v[22:25], v[176:179], v[216:219], v[22:25]
	v_mfma_f32_16x16x32_bf16 v[26:29], v[176:179], v[220:223], v[26:29]
	v_mfma_f32_16x16x32_bf16 v[30:33], v[176:179], v[224:227], v[30:33]
	v_mfma_f32_16x16x32_bf16 v[34:37], v[180:183], v[212:215], v[34:37]
	v_mfma_f32_16x16x32_bf16 v[38:41], v[180:183], v[216:219], v[38:41]
	v_mfma_f32_16x16x32_bf16 v[42:45], v[180:183], v[220:223], v[42:45]
	v_mfma_f32_16x16x32_bf16 v[46:49], v[180:183], v[224:227], v[46:49]
	v_mfma_f32_16x16x32_bf16 v[50:53], v[184:187], v[212:215], v[50:53]
	v_mfma_f32_16x16x32_bf16 v[54:57], v[184:187], v[216:219], v[54:57]
	v_mfma_f32_16x16x32_bf16 v[58:61], v[184:187], v[220:223], v[58:61]
	v_mfma_f32_16x16x32_bf16 v[62:65], v[184:187], v[224:227], v[62:65]
	s_setprio 0
	s_waitcnt vmcnt(6)
	s_barrier
	s_setprio 3
	v_add_u32_e32 v236, s40, v232
	v_add_u32_e32 v237, s40, v233
	ds_read_b128 v[188:191], v236
	ds_read_b128 v[196:199], v236 offset:2048
	ds_read_b128 v[200:203], v236 offset:4096
	ds_read_b128 v[204:207], v236 offset:6144
	ds_read_b128 v[212:215], v237
	ds_read_b128 v[216:219], v237 offset:2048
	ds_read_b128 v[220:223], v237 offset:4096
	ds_read_b128 v[224:227], v237 offset:6144
	s_mov_b32 m0, s51
	s_nop 0
	global_load_lds_dwordx4 v229, s[46:47]
	s_add_i32 m0, s51, 0x400
	s_nop 0
	global_load_lds_dwordx4 v231, s[46:47]
	s_add_i32 m0, s51, 0x2000
	s_nop 0
	global_load_lds_dwordx4 v228, s[48:49]
	s_add_i32 m0, s51, 0x2400
	s_nop 0
	global_load_lds_dwordx4 v230, s[48:49]
	s_add_i32 m0, s51, 0x4000
	s_nop 0
	global_load_lds_dwordx4 v229, s[48:49]
	s_add_i32 m0, s51, 0x4400
	s_nop 0
	global_load_lds_dwordx4 v231, s[48:49]
	s_waitcnt lgkmcnt(4)
	s_setprio 1
	v_mfma_f32_16x16x32_bf16 v[66:69], v[136:139], v[188:191], v[66:69]
	v_mfma_f32_16x16x32_bf16 v[70:73], v[136:139], v[196:199], v[70:73]
	v_mfma_f32_16x16x32_bf16 v[74:77], v[136:139], v[200:203], v[74:77]
	v_mfma_f32_16x16x32_bf16 v[78:81], v[136:139], v[204:207], v[78:81]
	v_mfma_f32_16x16x32_bf16 v[82:85], v[140:143], v[188:191], v[82:85]
	v_mfma_f32_16x16x32_bf16 v[86:89], v[140:143], v[196:199], v[86:89]
	v_mfma_f32_16x16x32_bf16 v[90:93], v[140:143], v[200:203], v[90:93]
	v_mfma_f32_16x16x32_bf16 v[94:97], v[140:143], v[204:207], v[94:97]
	v_mfma_f32_16x16x32_bf16 v[98:101], v[144:147], v[188:191], v[98:101]
	v_mfma_f32_16x16x32_bf16 v[102:105], v[144:147], v[196:199], v[102:105]
	v_mfma_f32_16x16x32_bf16 v[106:109], v[144:147], v[200:203], v[106:109]
	v_mfma_f32_16x16x32_bf16 v[110:113], v[144:147], v[204:207], v[110:113]
	v_mfma_f32_16x16x32_bf16 v[114:117], v[148:151], v[188:191], v[114:117]
	v_mfma_f32_16x16x32_bf16 v[118:121], v[148:151], v[196:199], v[118:121]
	v_mfma_f32_16x16x32_bf16 v[122:125], v[148:151], v[200:203], v[122:125]
	v_mfma_f32_16x16x32_bf16 v[126:129], v[148:151], v[204:207], v[126:129]
	s_waitcnt lgkmcnt(0)
	v_mfma_f32_16x16x32_bf16 v[66:69], v[172:175], v[212:215], v[66:69]
	v_mfma_f32_16x16x32_bf16 v[70:73], v[172:175], v[216:219], v[70:73]
	v_mfma_f32_16x16x32_bf16 v[74:77], v[172:175], v[220:223], v[74:77]
	v_mfma_f32_16x16x32_bf16 v[78:81], v[172:175], v[224:227], v[78:81]
	v_mfma_f32_16x16x32_bf16 v[82:85], v[176:179], v[212:215], v[82:85]
	v_mfma_f32_16x16x32_bf16 v[86:89], v[176:179], v[216:219], v[86:89]
	v_mfma_f32_16x16x32_bf16 v[90:93], v[176:179], v[220:223], v[90:93]
	v_mfma_f32_16x16x32_bf16 v[94:97], v[176:179], v[224:227], v[94:97]
	v_mfma_f32_16x16x32_bf16 v[98:101], v[180:183], v[212:215], v[98:101]
	v_mfma_f32_16x16x32_bf16 v[102:105], v[180:183], v[216:219], v[102:105]
	v_mfma_f32_16x16x32_bf16 v[106:109], v[180:183], v[220:223], v[106:109]
	v_mfma_f32_16x16x32_bf16 v[110:113], v[180:183], v[224:227], v[110:113]
	v_mfma_f32_16x16x32_bf16 v[114:117], v[184:187], v[212:215], v[114:117]
	v_mfma_f32_16x16x32_bf16 v[118:121], v[184:187], v[216:219], v[118:121]
	v_mfma_f32_16x16x32_bf16 v[122:125], v[184:187], v[220:223], v[122:125]
	v_mfma_f32_16x16x32_bf16 v[126:129], v[184:187], v[224:227], v[126:129]
	s_setprio 0
	v_add_u32_e32 v228, 0x80, v228
	v_add_u32_e32 v229, 0x80, v229
	v_add_u32_e32 v230, 0x80, v230
	v_add_u32_e32 v231, 0x80, v231
	s_waitcnt vmcnt(4)
	s_barrier
	s_setprio 3
	v_add_u32_e32 v234, s23, v232
	v_add_u32_e32 v236, s29, v232
	v_add_u32_e32 v235, s23, v233
	v_add_u32_e32 v237, s29, v233
	ds_read_b128 v[136:139], v234
	ds_read_b128 v[140:143], v234 offset:2048
	ds_read_b128 v[144:147], v234 offset:4096
	ds_read_b128 v[148:151], v234 offset:6144
	ds_read_b128 v[188:191], v236
	ds_read_b128 v[196:199], v236 offset:2048
	ds_read_b128 v[200:203], v236 offset:4096
	ds_read_b128 v[204:207], v236 offset:6144
	ds_read_b128 v[172:175], v235
	ds_read_b128 v[176:179], v235 offset:2048
	ds_read_b128 v[180:183], v235 offset:4096
	ds_read_b128 v[184:187], v235 offset:6144
	ds_read_b128 v[212:215], v237
	ds_read_b128 v[216:219], v237 offset:2048
	ds_read_b128 v[220:223], v237 offset:4096
	ds_read_b128 v[224:227], v237 offset:6144
	s_add_i32 m0, s51, 0x6000
	s_nop 0
	global_load_lds_dwordx4 v228, s[44:45]
	s_add_i32 m0, s51, 0x6400
	s_nop 0
	global_load_lds_dwordx4 v230, s[44:45]
	s_add_i32 m0, s51, 0x8000
	s_nop 0
	global_load_lds_dwordx4 v229, s[44:45]
	s_add_i32 m0, s51, 0x8400
	s_nop 0
	global_load_lds_dwordx4 v231, s[44:45]
	s_add_i32 m0, s51, 0xa000
	s_nop 0
	global_load_lds_dwordx4 v228, s[46:47]
	s_add_i32 m0, s51, 0xa400
	s_nop 0
	global_load_lds_dwordx4 v230, s[46:47]
	s_waitcnt lgkmcnt(8)
	s_setprio 1
	v_mfma_f32_16x16x32_bf16 v[2:5], v[136:139], v[188:191], v[2:5]
	v_mfma_f32_16x16x32_bf16 v[6:9], v[136:139], v[196:199], v[6:9]
	v_mfma_f32_16x16x32_bf16 v[10:13], v[136:139], v[200:203], v[10:13]
	v_mfma_f32_16x16x32_bf16 v[14:17], v[136:139], v[204:207], v[14:17]
	v_mfma_f32_16x16x32_bf16 v[18:21], v[140:143], v[188:191], v[18:21]
	v_mfma_f32_16x16x32_bf16 v[22:25], v[140:143], v[196:199], v[22:25]
	v_mfma_f32_16x16x32_bf16 v[26:29], v[140:143], v[200:203], v[26:29]
	v_mfma_f32_16x16x32_bf16 v[30:33], v[140:143], v[204:207], v[30:33]
	v_mfma_f32_16x16x32_bf16 v[34:37], v[144:147], v[188:191], v[34:37]
	v_mfma_f32_16x16x32_bf16 v[38:41], v[144:147], v[196:199], v[38:41]
	v_mfma_f32_16x16x32_bf16 v[42:45], v[144:147], v[200:203], v[42:45]
	v_mfma_f32_16x16x32_bf16 v[46:49], v[144:147], v[204:207], v[46:49]
	v_mfma_f32_16x16x32_bf16 v[50:53], v[148:151], v[188:191], v[50:53]
	v_mfma_f32_16x16x32_bf16 v[54:57], v[148:151], v[196:199], v[54:57]
	v_mfma_f32_16x16x32_bf16 v[58:61], v[148:151], v[200:203], v[58:61]
	v_mfma_f32_16x16x32_bf16 v[62:65], v[148:151], v[204:207], v[62:65]
	s_waitcnt lgkmcnt(0)
	v_mfma_f32_16x16x32_bf16 v[2:5], v[172:175], v[212:215], v[2:5]
	v_mfma_f32_16x16x32_bf16 v[6:9], v[172:175], v[216:219], v[6:9]
	v_mfma_f32_16x16x32_bf16 v[10:13], v[172:175], v[220:223], v[10:13]
	v_mfma_f32_16x16x32_bf16 v[14:17], v[172:175], v[224:227], v[14:17]
	v_mfma_f32_16x16x32_bf16 v[18:21], v[176:179], v[212:215], v[18:21]
	v_mfma_f32_16x16x32_bf16 v[22:25], v[176:179], v[216:219], v[22:25]
	v_mfma_f32_16x16x32_bf16 v[26:29], v[176:179], v[220:223], v[26:29]
	v_mfma_f32_16x16x32_bf16 v[30:33], v[176:179], v[224:227], v[30:33]
	v_mfma_f32_16x16x32_bf16 v[34:37], v[180:183], v[212:215], v[34:37]
	v_mfma_f32_16x16x32_bf16 v[38:41], v[180:183], v[216:219], v[38:41]
	v_mfma_f32_16x16x32_bf16 v[42:45], v[180:183], v[220:223], v[42:45]
	v_mfma_f32_16x16x32_bf16 v[46:49], v[180:183], v[224:227], v[46:49]
	v_mfma_f32_16x16x32_bf16 v[50:53], v[184:187], v[212:215], v[50:53]
	v_mfma_f32_16x16x32_bf16 v[54:57], v[184:187], v[216:219], v[54:57]
	v_mfma_f32_16x16x32_bf16 v[58:61], v[184:187], v[220:223], v[58:61]
	v_mfma_f32_16x16x32_bf16 v[62:65], v[184:187], v[224:227], v[62:65]
	s_setprio 0
	s_waitcnt vmcnt(6)
	s_barrier
	s_setprio 3
	v_add_u32_e32 v236, s41, v232
	v_add_u32_e32 v237, s41, v233
	ds_read_b128 v[188:191], v236
	ds_read_b128 v[196:199], v236 offset:2048
	ds_read_b128 v[200:203], v236 offset:4096
	ds_read_b128 v[204:207], v236 offset:6144
	ds_read_b128 v[212:215], v237
	ds_read_b128 v[216:219], v237 offset:2048
	ds_read_b128 v[220:223], v237 offset:4096
	ds_read_b128 v[224:227], v237 offset:6144
	s_add_i32 m0, s51, 0xc000
	s_nop 0
	global_load_lds_dwordx4 v229, s[46:47]
	s_add_i32 m0, s51, 0xc400
	s_nop 0
	global_load_lds_dwordx4 v231, s[46:47]
	s_add_i32 m0, s51, 0xe000
	s_nop 0
	global_load_lds_dwordx4 v228, s[48:49]
	s_add_i32 m0, s51, 0xe400
	s_nop 0
	global_load_lds_dwordx4 v230, s[48:49]
	s_add_i32 m0, s51, 0x10000
	s_nop 0
	global_load_lds_dwordx4 v229, s[48:49]
	s_add_i32 m0, s51, 0x10400
	s_nop 0
	global_load_lds_dwordx4 v231, s[48:49]
	s_waitcnt lgkmcnt(4)
	s_setprio 1
	v_mfma_f32_16x16x32_bf16 v[66:69], v[136:139], v[188:191], v[66:69]
	v_mfma_f32_16x16x32_bf16 v[70:73], v[136:139], v[196:199], v[70:73]
	v_mfma_f32_16x16x32_bf16 v[74:77], v[136:139], v[200:203], v[74:77]
	v_mfma_f32_16x16x32_bf16 v[78:81], v[136:139], v[204:207], v[78:81]
	v_mfma_f32_16x16x32_bf16 v[82:85], v[140:143], v[188:191], v[82:85]
	v_mfma_f32_16x16x32_bf16 v[86:89], v[140:143], v[196:199], v[86:89]
	v_mfma_f32_16x16x32_bf16 v[90:93], v[140:143], v[200:203], v[90:93]
	v_mfma_f32_16x16x32_bf16 v[94:97], v[140:143], v[204:207], v[94:97]
	v_mfma_f32_16x16x32_bf16 v[98:101], v[144:147], v[188:191], v[98:101]
	v_mfma_f32_16x16x32_bf16 v[102:105], v[144:147], v[196:199], v[102:105]
	v_mfma_f32_16x16x32_bf16 v[106:109], v[144:147], v[200:203], v[106:109]
	v_mfma_f32_16x16x32_bf16 v[110:113], v[144:147], v[204:207], v[110:113]
	v_mfma_f32_16x16x32_bf16 v[114:117], v[148:151], v[188:191], v[114:117]
	v_mfma_f32_16x16x32_bf16 v[118:121], v[148:151], v[196:199], v[118:121]
	v_mfma_f32_16x16x32_bf16 v[122:125], v[148:151], v[200:203], v[122:125]
	v_mfma_f32_16x16x32_bf16 v[126:129], v[148:151], v[204:207], v[126:129]
	s_waitcnt lgkmcnt(0)
	v_mfma_f32_16x16x32_bf16 v[66:69], v[172:175], v[212:215], v[66:69]
	v_mfma_f32_16x16x32_bf16 v[70:73], v[172:175], v[216:219], v[70:73]
	v_mfma_f32_16x16x32_bf16 v[74:77], v[172:175], v[220:223], v[74:77]
	v_mfma_f32_16x16x32_bf16 v[78:81], v[172:175], v[224:227], v[78:81]
	v_mfma_f32_16x16x32_bf16 v[82:85], v[176:179], v[212:215], v[82:85]
	v_mfma_f32_16x16x32_bf16 v[86:89], v[176:179], v[216:219], v[86:89]
	v_mfma_f32_16x16x32_bf16 v[90:93], v[176:179], v[220:223], v[90:93]
	v_mfma_f32_16x16x32_bf16 v[94:97], v[176:179], v[224:227], v[94:97]
	v_mfma_f32_16x16x32_bf16 v[98:101], v[180:183], v[212:215], v[98:101]
	v_mfma_f32_16x16x32_bf16 v[102:105], v[180:183], v[216:219], v[102:105]
	v_mfma_f32_16x16x32_bf16 v[106:109], v[180:183], v[220:223], v[106:109]
	v_mfma_f32_16x16x32_bf16 v[110:113], v[180:183], v[224:227], v[110:113]
	v_mfma_f32_16x16x32_bf16 v[114:117], v[184:187], v[212:215], v[114:117]
	v_mfma_f32_16x16x32_bf16 v[118:121], v[184:187], v[216:219], v[118:121]
	v_mfma_f32_16x16x32_bf16 v[122:125], v[184:187], v[220:223], v[122:125]
	v_mfma_f32_16x16x32_bf16 v[126:129], v[184:187], v[224:227], v[126:129]
	s_setprio 0
	v_add_u32_e32 v228, 0x80, v228
	v_add_u32_e32 v229, 0x80, v229
	v_add_u32_e32 v230, 0x80, v230
	v_add_u32_e32 v231, 0x80, v231
	s_waitcnt vmcnt(4)
	s_barrier
	s_setprio 3
	v_add_u32_e32 v234, s24, v232
	v_add_u32_e32 v236, s30, v232
	v_add_u32_e32 v235, s24, v233
	v_add_u32_e32 v237, s30, v233
	ds_read_b128 v[136:139], v234
	ds_read_b128 v[140:143], v234 offset:2048
	ds_read_b128 v[144:147], v234 offset:4096
	ds_read_b128 v[148:151], v234 offset:6144
	ds_read_b128 v[188:191], v236
	ds_read_b128 v[196:199], v236 offset:2048
	ds_read_b128 v[200:203], v236 offset:4096
	ds_read_b128 v[204:207], v236 offset:6144
	ds_read_b128 v[172:175], v235
	ds_read_b128 v[176:179], v235 offset:2048
	ds_read_b128 v[180:183], v235 offset:4096
	ds_read_b128 v[184:187], v235 offset:6144
	ds_read_b128 v[212:215], v237
	ds_read_b128 v[216:219], v237 offset:2048
	ds_read_b128 v[220:223], v237 offset:4096
	ds_read_b128 v[224:227], v237 offset:6144
	s_mov_b32 m0, s51
	s_nop 0
	global_load_lds_dwordx4 v228, s[44:45]
	s_add_i32 m0, s51, 0x400
	s_nop 0
	global_load_lds_dwordx4 v230, s[44:45]
	s_add_i32 m0, s51, 0x2000
	s_nop 0
	global_load_lds_dwordx4 v229, s[44:45]
	s_add_i32 m0, s51, 0x2400
	s_nop 0
	global_load_lds_dwordx4 v231, s[44:45]
	s_add_i32 m0, s51, 0x4000
	s_nop 0
	global_load_lds_dwordx4 v228, s[46:47]
	s_add_i32 m0, s51, 0x4400
	s_nop 0
	global_load_lds_dwordx4 v230, s[46:47]
	s_waitcnt lgkmcnt(8)
	s_setprio 1
	v_mfma_f32_16x16x32_bf16 v[2:5], v[136:139], v[188:191], v[2:5]
	v_mfma_f32_16x16x32_bf16 v[6:9], v[136:139], v[196:199], v[6:9]
	v_mfma_f32_16x16x32_bf16 v[10:13], v[136:139], v[200:203], v[10:13]
	v_mfma_f32_16x16x32_bf16 v[14:17], v[136:139], v[204:207], v[14:17]
	v_mfma_f32_16x16x32_bf16 v[18:21], v[140:143], v[188:191], v[18:21]
	v_mfma_f32_16x16x32_bf16 v[22:25], v[140:143], v[196:199], v[22:25]
	v_mfma_f32_16x16x32_bf16 v[26:29], v[140:143], v[200:203], v[26:29]
	v_mfma_f32_16x16x32_bf16 v[30:33], v[140:143], v[204:207], v[30:33]
	v_mfma_f32_16x16x32_bf16 v[34:37], v[144:147], v[188:191], v[34:37]
	v_mfma_f32_16x16x32_bf16 v[38:41], v[144:147], v[196:199], v[38:41]
	v_mfma_f32_16x16x32_bf16 v[42:45], v[144:147], v[200:203], v[42:45]
	v_mfma_f32_16x16x32_bf16 v[46:49], v[144:147], v[204:207], v[46:49]
	v_mfma_f32_16x16x32_bf16 v[50:53], v[148:151], v[188:191], v[50:53]
	v_mfma_f32_16x16x32_bf16 v[54:57], v[148:151], v[196:199], v[54:57]
	v_mfma_f32_16x16x32_bf16 v[58:61], v[148:151], v[200:203], v[58:61]
	v_mfma_f32_16x16x32_bf16 v[62:65], v[148:151], v[204:207], v[62:65]
	s_waitcnt lgkmcnt(0)
	v_mfma_f32_16x16x32_bf16 v[2:5], v[172:175], v[212:215], v[2:5]
	v_mfma_f32_16x16x32_bf16 v[6:9], v[172:175], v[216:219], v[6:9]
	v_mfma_f32_16x16x32_bf16 v[10:13], v[172:175], v[220:223], v[10:13]
	v_mfma_f32_16x16x32_bf16 v[14:17], v[172:175], v[224:227], v[14:17]
	v_mfma_f32_16x16x32_bf16 v[18:21], v[176:179], v[212:215], v[18:21]
	v_mfma_f32_16x16x32_bf16 v[22:25], v[176:179], v[216:219], v[22:25]
	v_mfma_f32_16x16x32_bf16 v[26:29], v[176:179], v[220:223], v[26:29]
	v_mfma_f32_16x16x32_bf16 v[30:33], v[176:179], v[224:227], v[30:33]
	v_mfma_f32_16x16x32_bf16 v[34:37], v[180:183], v[212:215], v[34:37]
	v_mfma_f32_16x16x32_bf16 v[38:41], v[180:183], v[216:219], v[38:41]
	v_mfma_f32_16x16x32_bf16 v[42:45], v[180:183], v[220:223], v[42:45]
	v_mfma_f32_16x16x32_bf16 v[46:49], v[180:183], v[224:227], v[46:49]
	v_mfma_f32_16x16x32_bf16 v[50:53], v[184:187], v[212:215], v[50:53]
	v_mfma_f32_16x16x32_bf16 v[54:57], v[184:187], v[216:219], v[54:57]
	v_mfma_f32_16x16x32_bf16 v[58:61], v[184:187], v[220:223], v[58:61]
	v_mfma_f32_16x16x32_bf16 v[62:65], v[184:187], v[224:227], v[62:65]
	s_setprio 0
	s_waitcnt vmcnt(6)
	s_barrier
	s_setprio 3
	v_add_u32_e32 v236, s42, v232
	v_add_u32_e32 v237, s42, v233
	ds_read_b128 v[188:191], v236
	ds_read_b128 v[196:199], v236 offset:2048
	ds_read_b128 v[200:203], v236 offset:4096
	ds_read_b128 v[204:207], v236 offset:6144
	ds_read_b128 v[212:215], v237
	ds_read_b128 v[216:219], v237 offset:2048
	ds_read_b128 v[220:223], v237 offset:4096
	ds_read_b128 v[224:227], v237 offset:6144
	s_add_i32 m0, s51, 0x6000
	s_nop 0
	global_load_lds_dwordx4 v229, s[46:47]
	s_add_i32 m0, s51, 0x6400
	s_nop 0
	global_load_lds_dwordx4 v231, s[46:47]
	s_add_i32 m0, s51, 0x8000
	s_nop 0
	global_load_lds_dwordx4 v228, s[48:49]
	s_add_i32 m0, s51, 0x8400
	s_nop 0
	global_load_lds_dwordx4 v230, s[48:49]
	s_add_i32 m0, s51, 0xa000
	s_nop 0
	global_load_lds_dwordx4 v229, s[48:49]
	s_add_i32 m0, s51, 0xa400
	s_nop 0
	global_load_lds_dwordx4 v231, s[48:49]
	s_waitcnt lgkmcnt(4)
	s_setprio 1
	v_mfma_f32_16x16x32_bf16 v[66:69], v[136:139], v[188:191], v[66:69]
	v_mfma_f32_16x16x32_bf16 v[70:73], v[136:139], v[196:199], v[70:73]
	v_mfma_f32_16x16x32_bf16 v[74:77], v[136:139], v[200:203], v[74:77]
	v_mfma_f32_16x16x32_bf16 v[78:81], v[136:139], v[204:207], v[78:81]
	v_mfma_f32_16x16x32_bf16 v[82:85], v[140:143], v[188:191], v[82:85]
	v_mfma_f32_16x16x32_bf16 v[86:89], v[140:143], v[196:199], v[86:89]
	v_mfma_f32_16x16x32_bf16 v[90:93], v[140:143], v[200:203], v[90:93]
	v_mfma_f32_16x16x32_bf16 v[94:97], v[140:143], v[204:207], v[94:97]
	v_mfma_f32_16x16x32_bf16 v[98:101], v[144:147], v[188:191], v[98:101]
	v_mfma_f32_16x16x32_bf16 v[102:105], v[144:147], v[196:199], v[102:105]
	v_mfma_f32_16x16x32_bf16 v[106:109], v[144:147], v[200:203], v[106:109]
	v_mfma_f32_16x16x32_bf16 v[110:113], v[144:147], v[204:207], v[110:113]
	v_mfma_f32_16x16x32_bf16 v[114:117], v[148:151], v[188:191], v[114:117]
	v_mfma_f32_16x16x32_bf16 v[118:121], v[148:151], v[196:199], v[118:121]
	v_mfma_f32_16x16x32_bf16 v[122:125], v[148:151], v[200:203], v[122:125]
	v_mfma_f32_16x16x32_bf16 v[126:129], v[148:151], v[204:207], v[126:129]
	s_waitcnt lgkmcnt(0)
	v_mfma_f32_16x16x32_bf16 v[66:69], v[172:175], v[212:215], v[66:69]
	v_mfma_f32_16x16x32_bf16 v[70:73], v[172:175], v[216:219], v[70:73]
	v_mfma_f32_16x16x32_bf16 v[74:77], v[172:175], v[220:223], v[74:77]
	v_mfma_f32_16x16x32_bf16 v[78:81], v[172:175], v[224:227], v[78:81]
	v_mfma_f32_16x16x32_bf16 v[82:85], v[176:179], v[212:215], v[82:85]
	v_mfma_f32_16x16x32_bf16 v[86:89], v[176:179], v[216:219], v[86:89]
	v_mfma_f32_16x16x32_bf16 v[90:93], v[176:179], v[220:223], v[90:93]
	v_mfma_f32_16x16x32_bf16 v[94:97], v[176:179], v[224:227], v[94:97]
	v_mfma_f32_16x16x32_bf16 v[98:101], v[180:183], v[212:215], v[98:101]
	v_mfma_f32_16x16x32_bf16 v[102:105], v[180:183], v[216:219], v[102:105]
	v_mfma_f32_16x16x32_bf16 v[106:109], v[180:183], v[220:223], v[106:109]
	v_mfma_f32_16x16x32_bf16 v[110:113], v[180:183], v[224:227], v[110:113]
	v_mfma_f32_16x16x32_bf16 v[114:117], v[184:187], v[212:215], v[114:117]
	v_mfma_f32_16x16x32_bf16 v[118:121], v[184:187], v[216:219], v[118:121]
	v_mfma_f32_16x16x32_bf16 v[122:125], v[184:187], v[220:223], v[122:125]
	v_mfma_f32_16x16x32_bf16 v[126:129], v[184:187], v[224:227], v[126:129]
	s_setprio 0
	v_add_u32_e32 v228, 0x80, v228
	v_add_u32_e32 v229, 0x80, v229
	v_add_u32_e32 v230, 0x80, v230
	v_add_u32_e32 v231, 0x80, v231
	s_waitcnt vmcnt(4)
	s_barrier
	s_add_i32 s52, s52, 1
	s_cmp_lt_u32 s52, 10
	s_cbranch_scc1 .Lin2_loop
	s_setprio 3
	v_add_u32_e32 v234, s22, v232
	v_add_u32_e32 v236, s28, v232
	v_add_u32_e32 v235, s22, v233
	v_add_u32_e32 v237, s28, v233
	ds_read_b128 v[136:139], v234
	ds_read_b128 v[140:143], v234 offset:2048
	ds_read_b128 v[144:147], v234 offset:4096
	ds_read_b128 v[148:151], v234 offset:6144
	ds_read_b128 v[188:191], v236
	ds_read_b128 v[196:199], v236 offset:2048
	ds_read_b128 v[200:203], v236 offset:4096
	ds_read_b128 v[204:207], v236 offset:6144
	ds_read_b128 v[172:175], v235
	ds_read_b128 v[176:179], v235 offset:2048
	ds_read_b128 v[180:183], v235 offset:4096
	ds_read_b128 v[184:187], v235 offset:6144
	ds_read_b128 v[212:215], v237
	ds_read_b128 v[216:219], v237 offset:2048
	ds_read_b128 v[220:223], v237 offset:4096
	ds_read_b128 v[224:227], v237 offset:6144
	s_add_i32 m0, s51, 0xc000
	s_nop 0
	global_load_lds_dwordx4 v228, s[44:45]
	s_add_i32 m0, s51, 0xc400
	s_nop 0
	global_load_lds_dwordx4 v230, s[44:45]
	s_add_i32 m0, s51, 0xe000
	s_nop 0
	global_load_lds_dwordx4 v229, s[44:45]
	s_add_i32 m0, s51, 0xe400
	s_nop 0
	global_load_lds_dwordx4 v231, s[44:45]
	s_add_i32 m0, s51, 0x10000
	s_nop 0
	global_load_lds_dwordx4 v228, s[46:47]
	s_add_i32 m0, s51, 0x10400
	s_nop 0
	global_load_lds_dwordx4 v230, s[46:47]
	s_waitcnt lgkmcnt(8)
	s_setprio 1
	v_mfma_f32_16x16x32_bf16 v[2:5], v[136:139], v[188:191], v[2:5]
	v_mfma_f32_16x16x32_bf16 v[6:9], v[136:139], v[196:199], v[6:9]
	v_mfma_f32_16x16x32_bf16 v[10:13], v[136:139], v[200:203], v[10:13]
	v_mfma_f32_16x16x32_bf16 v[14:17], v[136:139], v[204:207], v[14:17]
	v_mfma_f32_16x16x32_bf16 v[18:21], v[140:143], v[188:191], v[18:21]
	v_mfma_f32_16x16x32_bf16 v[22:25], v[140:143], v[196:199], v[22:25]
	v_mfma_f32_16x16x32_bf16 v[26:29], v[140:143], v[200:203], v[26:29]
	v_mfma_f32_16x16x32_bf16 v[30:33], v[140:143], v[204:207], v[30:33]
	v_mfma_f32_16x16x32_bf16 v[34:37], v[144:147], v[188:191], v[34:37]
	v_mfma_f32_16x16x32_bf16 v[38:41], v[144:147], v[196:199], v[38:41]
	v_mfma_f32_16x16x32_bf16 v[42:45], v[144:147], v[200:203], v[42:45]
	v_mfma_f32_16x16x32_bf16 v[46:49], v[144:147], v[204:207], v[46:49]
	v_mfma_f32_16x16x32_bf16 v[50:53], v[148:151], v[188:191], v[50:53]
	v_mfma_f32_16x16x32_bf16 v[54:57], v[148:151], v[196:199], v[54:57]
	v_mfma_f32_16x16x32_bf16 v[58:61], v[148:151], v[200:203], v[58:61]
	v_mfma_f32_16x16x32_bf16 v[62:65], v[148:151], v[204:207], v[62:65]
	s_waitcnt lgkmcnt(0)
	v_mfma_f32_16x16x32_bf16 v[2:5], v[172:175], v[212:215], v[2:5]
	v_mfma_f32_16x16x32_bf16 v[6:9], v[172:175], v[216:219], v[6:9]
	v_mfma_f32_16x16x32_bf16 v[10:13], v[172:175], v[220:223], v[10:13]
	v_mfma_f32_16x16x32_bf16 v[14:17], v[172:175], v[224:227], v[14:17]
	v_mfma_f32_16x16x32_bf16 v[18:21], v[176:179], v[212:215], v[18:21]
	v_mfma_f32_16x16x32_bf16 v[22:25], v[176:179], v[216:219], v[22:25]
	v_mfma_f32_16x16x32_bf16 v[26:29], v[176:179], v[220:223], v[26:29]
	v_mfma_f32_16x16x32_bf16 v[30:33], v[176:179], v[224:227], v[30:33]
	v_mfma_f32_16x16x32_bf16 v[34:37], v[180:183], v[212:215], v[34:37]
	v_mfma_f32_16x16x32_bf16 v[38:41], v[180:183], v[216:219], v[38:41]
	v_mfma_f32_16x16x32_bf16 v[42:45], v[180:183], v[220:223], v[42:45]
	v_mfma_f32_16x16x32_bf16 v[46:49], v[180:183], v[224:227], v[46:49]
	v_mfma_f32_16x16x32_bf16 v[50:53], v[184:187], v[212:215], v[50:53]
	v_mfma_f32_16x16x32_bf16 v[54:57], v[184:187], v[216:219], v[54:57]
	v_mfma_f32_16x16x32_bf16 v[58:61], v[184:187], v[220:223], v[58:61]
	v_mfma_f32_16x16x32_bf16 v[62:65], v[184:187], v[224:227], v[62:65]
	s_setprio 0
	s_waitcnt vmcnt(6)
	s_barrier
	s_setprio 3
	v_add_u32_e32 v236, s40, v232
	v_add_u32_e32 v237, s40, v233
	ds_read_b128 v[188:191], v236
	ds_read_b128 v[196:199], v236 offset:2048
	ds_read_b128 v[200:203], v236 offset:4096
	ds_read_b128 v[204:207], v236 offset:6144
	ds_read_b128 v[212:215], v237
	ds_read_b128 v[216:219], v237 offset:2048
	ds_read_b128 v[220:223], v237 offset:4096
	ds_read_b128 v[224:227], v237 offset:6144
	s_mov_b32 m0, s51
	s_nop 0
	global_load_lds_dwordx4 v229, s[46:47]
	s_add_i32 m0, s51, 0x400
	s_nop 0
	global_load_lds_dwordx4 v231, s[46:47]
	s_add_i32 m0, s51, 0x2000
	s_nop 0
	global_load_lds_dwordx4 v228, s[48:49]
	s_add_i32 m0, s51, 0x2400
	s_nop 0
	global_load_lds_dwordx4 v230, s[48:49]
	s_add_i32 m0, s51, 0x4000
	s_nop 0
	global_load_lds_dwordx4 v229, s[48:49]
	s_add_i32 m0, s51, 0x4400
	s_nop 0
	global_load_lds_dwordx4 v231, s[48:49]
	s_waitcnt lgkmcnt(4)
	s_setprio 1
	v_mfma_f32_16x16x32_bf16 v[66:69], v[136:139], v[188:191], v[66:69]
	v_mfma_f32_16x16x32_bf16 v[70:73], v[136:139], v[196:199], v[70:73]
	v_mfma_f32_16x16x32_bf16 v[74:77], v[136:139], v[200:203], v[74:77]
	v_mfma_f32_16x16x32_bf16 v[78:81], v[136:139], v[204:207], v[78:81]
	v_mfma_f32_16x16x32_bf16 v[82:85], v[140:143], v[188:191], v[82:85]
	v_mfma_f32_16x16x32_bf16 v[86:89], v[140:143], v[196:199], v[86:89]
	v_mfma_f32_16x16x32_bf16 v[90:93], v[140:143], v[200:203], v[90:93]
	v_mfma_f32_16x16x32_bf16 v[94:97], v[140:143], v[204:207], v[94:97]
	v_mfma_f32_16x16x32_bf16 v[98:101], v[144:147], v[188:191], v[98:101]
	v_mfma_f32_16x16x32_bf16 v[102:105], v[144:147], v[196:199], v[102:105]
	v_mfma_f32_16x16x32_bf16 v[106:109], v[144:147], v[200:203], v[106:109]
	v_mfma_f32_16x16x32_bf16 v[110:113], v[144:147], v[204:207], v[110:113]
	v_mfma_f32_16x16x32_bf16 v[114:117], v[148:151], v[188:191], v[114:117]
	v_mfma_f32_16x16x32_bf16 v[118:121], v[148:151], v[196:199], v[118:121]
	v_mfma_f32_16x16x32_bf16 v[122:125], v[148:151], v[200:203], v[122:125]
	v_mfma_f32_16x16x32_bf16 v[126:129], v[148:151], v[204:207], v[126:129]
	s_waitcnt lgkmcnt(0)
	v_mfma_f32_16x16x32_bf16 v[66:69], v[172:175], v[212:215], v[66:69]
	v_mfma_f32_16x16x32_bf16 v[70:73], v[172:175], v[216:219], v[70:73]
	v_mfma_f32_16x16x32_bf16 v[74:77], v[172:175], v[220:223], v[74:77]
	v_mfma_f32_16x16x32_bf16 v[78:81], v[172:175], v[224:227], v[78:81]
	v_mfma_f32_16x16x32_bf16 v[82:85], v[176:179], v[212:215], v[82:85]
	v_mfma_f32_16x16x32_bf16 v[86:89], v[176:179], v[216:219], v[86:89]
	v_mfma_f32_16x16x32_bf16 v[90:93], v[176:179], v[220:223], v[90:93]
	v_mfma_f32_16x16x32_bf16 v[94:97], v[176:179], v[224:227], v[94:97]
	v_mfma_f32_16x16x32_bf16 v[98:101], v[180:183], v[212:215], v[98:101]
	v_mfma_f32_16x16x32_bf16 v[102:105], v[180:183], v[216:219], v[102:105]
	v_mfma_f32_16x16x32_bf16 v[106:109], v[180:183], v[220:223], v[106:109]
	v_mfma_f32_16x16x32_bf16 v[110:113], v[180:183], v[224:227], v[110:113]
	v_mfma_f32_16x16x32_bf16 v[114:117], v[184:187], v[212:215], v[114:117]
	v_mfma_f32_16x16x32_bf16 v[118:121], v[184:187], v[216:219], v[118:121]
	v_mfma_f32_16x16x32_bf16 v[122:125], v[184:187], v[220:223], v[122:125]
	v_mfma_f32_16x16x32_bf16 v[126:129], v[184:187], v[224:227], v[126:129]
	s_setprio 0
	v_add_u32_e32 v228, 0x80, v228
	v_add_u32_e32 v229, 0x80, v229
	v_add_u32_e32 v230, 0x80, v230
	v_add_u32_e32 v231, 0x80, v231
	s_waitcnt vmcnt(4)
	s_barrier
	s_setprio 3
	v_add_u32_e32 v234, s23, v232
	v_add_u32_e32 v236, s29, v232
	v_add_u32_e32 v235, s23, v233
	v_add_u32_e32 v237, s29, v233
	ds_read_b128 v[136:139], v234
	ds_read_b128 v[140:143], v234 offset:2048
	ds_read_b128 v[144:147], v234 offset:4096
	ds_read_b128 v[148:151], v234 offset:6144
	ds_read_b128 v[188:191], v236
	ds_read_b128 v[196:199], v236 offset:2048
	ds_read_b128 v[200:203], v236 offset:4096
	ds_read_b128 v[204:207], v236 offset:6144
	ds_read_b128 v[172:175], v235
	ds_read_b128 v[176:179], v235 offset:2048
	ds_read_b128 v[180:183], v235 offset:4096
	ds_read_b128 v[184:187], v235 offset:6144
	ds_read_b128 v[212:215], v237
	ds_read_b128 v[216:219], v237 offset:2048
	ds_read_b128 v[220:223], v237 offset:4096
	ds_read_b128 v[224:227], v237 offset:6144
	s_waitcnt lgkmcnt(8)
	s_setprio 1
	v_mfma_f32_16x16x32_bf16 v[2:5], v[136:139], v[188:191], v[2:5]
	v_mfma_f32_16x16x32_bf16 v[6:9], v[136:139], v[196:199], v[6:9]
	v_mfma_f32_16x16x32_bf16 v[10:13], v[136:139], v[200:203], v[10:13]
	v_mfma_f32_16x16x32_bf16 v[14:17], v[136:139], v[204:207], v[14:17]
	v_mfma_f32_16x16x32_bf16 v[18:21], v[140:143], v[188:191], v[18:21]
	v_mfma_f32_16x16x32_bf16 v[22:25], v[140:143], v[196:199], v[22:25]
	v_mfma_f32_16x16x32_bf16 v[26:29], v[140:143], v[200:203], v[26:29]
	v_mfma_f32_16x16x32_bf16 v[30:33], v[140:143], v[204:207], v[30:33]
	v_mfma_f32_16x16x32_bf16 v[34:37], v[144:147], v[188:191], v[34:37]
	v_mfma_f32_16x16x32_bf16 v[38:41], v[144:147], v[196:199], v[38:41]
	v_mfma_f32_16x16x32_bf16 v[42:45], v[144:147], v[200:203], v[42:45]
	v_mfma_f32_16x16x32_bf16 v[46:49], v[144:147], v[204:207], v[46:49]
	v_mfma_f32_16x16x32_bf16 v[50:53], v[148:151], v[188:191], v[50:53]
	v_mfma_f32_16x16x32_bf16 v[54:57], v[148:151], v[196:199], v[54:57]
	v_mfma_f32_16x16x32_bf16 v[58:61], v[148:151], v[200:203], v[58:61]
	v_mfma_f32_16x16x32_bf16 v[62:65], v[148:151], v[204:207], v[62:65]
	s_waitcnt lgkmcnt(0)
	v_mfma_f32_16x16x32_bf16 v[2:5], v[172:175], v[212:215], v[2:5]
	v_mfma_f32_16x16x32_bf16 v[6:9], v[172:175], v[216:219], v[6:9]
	v_mfma_f32_16x16x32_bf16 v[10:13], v[172:175], v[220:223], v[10:13]
	v_mfma_f32_16x16x32_bf16 v[14:17], v[172:175], v[224:227], v[14:17]
	v_mfma_f32_16x16x32_bf16 v[18:21], v[176:179], v[212:215], v[18:21]
	v_mfma_f32_16x16x32_bf16 v[22:25], v[176:179], v[216:219], v[22:25]
	v_mfma_f32_16x16x32_bf16 v[26:29], v[176:179], v[220:223], v[26:29]
	v_mfma_f32_16x16x32_bf16 v[30:33], v[176:179], v[224:227], v[30:33]
	v_mfma_f32_16x16x32_bf16 v[34:37], v[180:183], v[212:215], v[34:37]
	v_mfma_f32_16x16x32_bf16 v[38:41], v[180:183], v[216:219], v[38:41]
	v_mfma_f32_16x16x32_bf16 v[42:45], v[180:183], v[220:223], v[42:45]
	v_mfma_f32_16x16x32_bf16 v[46:49], v[180:183], v[224:227], v[46:49]
	v_mfma_f32_16x16x32_bf16 v[50:53], v[184:187], v[212:215], v[50:53]
	v_mfma_f32_16x16x32_bf16 v[54:57], v[184:187], v[216:219], v[54:57]
	v_mfma_f32_16x16x32_bf16 v[58:61], v[184:187], v[220:223], v[58:61]
	v_mfma_f32_16x16x32_bf16 v[62:65], v[184:187], v[224:227], v[62:65]
	s_setprio 0
	s_waitcnt vmcnt(0)
	s_barrier
	s_setprio 3
	v_add_u32_e32 v236, s41, v232
	v_add_u32_e32 v237, s41, v233
	ds_read_b128 v[188:191], v236
	ds_read_b128 v[196:199], v236 offset:2048
	ds_read_b128 v[200:203], v236 offset:4096
	ds_read_b128 v[204:207], v236 offset:6144
	ds_read_b128 v[212:215], v237
	ds_read_b128 v[216:219], v237 offset:2048
	ds_read_b128 v[220:223], v237 offset:4096
	ds_read_b128 v[224:227], v237 offset:6144
	s_waitcnt lgkmcnt(4)
	s_setprio 1
	v_mfma_f32_16x16x32_bf16 v[66:69], v[136:139], v[188:191], v[66:69]
	v_mfma_f32_16x16x32_bf16 v[70:73], v[136:139], v[196:199], v[70:73]
	v_mfma_f32_16x16x32_bf16 v[74:77], v[136:139], v[200:203], v[74:77]
	v_mfma_f32_16x16x32_bf16 v[78:81], v[136:139], v[204:207], v[78:81]
	v_mfma_f32_16x16x32_bf16 v[82:85], v[140:143], v[188:191], v[82:85]
	v_mfma_f32_16x16x32_bf16 v[86:89], v[140:143], v[196:199], v[86:89]
	v_mfma_f32_16x16x32_bf16 v[90:93], v[140:143], v[200:203], v[90:93]
	v_mfma_f32_16x16x32_bf16 v[94:97], v[140:143], v[204:207], v[94:97]
	v_mfma_f32_16x16x32_bf16 v[98:101], v[144:147], v[188:191], v[98:101]
	v_mfma_f32_16x16x32_bf16 v[102:105], v[144:147], v[196:199], v[102:105]
	v_mfma_f32_16x16x32_bf16 v[106:109], v[144:147], v[200:203], v[106:109]
	v_mfma_f32_16x16x32_bf16 v[110:113], v[144:147], v[204:207], v[110:113]
	v_mfma_f32_16x16x32_bf16 v[114:117], v[148:151], v[188:191], v[114:117]
	v_mfma_f32_16x16x32_bf16 v[118:121], v[148:151], v[196:199], v[118:121]
	v_mfma_f32_16x16x32_bf16 v[122:125], v[148:151], v[200:203], v[122:125]
	v_mfma_f32_16x16x32_bf16 v[126:129], v[148:151], v[204:207], v[126:129]
	s_waitcnt lgkmcnt(0)
	v_mfma_f32_16x16x32_bf16 v[66:69], v[172:175], v[212:215], v[66:69]
	v_mfma_f32_16x16x32_bf16 v[70:73], v[172:175], v[216:219], v[70:73]
	v_mfma_f32_16x16x32_bf16 v[74:77], v[172:175], v[220:223], v[74:77]
	v_mfma_f32_16x16x32_bf16 v[78:81], v[172:175], v[224:227], v[78:81]
	v_mfma_f32_16x16x32_bf16 v[82:85], v[176:179], v[212:215], v[82:85]
	v_mfma_f32_16x16x32_bf16 v[86:89], v[176:179], v[216:219], v[86:89]
	v_mfma_f32_16x16x32_bf16 v[90:93], v[176:179], v[220:223], v[90:93]
	v_mfma_f32_16x16x32_bf16 v[94:97], v[176:179], v[224:227], v[94:97]
	v_mfma_f32_16x16x32_bf16 v[98:101], v[180:183], v[212:215], v[98:101]
	v_mfma_f32_16x16x32_bf16 v[102:105], v[180:183], v[216:219], v[102:105]
	v_mfma_f32_16x16x32_bf16 v[106:109], v[180:183], v[220:223], v[106:109]
	v_mfma_f32_16x16x32_bf16 v[110:113], v[180:183], v[224:227], v[110:113]
	v_mfma_f32_16x16x32_bf16 v[114:117], v[184:187], v[212:215], v[114:117]
	v_mfma_f32_16x16x32_bf16 v[118:121], v[184:187], v[216:219], v[118:121]
	v_mfma_f32_16x16x32_bf16 v[122:125], v[184:187], v[220:223], v[122:125]
	v_mfma_f32_16x16x32_bf16 v[126:129], v[184:187], v[224:227], v[126:129]
	s_setprio 0
	s_nop 7
	s_barrier
	v_and_b32_e32 v241, 63, v131
	v_and_b32_e32 v242, 15, v241
	v_lshrrev_b32_e32 v243, 4, v241
	s_lshr_b32 s56, s50, 1
	s_and_b32 s57, s50, 1
	s_mul_i32 s0, s56, 64*272
	s_lshl_b32 s52, s57, 7
	s_add_i32 s0, s0, s52
	s_add_i32 s0, s0, 16
	v_mul_u32_u24_e32 v244, 1088, v243
	v_lshl_add_u32 v244, v242, 1, v244
	v_add_u32_e32 v229, s0, v244
	s_mul_i32 s0, s57, 64*272
	s_lshl_b32 s52, s56, 7
	s_add_i32 s0, s0, s52
	s_add_i32 s0, s0, 16
	v_mul_u32_u24_e32 v244, 272, v242
	v_lshl_add_u32 v244, v243, 3, v244
	v_add_u32_e32 v230, s0, v244
	s_lshl_b32 s0, s57, 9
	s_lshl_b32 s52, s56, 8
	s_add_i32 s0, s0, s52
	s_add_i32 s0, s0, 16+34816
	v_lshl_add_u32 v228, v243, 4, s0
	s_lshl_b32 s0, s57, 8
	v_lshl_add_u32 v234, v242, 2, s0
	v_lshrrev_b32_e32 v241, 4, v131
	v_and_b32_e32 v242, 15, v131
	v_lshlrev_b32_e32 v242, 4, v242
	v_mul_u32_u24_e32 v243, 272, v241
	v_add3_u32 v231, v243, v242, 16
	s_movk_i32 s0, 0x2500
	v_mad_u32_u24 v232, v241, s0, v242
	v_lshl_add_u32 v233, v241, 12, v242
	s_lshr_b32 s52, s54, 7
	s_mov_b32 s57, 0
	s_movk_i32 s56, 0x170
	s_cmp_lt_u32 s52, 8
	s_cbranch_scc0 .Lin2_t1_v1
	s_mov_b32 s57, 1
	s_movk_i32 s56, 0x28
	s_branch .Lin2_t1_vd
